# S5 pass-3: Bu transposed in registers (swapped MFMA operands + permlane32/16 swaps), flag hand-off instead of per-round barrier; S5 pass-1 rewritten LDS-free
# speedup vs baseline: 1.0307x; 1.0252x over previous
; DI void s5_pass1_item(const Params& P, int bitem, unsigned char* smem) {
;     int tid_ = threadIdx.x; asm volatile("" : "+v"(tid_));
;     unsigned char* ws = P.ws; const int tid = tid_, wid = tid >> 6, lane = tid & 63, r = lane & 15, q = lane >> 4;
;     const int item = bitem * 8 + wid, ch = item & 31, grp = (item >> 5) & 63, b = item >> 11;
;     const bf16_t* proj = (const bf16_t*)(ws + WS_PROJ); const float* sm = (const float*)(ws + WS_SMALL);
;     float* buf = (float*)smem + wid * 2176;
;     const bf16_t* tb = (const bf16_t*)(sm + SM_BB);
;     bf16x8 af[8];
; #pragma unroll
;     for (int pt = 0; pt < 8; ++pt) af[pt] = *(const bf16x8*)(tb + (grp * 128 + 16 * pt + r) * 32 + 8 * q);
;     const f32x4 ab = *(const f32x4*)(sm + SM_AB + (grp * 64 + lane) * 4);
;     const bf16_t* ubase = proj + (size_t)(b * TT + ch * 64) * NPROJ + C_SSM + grp * 16;
;     float xr = 0.f, xi = 0.f;
;     bf16x8 ubs[4];
; #pragma unroll
;     for (int sub = 0; sub < 4; ++sub) ubs[sub] = *(const bf16x8*)(ubase + (size_t)(sub * 16 + r) * NPROJ + 8 * (q & 1));
; #pragma unroll
;     for (int sub = 0; sub < 4; ++sub) {
;         s5_bu16(ubs[sub], af, buf, r, q);
;         asm volatile("s_waitcnt lgkmcnt(0)" ::: "memory");
; #pragma unroll
;         for (int tt = 0; tt < 16; ++tt) { const float bur = buf[lane * 17 + tt], bui = buf[(64 + lane) * 17 + tt];
;             const float nxr = ab[0] * xr - ab[1] * xi + bur, nxi = ab[0] * xi + ab[1] * xr + bui; xr = nxr; xi = nxi; }
;         asm volatile("s_waitcnt lgkmcnt(0)" ::: "memory");
;     }
; __global__ void __launch_bounds__(512, 2) hymba_fwd(Params P) {
;     ...
;         for (int it = blockIdx.x; it < 254 + 2048; it += G) {
;             if (it < 254) compress_item(P, it, shm);
;             else { s5_pass1_item(P, it - 254, shm); __syncthreads(); }
.LBB0_635:
	s_cmpk_gt_i32 s71, 0xfd
	s_mov_b64 s[4:5], -1
	s_cbranch_scc0 .LBB0_637
	v_readlane_b32 s46, v245, 11
	s_nop 1
	s_cmpk_lg_u32 s46, 0x100
	s_cbranch_scc0 .Ls5p1_start
	v_mov_b32_e32 v36, v206
	v_readlane_b32 s72, v245, 5
	v_ashrrev_i32_e32 v37, 6, v36
	v_and_b32_e32 v38, 15, v36
	v_add_u32_e32 v12, s49, v37
	v_bfe_u32 v39, v12, 5, 6
	v_and_b32_e32 v46, 48, v36
	v_lshlrev_b32_e32 v4, 6, v38
	v_and_b32_e32 v55, 31, v12
	v_and_b32_e32 v57, 0xfffff800, v12
	v_readlane_b32 s74, v245, 7
	v_readlane_b32 s75, v245, 8
	v_lshl_add_u64 v[2:3], s[2:3], 0, v[46:47]
	v_lshl_or_b32 v46, v39, 13, v4
	v_lshl_or_b32 v14, v55, 6, v57
	v_mov_b64_e32 v[12:13], s[74:75]
	v_lshl_add_u64 v[10:11], v[2:3], 0, v[46:47]
	v_mad_i64_i32 v[12:13], s[4:5], v14, s53, v[12:13]
	v_lshlrev_b32_e32 v46, 5, v39
	v_lshl_add_u64 v[12:13], v[12:13], 0, v[46:47]
	v_and_b32_e32 v14, 16, v36
	v_mov_b32_e32 v15, v47
	v_lshl_add_u64 v[12:13], v[12:13], 0, v[14:15]
	v_mul_u32_u24_e32 v14, 0xf00, v38
	v_lshlrev_b32_e32 v14, 1, v14
	v_lshl_add_u64 v[34:35], v[12:13], 0, v[14:15]
	v_add_co_u32_e32 v12, vcc, s54, v34
	global_load_dwordx4 v[6:9], v[10:11], off
	global_load_dwordx4 v[2:5], v[10:11], off offset:1024
	v_addc_co_u32_e32 v13, vcc, 0, v35, vcc
	global_load_dwordx4 v[96:99], v[12:13], off offset:1072
	global_load_dwordx4 v[30:33], v[10:11], off offset:2048
	global_load_dwordx4 v[26:29], v[10:11], off offset:3072
	v_add_co_u32_e32 v10, vcc, s52, v10
	v_and_b32_e32 v59, 63, v36
	s_nop 0
	v_addc_co_u32_e32 v11, vcc, 0, v11, vcc
	global_load_dwordx4 v[22:25], v[10:11], off
	global_load_dwordx4 v[18:21], v[10:11], off offset:1024
	global_load_dwordx4 v[14:17], v[10:11], off offset:2048
	s_nop 0
	global_load_dwordx4 v[10:13], v[10:11], off offset:3072
	v_lshlrev_b32_e32 v40, 4, v59
	v_lshl_or_b32 v39, v39, 10, v40
	global_load_dwordx2 v[88:89], v39, s[6:7]
	v_bfe_u32 v36, v36, 4, 2
	v_mul_lo_u32 v37, v37, s51
	v_mul_u32_u24_e32 v36, 0x110, v36
	v_lshlrev_b32_e32 v38, 2, v38
	v_add_u32_e32 v37, 0, v37
	v_add3_u32 v65, v37, v36, v38
	v_add_co_u32_e32 v36, vcc, s55, v34
	v_mad_u32_u24 v61, v59, s58, v37
	s_nop 0
	v_addc_co_u32_e32 v37, vcc, 0, v35, vcc
	v_add_co_u32_e32 v38, vcc, s56, v34
	v_add_u32_e32 v69, 0x400, v65
	s_nop 0
	v_addc_co_u32_e32 v39, vcc, 0, v35, vcc
	v_add_co_u32_e32 v34, vcc, s57, v34
	v_add_u32_e32 v67, 0x800, v65
	s_nop 0
	v_addc_co_u32_e32 v35, vcc, 0, v35, vcc
	global_load_dwordx4 v[42:45], v[36:37], off offset:1072
	s_nop 0
	global_load_dwordx4 v[38:41], v[38:39], off offset:1072
	s_nop 0
	global_load_dwordx4 v[34:37], v[34:35], off offset:1072
	v_add_u32_e32 v71, 0xc00, v65
	v_add_u32_e32 v73, 0x1000, v65
	v_add_u32_e32 v75, 0x1400, v65
	v_add_u32_e32 v77, 0x1800, v65
	v_add_u32_e32 v63, 0x1100, v61
	v_add_u32_e32 v81, 0x1110, v61
	v_add_u32_e32 v83, 0x1118, v61
	v_readlane_b32 s73, v245, 6
	v_readlane_b32 s76, v245, 9
	v_readlane_b32 s77, v245, 10
	v_readlane_b32 s78, v245, 11
	v_readlane_b32 s79, v245, 12
	s_mov_b64 s[4:5], 0
	s_waitcnt vmcnt(10)
	v_mfma_f32_16x16x32_bf16 v[100:103], v[6:9], v[96:99], 0
	v_mfma_f32_16x16x32_bf16 v[104:107], v[2:5], v[96:99], 0
	s_waitcnt vmcnt(9)
	v_mfma_f32_16x16x32_bf16 v[108:111], v[30:33], v[96:99], 0
	s_waitcnt vmcnt(8)
	v_mfma_f32_16x16x32_bf16 v[112:115], v[26:29], v[96:99], 0
	s_waitcnt vmcnt(7)
	v_mfma_f32_16x16x32_bf16 v[116:119], v[22:25], v[96:99], 0
	s_waitcnt vmcnt(6)
	v_mfma_f32_16x16x32_bf16 v[120:123], v[18:21], v[96:99], 0
	s_waitcnt vmcnt(5)
	v_mfma_f32_16x16x32_bf16 v[124:127], v[14:17], v[96:99], 0
	ds_write2_b32 v65, v100, v101 offset1:17
	ds_write2_b32 v65, v102, v103 offset0:34 offset1:51
	ds_write2_b32 v69, v104, v105 offset0:16 offset1:33
	ds_write2_b32 v69, v106, v107 offset0:50 offset1:67
	ds_write2_b32 v67, v108, v109 offset0:32 offset1:49
	ds_write2_b32 v67, v110, v111 offset0:66 offset1:83
	ds_write2_b32 v71, v112, v113 offset0:48 offset1:65
	ds_write2_b32 v71, v114, v115 offset0:82 offset1:99
	ds_write2_b32 v73, v116, v117 offset0:64 offset1:81
	ds_write2_b32 v73, v118, v119 offset0:98 offset1:115
	ds_write2_b32 v75, v120, v121 offset0:80 offset1:97
	ds_write2_b32 v75, v122, v123 offset0:114 offset1:131
	ds_write2_b32 v77, v124, v125 offset0:96 offset1:113
	ds_write2_b32 v77, v126, v127 offset0:130 offset1:147
	s_waitcnt vmcnt(4)
	v_mfma_f32_16x16x32_bf16 v[100:103], v[10:13], v[96:99], 0
	v_add_u32_e32 v98, 0x1c00, v65
	s_nop 6
	ds_write2_b32 v98, v100, v101 offset0:112 offset1:129
	ds_write2_b32 v98, v102, v103 offset0:146 offset1:163
	s_waitcnt lgkmcnt(0)
	ds_read2_b32 v[96:97], v61 offset1:1
	ds_read2_b32 v[100:101], v63 offset1:1
	s_waitcnt vmcnt(3)
	v_pk_mul_f32 v[102:103], v[88:89], 0 op_sel_hi:[1,0]
	ds_read2_b32 v[104:105], v61 offset0:2 offset1:3
	ds_read2_b32 v[106:107], v61 offset0:4 offset1:5
	ds_read2_b32 v[108:109], v61 offset0:6 offset1:7
	v_add_f32_e32 v85, v102, v103
	v_sub_f32_e32 v79, v102, v103
	s_waitcnt lgkmcnt(3)
	v_add_f32_e32 v100, v85, v100
	v_add_f32_e32 v96, v79, v96
	v_pk_mul_f32 v[114:115], v[88:89], v[100:101] op_sel:[1,0] op_sel_hi:[0,0]
	v_pk_fma_f32 v[116:117], v[88:89], v[96:97], v[114:115] neg_lo:[0,0,1] neg_hi:[0,0,1]
	v_pk_fma_f32 v[114:115], v[88:89], v[96:97], v[114:115] op_sel_hi:[1,0,1]
	v_mov_b32_e32 v100, v97
	v_mov_b32_e32 v117, v115
	v_add_u32_e32 v79, 0x1108, v61
	v_pk_add_f32 v[96:97], v[100:101], v[116:117]
	ds_read2_b32 v[102:103], v79 offset1:1
	ds_read2_b32 v[110:111], v81 offset1:1
	ds_read2_b32 v[112:113], v83 offset1:1
	v_pk_mul_f32 v[100:101], v[88:89], v[96:97]
	v_pk_mul_f32 v[96:97], v[88:89], v[96:97] op_sel:[0,1] op_sel_hi:[1,0]
	v_sub_f32_e32 v85, v100, v101
	s_waitcnt lgkmcnt(5)
; DI void s5_bu16(const bf16x8 ub, const bf16x8 (&af)[8], float* buf, int r, int q) {
; #pragma unroll
;     for (int pt = 0; pt < 8; ++pt) { f32x4 d = {0.f, 0.f, 0.f, 0.f}; d = __builtin_amdgcn_mfma_f32_16x16x32_bf16(af[pt], ub, d, 0, 0, 0);
; #pragma unroll
;         for (int j = 0; j < 4; ++j) buf[(16 * pt + 4 * q + j) * 17 + r] = d[j]; }
; }
; DI void s5_pass1_item(const Params& P, int bitem, unsigned char* smem) {
;     int tid_ = threadIdx.x; asm volatile("" : "+v"(tid_));
;     unsigned char* ws = P.ws; const int tid = tid_, wid = tid >> 6, lane = tid & 63, r = lane & 15, q = lane >> 4;
;     const int item = bitem * 8 + wid, ch = item & 31, grp = (item >> 5) & 63, b = item >> 11;
;     const bf16_t* proj = (const bf16_t*)(ws + WS_PROJ); const float* sm = (const float*)(ws + WS_SMALL);
;     float* buf = (float*)smem + wid * 2176;
;     const bf16_t* tb = (const bf16_t*)(sm + SM_BB);
;     bf16x8 af[8];
; #pragma unroll
;     for (int pt = 0; pt < 8; ++pt) af[pt] = *(const bf16x8*)(tb + (grp * 128 + 16 * pt + r) * 32 + 8 * q);
;     const f32x4 ab = *(const f32x4*)(sm + SM_AB + (grp * 64 + lane) * 4);
;     const bf16_t* ubase = proj + (size_t)(b * TT + ch * 64) * NPROJ + C_SSM + grp * 16;
;     float xr = 0.f, xi = 0.f;
;     bf16x8 ubs[4];
; #pragma unroll
;     for (int sub = 0; sub < 4; ++sub) ubs[sub] = *(const bf16x8*)(ubase + (size_t)(sub * 16 + r) * NPROJ + 8 * (q & 1));
; #pragma unroll
;     for (int sub = 0; sub < 4; ++sub) {
;         s5_bu16(ubs[sub], af, buf, r, q);
;         asm volatile("s_waitcnt lgkmcnt(0)" ::: "memory");
; #pragma unroll
;         for (int tt = 0; tt < 16; ++tt) { const float bur = buf[lane * 17 + tt], bui = buf[(64 + lane) * 17 + tt];
;             const float nxr = ab[0] * xr - ab[1] * xi + bur, nxi = ab[0] * xi + ab[1] * xr + bui; xr = nxr; xi = nxi; }
;         asm volatile("s_waitcnt lgkmcnt(0)" ::: "memory");
;     }
;     f32x2_t e = {xr, xi};
;     *(f32x2_t*)(ws + WS_S5END + ((size_t)((b * 64 + grp) * 32 + ch) * 64 + lane) * 8) = e;
	v_add_f32_e32 v100, v104, v85
	v_add_f32_e32 v85, v96, v97
	s_waitcnt lgkmcnt(2)
	v_add_f32_e32 v96, v102, v85
	v_pk_mul_f32 v[96:97], v[88:89], v[96:97] op_sel:[1,0] op_sel_hi:[0,0]
	v_pk_fma_f32 v[114:115], v[88:89], v[100:101], v[96:97] neg_lo:[0,0,1] neg_hi:[0,0,1]
	v_pk_fma_f32 v[96:97], v[88:89], v[100:101], v[96:97] op_sel_hi:[1,0,1]
	v_mov_b32_e32 v102, v105
	v_mov_b32_e32 v115, v97
	v_pk_add_f32 v[96:97], v[102:103], v[114:115]
	s_nop 0
	v_pk_mul_f32 v[100:101], v[88:89], v[96:97]
	v_pk_mul_f32 v[96:97], v[88:89], v[96:97] op_sel:[0,1] op_sel_hi:[1,0]
	v_sub_f32_e32 v85, v100, v101
	v_add_f32_e32 v100, v106, v85
	v_add_f32_e32 v85, v96, v97
	s_waitcnt lgkmcnt(1)
	v_add_f32_e32 v96, v110, v85
	v_pk_mul_f32 v[96:97], v[88:89], v[96:97] op_sel:[1,0] op_sel_hi:[0,0]
	v_pk_fma_f32 v[102:103], v[88:89], v[100:101], v[96:97] neg_lo:[0,0,1] neg_hi:[0,0,1]
	v_pk_fma_f32 v[96:97], v[88:89], v[100:101], v[96:97] op_sel_hi:[1,0,1]
	v_mov_b32_e32 v110, v107
	v_mov_b32_e32 v103, v97
	v_pk_add_f32 v[96:97], v[110:111], v[102:103]
	ds_read2_b32 v[102:103], v61 offset0:8 offset1:9
	v_pk_mul_f32 v[100:101], v[88:89], v[96:97]
	v_pk_mul_f32 v[96:97], v[88:89], v[96:97] op_sel:[0,1] op_sel_hi:[1,0]
	v_sub_f32_e32 v85, v100, v101
	v_add_f32_e32 v100, v108, v85
	v_add_f32_e32 v85, v96, v97
	s_waitcnt lgkmcnt(1)
	v_add_f32_e32 v96, v112, v85
	v_add_u32_e32 v85, 0x1120, v61
	v_pk_mul_f32 v[96:97], v[88:89], v[96:97] op_sel:[1,0] op_sel_hi:[0,0]
	ds_read2_b32 v[104:105], v85 offset1:1
	v_pk_fma_f32 v[106:107], v[88:89], v[100:101], v[96:97] neg_lo:[0,0,1] neg_hi:[0,0,1]
	v_pk_fma_f32 v[96:97], v[88:89], v[100:101], v[96:97] op_sel_hi:[1,0,1]
	v_mov_b32_e32 v112, v109
	v_mov_b32_e32 v107, v97
	v_pk_add_f32 v[96:97], v[112:113], v[106:107]
	s_nop 0
	v_pk_mul_f32 v[100:101], v[88:89], v[96:97]
	v_pk_mul_f32 v[96:97], v[88:89], v[96:97] op_sel:[0,1] op_sel_hi:[1,0]
	v_sub_f32_e32 v87, v100, v101
	v_add_f32_e32 v99, v96, v97
	s_waitcnt lgkmcnt(0)
	v_add_f32_e32 v104, v104, v99
	v_add_f32_e32 v102, v102, v87
	v_pk_mul_f32 v[116:117], v[88:89], v[104:105] op_sel:[1,0] op_sel_hi:[0,0]
	v_pk_fma_f32 v[118:119], v[88:89], v[102:103], v[116:117] neg_lo:[0,0,1] neg_hi:[0,0,1]
	v_pk_fma_f32 v[116:117], v[88:89], v[102:103], v[116:117] op_sel_hi:[1,0,1]
	v_mov_b32_e32 v104, v103
	v_mov_b32_e32 v119, v117
	ds_read2_b32 v[100:101], v61 offset0:10 offset1:11
	ds_read2_b32 v[106:107], v61 offset0:12 offset1:13
	ds_read2_b32 v[112:113], v61 offset0:14 offset1:15
	v_add_u32_e32 v87, 0x1128, v61
	v_pk_add_f32 v[102:103], v[104:105], v[118:119]
	v_add_u32_e32 v96, 0x1130, v61
	v_add_u32_e32 v97, 0x1138, v61
	ds_read2_b32 v[108:109], v87 offset1:1
	ds_read2_b32 v[110:111], v96 offset1:1
	ds_read2_b32 v[114:115], v97 offset1:1
	v_pk_mul_f32 v[104:105], v[88:89], v[102:103]
	v_pk_mul_f32 v[102:103], v[88:89], v[102:103] op_sel:[0,1] op_sel_hi:[1,0]
	v_sub_f32_e32 v99, v104, v105
	s_waitcnt lgkmcnt(5)
	v_add_f32_e32 v100, v100, v99
	v_add_f32_e32 v99, v102, v103
	s_waitcnt lgkmcnt(2)
	v_add_f32_e32 v102, v108, v99
	v_pk_mul_f32 v[102:103], v[88:89], v[102:103] op_sel:[1,0] op_sel_hi:[0,0]
	v_pk_fma_f32 v[104:105], v[88:89], v[100:101], v[102:103] neg_lo:[0,0,1] neg_hi:[0,0,1]
	v_pk_fma_f32 v[102:103], v[88:89], v[100:101], v[102:103] op_sel_hi:[1,0,1]
	v_mov_b32_e32 v108, v101
	v_mov_b32_e32 v105, v103
	v_pk_add_f32 v[100:101], v[108:109], v[104:105]
	s_waitcnt lgkmcnt(0)
	s_nop 0
	v_pk_mul_f32 v[102:103], v[88:89], v[100:101]
	v_pk_mul_f32 v[100:101], v[88:89], v[100:101] op_sel:[0,1] op_sel_hi:[1,0]
	v_sub_f32_e32 v99, v102, v103
	v_add_f32_e32 v102, v106, v99
	v_add_f32_e32 v99, v100, v101
	s_waitcnt lgkmcnt(1)
	v_add_f32_e32 v100, v110, v99
	v_pk_mul_f32 v[100:101], v[88:89], v[100:101] op_sel:[1,0] op_sel_hi:[0,0]
	v_pk_fma_f32 v[104:105], v[88:89], v[102:103], v[100:101] neg_lo:[0,0,1] neg_hi:[0,0,1]
	v_pk_fma_f32 v[100:101], v[88:89], v[102:103], v[100:101] op_sel_hi:[1,0,1]
	v_mov_b32_e32 v110, v107
	v_mov_b32_e32 v105, v101
	v_pk_add_f32 v[108:109], v[110:111], v[104:105]
	s_waitcnt vmcnt(2)
	v_mfma_f32_16x16x32_bf16 v[100:103], v[6:9], v[42:45], 0
	v_mul_f32_e64 v104, v88, v108
	v_mul_f32_e64 v105, v89, v109
	v_pk_mul_f32 v[108:109], v[88:89], v[108:109] op_sel:[0,1] op_sel_hi:[1,0]
	v_sub_f32_e32 v99, v104, v105
	v_mfma_f32_16x16x32_bf16 v[104:107], v[2:5], v[42:45], 0
	v_add_f32_e32 v112, v112, v99
	v_add_f32_e32 v99, v108, v109
	s_nop 0
	ds_write2_b32 v65, v100, v101 offset1:17
	ds_write2_b32 v65, v102, v103 offset0:34 offset1:51
	v_mfma_f32_16x16x32_bf16 v[108:111], v[30:33], v[42:45], 0
	s_nop 1
	ds_write2_b32 v69, v104, v105 offset0:16 offset1:33
	ds_write2_b32 v69, v106, v107 offset0:50 offset1:67
	s_nop 3
	ds_write2_b32 v67, v108, v109 offset0:32 offset1:49
	s_waitcnt lgkmcnt(5)
	v_add_f32_e32 v114, v114, v99
	v_mfma_f32_16x16x32_bf16 v[100:103], v[26:29], v[42:45], 0
	ds_write2_b32 v67, v110, v111 offset0:66 offset1:83
	s_nop 6
	ds_write2_b32 v71, v100, v101 offset0:48 offset1:65
	ds_write2_b32 v71, v102, v103 offset0:82 offset1:99
	v_mfma_f32_16x16x32_bf16 v[104:107], v[22:25], v[42:45], 0
	v_mfma_f32_16x16x32_bf16 v[100:103], v[18:21], v[42:45], 0
	s_nop 6
	ds_write2_b32 v73, v104, v105 offset0:64 offset1:81
	ds_write2_b32 v73, v106, v107 offset0:98 offset1:115
	ds_write2_b32 v75, v100, v101 offset0:80 offset1:97
	v_pk_mul_f32 v[100:101], v[88:89], v[114:115] op_sel:[1,0] op_sel_hi:[0,0]
	v_mfma_f32_16x16x32_bf16 v[104:107], v[14:17], v[42:45], 0
	ds_write2_b32 v75, v102, v103 offset0:114 offset1:131
	s_nop 6
	ds_write2_b32 v77, v104, v105 offset0:96 offset1:113
	ds_write2_b32 v77, v106, v107 offset0:130 offset1:147
	v_mfma_f32_16x16x32_bf16 v[42:45], v[10:13], v[42:45], 0
	s_nop 7
	ds_write2_b32 v98, v42, v43 offset0:112 offset1:129
	ds_write2_b32 v98, v44, v45 offset0:146 offset1:163
	s_waitcnt lgkmcnt(0)
; DI void s5_bu16(const bf16x8 ub, const bf16x8 (&af)[8], float* buf, int r, int q) {
; #pragma unroll
;     for (int pt = 0; pt < 8; ++pt) { f32x4 d = {0.f, 0.f, 0.f, 0.f}; d = __builtin_amdgcn_mfma_f32_16x16x32_bf16(af[pt], ub, d, 0, 0, 0);
; #pragma unroll
;         for (int j = 0; j < 4; ++j) buf[(16 * pt + 4 * q + j) * 17 + r] = d[j]; }
; }
; DI void s5_pass1_item(const Params& P, int bitem, unsigned char* smem) {
;     int tid_ = threadIdx.x; asm volatile("" : "+v"(tid_));
;     unsigned char* ws = P.ws; const int tid = tid_, wid = tid >> 6, lane = tid & 63, r = lane & 15, q = lane >> 4;
;     const int item = bitem * 8 + wid, ch = item & 31, grp = (item >> 5) & 63, b = item >> 11;
;     const bf16_t* proj = (const bf16_t*)(ws + WS_PROJ); const float* sm = (const float*)(ws + WS_SMALL);
;     float* buf = (float*)smem + wid * 2176;
;     const bf16_t* tb = (const bf16_t*)(sm + SM_BB);
;     bf16x8 af[8];
; #pragma unroll
;     for (int pt = 0; pt < 8; ++pt) af[pt] = *(const bf16x8*)(tb + (grp * 128 + 16 * pt + r) * 32 + 8 * q);
;     const f32x4 ab = *(const f32x4*)(sm + SM_AB + (grp * 64 + lane) * 4);
;     const bf16_t* ubase = proj + (size_t)(b * TT + ch * 64) * NPROJ + C_SSM + grp * 16;
;     float xr = 0.f, xi = 0.f;
;     bf16x8 ubs[4];
; #pragma unroll
;     for (int sub = 0; sub < 4; ++sub) ubs[sub] = *(const bf16x8*)(ubase + (size_t)(sub * 16 + r) * NPROJ + 8 * (q & 1));
; #pragma unroll
;     for (int sub = 0; sub < 4; ++sub) {
;         s5_bu16(ubs[sub], af, buf, r, q);
;         asm volatile("s_waitcnt lgkmcnt(0)" ::: "memory");
; #pragma unroll
;         for (int tt = 0; tt < 16; ++tt) { const float bur = buf[lane * 17 + tt], bui = buf[(64 + lane) * 17 + tt];
;             const float nxr = ab[0] * xr - ab[1] * xi + bur, nxi = ab[0] * xi + ab[1] * xr + bui; xr = nxr; xi = nxi; }
;         asm volatile("s_waitcnt lgkmcnt(0)" ::: "memory");
;     }
;     f32x2_t e = {xr, xi};
;     *(f32x2_t*)(ws + WS_S5END + ((size_t)((b * 64 + grp) * 32 + ch) * 64 + lane) * 8) = e;
	v_pk_fma_f32 v[102:103], v[88:89], v[112:113], v[100:101] neg_lo:[0,0,1] neg_hi:[0,0,1]
	v_pk_fma_f32 v[100:101], v[88:89], v[112:113], v[100:101] op_sel_hi:[1,0,1]
	ds_read2_b32 v[42:43], v61 offset1:1
	ds_read2_b32 v[44:45], v63 offset1:1
	v_mov_b32_e32 v103, v101
	v_mov_b32_e32 v114, v113
	v_pk_add_f32 v[100:101], v[114:115], v[102:103]
	s_nop 0
	v_pk_mul_f32 v[102:103], v[88:89], v[100:101]
	v_pk_mul_f32 v[100:101], v[88:89], v[100:101] op_sel:[0,1] op_sel_hi:[1,0]
	v_sub_f32_e32 v99, v102, v103
	s_waitcnt lgkmcnt(1)
	v_add_f32_e32 v42, v99, v42
	v_add_f32_e32 v99, v100, v101
	s_waitcnt lgkmcnt(0)
	v_add_f32_e32 v44, v99, v44
	v_pk_mul_f32 v[112:113], v[88:89], v[44:45] op_sel:[1,0] op_sel_hi:[0,0]
	v_pk_fma_f32 v[114:115], v[88:89], v[42:43], v[112:113] neg_lo:[0,0,1] neg_hi:[0,0,1]
	v_pk_fma_f32 v[112:113], v[88:89], v[42:43], v[112:113] op_sel_hi:[1,0,1]
	v_mov_b32_e32 v44, v43
	v_mov_b32_e32 v115, v113
	ds_read2_b32 v[102:103], v61 offset0:2 offset1:3
	ds_read2_b32 v[104:105], v61 offset0:4 offset1:5
	ds_read2_b32 v[106:107], v61 offset0:6 offset1:7
	ds_read2_b32 v[100:101], v79 offset1:1
	ds_read2_b32 v[108:109], v81 offset1:1
	ds_read2_b32 v[110:111], v83 offset1:1
	v_pk_add_f32 v[42:43], v[44:45], v[114:115]
	s_nop 0
	v_pk_mul_f32 v[44:45], v[88:89], v[42:43]
	v_pk_mul_f32 v[42:43], v[88:89], v[42:43] op_sel:[0,1] op_sel_hi:[1,0]
	v_sub_f32_e32 v44, v44, v45
	v_add_f32_e32 v42, v42, v43
	s_waitcnt lgkmcnt(2)
	v_add_f32_e32 v42, v100, v42
	v_add_f32_e32 v44, v102, v44
	v_pk_mul_f32 v[42:43], v[88:89], v[42:43] op_sel:[1,0] op_sel_hi:[0,0]
	v_pk_fma_f32 v[112:113], v[88:89], v[44:45], v[42:43] neg_lo:[0,0,1] neg_hi:[0,0,1]
	v_pk_fma_f32 v[42:43], v[88:89], v[44:45], v[42:43] op_sel_hi:[1,0,1]
	v_mov_b32_e32 v100, v103
	v_mov_b32_e32 v113, v43
	v_pk_add_f32 v[42:43], v[100:101], v[112:113]
	s_nop 0
	v_pk_mul_f32 v[44:45], v[88:89], v[42:43]
	v_pk_mul_f32 v[42:43], v[88:89], v[42:43] op_sel:[0,1] op_sel_hi:[1,0]
	v_sub_f32_e32 v44, v44, v45
	v_add_f32_e32 v42, v42, v43
	s_waitcnt lgkmcnt(1)
	v_add_f32_e32 v42, v108, v42
	v_add_f32_e32 v44, v104, v44
	v_pk_mul_f32 v[42:43], v[88:89], v[42:43] op_sel:[1,0] op_sel_hi:[0,0]
	v_pk_fma_f32 v[100:101], v[88:89], v[44:45], v[42:43] neg_lo:[0,0,1] neg_hi:[0,0,1]
	v_pk_fma_f32 v[42:43], v[88:89], v[44:45], v[42:43] op_sel_hi:[1,0,1]
	v_mov_b32_e32 v108, v105
	v_mov_b32_e32 v101, v43
	v_pk_add_f32 v[42:43], v[108:109], v[100:101]
	ds_read2_b32 v[100:101], v61 offset0:8 offset1:9
	ds_read2_b32 v[102:103], v85 offset1:1
	v_pk_mul_f32 v[44:45], v[88:89], v[42:43]
	v_pk_mul_f32 v[42:43], v[88:89], v[42:43] op_sel:[0,1] op_sel_hi:[1,0]
	v_sub_f32_e32 v44, v44, v45
	v_add_f32_e32 v42, v42, v43
	s_waitcnt lgkmcnt(2)
	v_add_f32_e32 v42, v110, v42
	v_add_f32_e32 v44, v106, v44
	v_pk_mul_f32 v[42:43], v[88:89], v[42:43] op_sel:[1,0] op_sel_hi:[0,0]
	v_pk_fma_f32 v[104:105], v[88:89], v[44:45], v[42:43] neg_lo:[0,0,1] neg_hi:[0,0,1]
	v_pk_fma_f32 v[42:43], v[88:89], v[44:45], v[42:43] op_sel_hi:[1,0,1]
	v_mov_b32_e32 v110, v107
	v_mov_b32_e32 v105, v43
	v_pk_add_f32 v[42:43], v[110:111], v[104:105]
	s_nop 0
	v_pk_mul_f32 v[44:45], v[88:89], v[42:43]
	v_pk_mul_f32 v[42:43], v[88:89], v[42:43] op_sel:[0,1] op_sel_hi:[1,0]
	v_sub_f32_e32 v99, v44, v45
	s_waitcnt lgkmcnt(1)
	v_add_f32_e32 v100, v100, v99
	v_add_f32_e32 v99, v42, v43
	s_waitcnt lgkmcnt(0)
	v_add_f32_e32 v102, v102, v99
	v_pk_mul_f32 v[112:113], v[88:89], v[102:103] op_sel:[1,0] op_sel_hi:[0,0]
	v_pk_fma_f32 v[114:115], v[88:89], v[100:101], v[112:113] neg_lo:[0,0,1] neg_hi:[0,0,1]
	v_pk_fma_f32 v[112:113], v[88:89], v[100:101], v[112:113] op_sel_hi:[1,0,1]
	v_mov_b32_e32 v102, v101
	v_mov_b32_e32 v115, v113
	ds_read2_b32 v[44:45], v61 offset0:10 offset1:11
	ds_read2_b32 v[104:105], v61 offset0:12 offset1:13
	ds_read2_b32 v[108:109], v61 offset0:14 offset1:15
	v_pk_add_f32 v[100:101], v[102:103], v[114:115]
	ds_read2_b32 v[42:43], v87 offset1:1
	ds_read2_b32 v[106:107], v96 offset1:1
	ds_read2_b32 v[110:111], v97 offset1:1
	v_pk_mul_f32 v[102:103], v[88:89], v[100:101]
	v_pk_mul_f32 v[100:101], v[88:89], v[100:101] op_sel:[0,1] op_sel_hi:[1,0]
	v_sub_f32_e32 v99, v102, v103
	s_waitcnt lgkmcnt(5)
	v_add_f32_e32 v44, v44, v99
	v_add_f32_e32 v99, v100, v101
	s_waitcnt lgkmcnt(2)
	v_add_f32_e32 v42, v42, v99
	v_pk_mul_f32 v[100:101], v[88:89], v[42:43] op_sel:[1,0] op_sel_hi:[0,0]
	v_pk_fma_f32 v[102:103], v[88:89], v[44:45], v[100:101] neg_lo:[0,0,1] neg_hi:[0,0,1]
	v_pk_fma_f32 v[100:101], v[88:89], v[44:45], v[100:101] op_sel_hi:[1,0,1]
	v_mov_b32_e32 v42, v45
	v_mov_b32_e32 v103, v101
	v_pk_add_f32 v[42:43], v[42:43], v[102:103]
	s_waitcnt lgkmcnt(0)
	s_nop 0
	v_pk_mul_f32 v[44:45], v[88:89], v[42:43]
	v_pk_mul_f32 v[42:43], v[88:89], v[42:43] op_sel:[0,1] op_sel_hi:[1,0]
	v_sub_f32_e32 v44, v44, v45
	v_add_f32_e32 v42, v42, v43
	s_waitcnt lgkmcnt(1)
	v_add_f32_e32 v42, v106, v42
	v_add_f32_e32 v44, v104, v44
	v_pk_mul_f32 v[42:43], v[88:89], v[42:43] op_sel:[1,0] op_sel_hi:[0,0]
	v_pk_fma_f32 v[100:101], v[88:89], v[44:45], v[42:43] neg_lo:[0,0,1] neg_hi:[0,0,1]
	v_pk_fma_f32 v[42:43], v[88:89], v[44:45], v[42:43] op_sel_hi:[1,0,1]
	v_mov_b32_e32 v106, v105
	v_mov_b32_e32 v101, v43
	v_pk_add_f32 v[104:105], v[106:107], v[100:101]
	s_waitcnt vmcnt(1)
	v_mfma_f32_16x16x32_bf16 v[42:45], v[6:9], v[38:41], 0
	v_mul_f32_e64 v100, v88, v104
	v_mul_f32_e64 v101, v89, v105
	v_pk_mul_f32 v[104:105], v[88:89], v[104:105] op_sel:[0,1] op_sel_hi:[1,0]
	v_sub_f32_e32 v99, v100, v101
	v_mfma_f32_16x16x32_bf16 v[100:103], v[2:5], v[38:41], 0
	v_add_f32_e32 v108, v108, v99
	v_add_f32_e32 v99, v104, v105
	s_nop 0
	ds_write2_b32 v65, v42, v43 offset1:17
	ds_write2_b32 v65, v44, v45 offset0:34 offset1:51
	v_mfma_f32_16x16x32_bf16 v[104:107], v[30:33], v[38:41], 0
	s_nop 1
	ds_write2_b32 v69, v100, v101 offset0:16 offset1:33
	ds_write2_b32 v69, v102, v103 offset0:50 offset1:67
	s_nop 3
	ds_write2_b32 v67, v104, v105 offset0:32 offset1:49
	s_waitcnt lgkmcnt(5)
; DI void s5_bu16(const bf16x8 ub, const bf16x8 (&af)[8], float* buf, int r, int q) {
; #pragma unroll
;     for (int pt = 0; pt < 8; ++pt) { f32x4 d = {0.f, 0.f, 0.f, 0.f}; d = __builtin_amdgcn_mfma_f32_16x16x32_bf16(af[pt], ub, d, 0, 0, 0);
; #pragma unroll
;         for (int j = 0; j < 4; ++j) buf[(16 * pt + 4 * q + j) * 17 + r] = d[j]; }
; }
; DI void s5_pass1_item(const Params& P, int bitem, unsigned char* smem) {
;     int tid_ = threadIdx.x; asm volatile("" : "+v"(tid_));
;     unsigned char* ws = P.ws; const int tid = tid_, wid = tid >> 6, lane = tid & 63, r = lane & 15, q = lane >> 4;
;     const int item = bitem * 8 + wid, ch = item & 31, grp = (item >> 5) & 63, b = item >> 11;
;     const bf16_t* proj = (const bf16_t*)(ws + WS_PROJ); const float* sm = (const float*)(ws + WS_SMALL);
;     float* buf = (float*)smem + wid * 2176;
;     const bf16_t* tb = (const bf16_t*)(sm + SM_BB);
;     bf16x8 af[8];
; #pragma unroll
;     for (int pt = 0; pt < 8; ++pt) af[pt] = *(const bf16x8*)(tb + (grp * 128 + 16 * pt + r) * 32 + 8 * q);
;     const f32x4 ab = *(const f32x4*)(sm + SM_AB + (grp * 64 + lane) * 4);
;     const bf16_t* ubase = proj + (size_t)(b * TT + ch * 64) * NPROJ + C_SSM + grp * 16;
;     float xr = 0.f, xi = 0.f;
;     bf16x8 ubs[4];
; #pragma unroll
;     for (int sub = 0; sub < 4; ++sub) ubs[sub] = *(const bf16x8*)(ubase + (size_t)(sub * 16 + r) * NPROJ + 8 * (q & 1));
; #pragma unroll
;     for (int sub = 0; sub < 4; ++sub) {
;         s5_bu16(ubs[sub], af, buf, r, q);
;         asm volatile("s_waitcnt lgkmcnt(0)" ::: "memory");
; #pragma unroll
;         for (int tt = 0; tt < 16; ++tt) { const float bur = buf[lane * 17 + tt], bui = buf[(64 + lane) * 17 + tt];
;             const float nxr = ab[0] * xr - ab[1] * xi + bur, nxi = ab[0] * xi + ab[1] * xr + bui; xr = nxr; xi = nxi; }
;         asm volatile("s_waitcnt lgkmcnt(0)" ::: "memory");
;     }
;     f32x2_t e = {xr, xi};
;     *(f32x2_t*)(ws + WS_S5END + ((size_t)((b * 64 + grp) * 32 + ch) * 64 + lane) * 8) = e;
	v_add_f32_e32 v110, v110, v99
	v_mfma_f32_16x16x32_bf16 v[42:45], v[26:29], v[38:41], 0
	ds_write2_b32 v67, v106, v107 offset0:66 offset1:83
	s_nop 6
	ds_write2_b32 v71, v42, v43 offset0:48 offset1:65
	ds_write2_b32 v71, v44, v45 offset0:82 offset1:99
	v_mfma_f32_16x16x32_bf16 v[100:103], v[22:25], v[38:41], 0
	v_mfma_f32_16x16x32_bf16 v[42:45], v[18:21], v[38:41], 0
	s_nop 6
	ds_write2_b32 v73, v100, v101 offset0:64 offset1:81
	ds_write2_b32 v73, v102, v103 offset0:98 offset1:115
	ds_write2_b32 v75, v42, v43 offset0:80 offset1:97
	v_pk_mul_f32 v[42:43], v[88:89], v[110:111] op_sel:[1,0] op_sel_hi:[0,0]
	v_mfma_f32_16x16x32_bf16 v[100:103], v[14:17], v[38:41], 0
	ds_write2_b32 v75, v44, v45 offset0:114 offset1:131
	s_nop 6
	ds_write2_b32 v77, v100, v101 offset0:96 offset1:113
	ds_write2_b32 v77, v102, v103 offset0:130 offset1:147
	v_mfma_f32_16x16x32_bf16 v[38:41], v[10:13], v[38:41], 0
	s_nop 7
	ds_write2_b32 v98, v38, v39 offset0:112 offset1:129
	ds_write2_b32 v98, v40, v41 offset0:146 offset1:163
	s_waitcnt lgkmcnt(0)
	v_pk_fma_f32 v[44:45], v[88:89], v[108:109], v[42:43] neg_lo:[0,0,1] neg_hi:[0,0,1]
	v_pk_fma_f32 v[42:43], v[88:89], v[108:109], v[42:43] op_sel_hi:[1,0,1]
	ds_read2_b32 v[38:39], v61 offset1:1
	ds_read2_b32 v[40:41], v63 offset1:1
	v_mov_b32_e32 v45, v43
	v_mov_b32_e32 v110, v109
	v_pk_add_f32 v[42:43], v[110:111], v[44:45]
	s_waitcnt vmcnt(0)
	v_mfma_f32_16x16x32_bf16 v[6:9], v[6:9], v[34:37], 0
	v_mul_f32_e64 v44, v88, v42
	v_mul_f32_e64 v45, v89, v43
	v_pk_mul_f32 v[42:43], v[88:89], v[42:43] op_sel:[0,1] op_sel_hi:[1,0]
	v_sub_f32_e32 v99, v44, v45
	s_waitcnt lgkmcnt(1)
	v_add_f32_e32 v38, v99, v38
	v_add_f32_e32 v99, v42, v43
	s_waitcnt lgkmcnt(0)
	v_add_f32_e32 v40, v99, v40
	v_pk_mul_f32 v[108:109], v[88:89], v[40:41] op_sel:[1,0] op_sel_hi:[0,0]
	v_pk_fma_f32 v[110:111], v[88:89], v[38:39], v[108:109] neg_lo:[0,0,1] neg_hi:[0,0,1]
	v_pk_fma_f32 v[108:109], v[88:89], v[38:39], v[108:109] op_sel_hi:[1,0,1]
	v_mov_b32_e32 v40, v39
	v_mov_b32_e32 v111, v109
	ds_read2_b32 v[44:45], v61 offset0:2 offset1:3
	ds_read2_b32 v[100:101], v61 offset0:4 offset1:5
	ds_read2_b32 v[102:103], v61 offset0:6 offset1:7
	ds_read2_b32 v[42:43], v79 offset1:1
	ds_read2_b32 v[104:105], v81 offset1:1
	ds_read2_b32 v[106:107], v83 offset1:1
	v_pk_add_f32 v[38:39], v[40:41], v[110:111]
	v_mfma_f32_16x16x32_bf16 v[2:5], v[2:5], v[34:37], 0
	v_mul_f32_e64 v40, v88, v38
	v_mul_f32_e64 v41, v89, v39
	v_pk_mul_f32 v[38:39], v[88:89], v[38:39] op_sel:[0,1] op_sel_hi:[1,0]
	v_sub_f32_e32 v40, v40, v41
	v_add_f32_e32 v38, v38, v39
	s_waitcnt lgkmcnt(2)
	v_add_f32_e32 v38, v42, v38
	v_add_f32_e32 v40, v44, v40
	v_pk_mul_f32 v[38:39], v[88:89], v[38:39] op_sel:[1,0] op_sel_hi:[0,0]
	v_pk_fma_f32 v[108:109], v[88:89], v[40:41], v[38:39] neg_lo:[0,0,1] neg_hi:[0,0,1]
	v_pk_fma_f32 v[38:39], v[88:89], v[40:41], v[38:39] op_sel_hi:[1,0,1]
	v_mov_b32_e32 v42, v45
	v_mov_b32_e32 v109, v39
	v_pk_add_f32 v[38:39], v[42:43], v[108:109]
	v_mfma_f32_16x16x32_bf16 v[30:33], v[30:33], v[34:37], 0
	v_mul_f32_e64 v40, v88, v38
	v_mul_f32_e64 v41, v89, v39
	v_pk_mul_f32 v[38:39], v[88:89], v[38:39] op_sel:[0,1] op_sel_hi:[1,0]
	v_sub_f32_e32 v40, v40, v41
	v_add_f32_e32 v38, v38, v39
	s_waitcnt lgkmcnt(1)
	v_add_f32_e32 v38, v104, v38
	v_add_f32_e32 v40, v100, v40
	v_pk_mul_f32 v[38:39], v[88:89], v[38:39] op_sel:[1,0] op_sel_hi:[0,0]
	v_pk_fma_f32 v[42:43], v[88:89], v[40:41], v[38:39] neg_lo:[0,0,1] neg_hi:[0,0,1]
	v_pk_fma_f32 v[38:39], v[88:89], v[40:41], v[38:39] op_sel_hi:[1,0,1]
	v_mov_b32_e32 v104, v101
	v_mov_b32_e32 v43, v39
	v_pk_add_f32 v[38:39], v[104:105], v[42:43]
	ds_read2_b32 v[42:43], v61 offset0:8 offset1:9
	ds_read2_b32 v[44:45], v85 offset1:1
	v_pk_mul_f32 v[40:41], v[88:89], v[38:39]
	v_pk_mul_f32 v[38:39], v[88:89], v[38:39] op_sel:[0,1] op_sel_hi:[1,0]
	v_sub_f32_e32 v40, v40, v41
	v_add_f32_e32 v38, v38, v39
	s_waitcnt lgkmcnt(2)
	v_add_f32_e32 v38, v106, v38
	v_add_f32_e32 v40, v102, v40
	v_pk_mul_f32 v[38:39], v[88:89], v[38:39] op_sel:[1,0] op_sel_hi:[0,0]
	v_pk_fma_f32 v[100:101], v[88:89], v[40:41], v[38:39] neg_lo:[0,0,1] neg_hi:[0,0,1]
	v_pk_fma_f32 v[38:39], v[88:89], v[40:41], v[38:39] op_sel_hi:[1,0,1]
	v_mov_b32_e32 v106, v103
	v_mov_b32_e32 v101, v39
	v_pk_add_f32 v[38:39], v[106:107], v[100:101]
	s_nop 0
	v_pk_mul_f32 v[40:41], v[88:89], v[38:39]
	v_pk_mul_f32 v[38:39], v[88:89], v[38:39] op_sel:[0,1] op_sel_hi:[1,0]
	v_sub_f32_e32 v99, v40, v41
	s_waitcnt lgkmcnt(1)
	v_add_f32_e32 v42, v42, v99
	v_add_f32_e32 v99, v38, v39
	s_waitcnt lgkmcnt(0)
	v_add_f32_e32 v44, v44, v99
	v_pk_mul_f32 v[108:109], v[88:89], v[44:45] op_sel:[1,0] op_sel_hi:[0,0]
	v_pk_fma_f32 v[110:111], v[88:89], v[42:43], v[108:109] neg_lo:[0,0,1] neg_hi:[0,0,1]
	v_pk_fma_f32 v[108:109], v[88:89], v[42:43], v[108:109] op_sel_hi:[1,0,1]
	v_mov_b32_e32 v44, v43
	v_mov_b32_e32 v111, v109
	ds_read2_b32 v[40:41], v61 offset0:10 offset1:11
	ds_read2_b32 v[100:101], v61 offset0:12 offset1:13
	ds_read2_b32 v[102:103], v61 offset0:14 offset1:15
	ds_read2_b32 v[38:39], v87 offset1:1
	ds_read2_b32 v[104:105], v96 offset1:1
	ds_read2_b32 v[106:107], v97 offset1:1
	v_pk_add_f32 v[42:43], v[44:45], v[110:111]
	s_waitcnt lgkmcnt(0)
	ds_write2_b32 v65, v6, v7 offset1:17
	ds_write2_b32 v65, v8, v9 offset0:34 offset1:51
	v_pk_mul_f32 v[44:45], v[88:89], v[42:43]
	v_pk_mul_f32 v[42:43], v[88:89], v[42:43] op_sel:[0,1] op_sel_hi:[1,0]
	v_sub_f32_e32 v44, v44, v45
	v_add_f32_e32 v42, v42, v43
	s_waitcnt lgkmcnt(4)
; DI void s5_bu16(const bf16x8 ub, const bf16x8 (&af)[8], float* buf, int r, int q) {
; #pragma unroll
;     for (int pt = 0; pt < 8; ++pt) { f32x4 d = {0.f, 0.f, 0.f, 0.f}; d = __builtin_amdgcn_mfma_f32_16x16x32_bf16(af[pt], ub, d, 0, 0, 0);
; #pragma unroll
;         for (int j = 0; j < 4; ++j) buf[(16 * pt + 4 * q + j) * 17 + r] = d[j]; }
; }
; DI void s5_pass1_item(const Params& P, int bitem, unsigned char* smem) {
;     int tid_ = threadIdx.x; asm volatile("" : "+v"(tid_));
;     unsigned char* ws = P.ws; const int tid = tid_, wid = tid >> 6, lane = tid & 63, r = lane & 15, q = lane >> 4;
;     const int item = bitem * 8 + wid, ch = item & 31, grp = (item >> 5) & 63, b = item >> 11;
;     const bf16_t* proj = (const bf16_t*)(ws + WS_PROJ); const float* sm = (const float*)(ws + WS_SMALL);
;     float* buf = (float*)smem + wid * 2176;
;     const bf16_t* tb = (const bf16_t*)(sm + SM_BB);
;     bf16x8 af[8];
; #pragma unroll
;     for (int pt = 0; pt < 8; ++pt) af[pt] = *(const bf16x8*)(tb + (grp * 128 + 16 * pt + r) * 32 + 8 * q);
;     const f32x4 ab = *(const f32x4*)(sm + SM_AB + (grp * 64 + lane) * 4);
;     const bf16_t* ubase = proj + (size_t)(b * TT + ch * 64) * NPROJ + C_SSM + grp * 16;
;     float xr = 0.f, xi = 0.f;
;     bf16x8 ubs[4];
; #pragma unroll
;     for (int sub = 0; sub < 4; ++sub) ubs[sub] = *(const bf16x8*)(ubase + (size_t)(sub * 16 + r) * NPROJ + 8 * (q & 1));
; #pragma unroll
;     for (int sub = 0; sub < 4; ++sub) {
;         s5_bu16(ubs[sub], af, buf, r, q);
;         asm volatile("s_waitcnt lgkmcnt(0)" ::: "memory");
; #pragma unroll
;         for (int tt = 0; tt < 16; ++tt) { const float bur = buf[lane * 17 + tt], bui = buf[(64 + lane) * 17 + tt];
;             const float nxr = ab[0] * xr - ab[1] * xi + bur, nxi = ab[0] * xi + ab[1] * xr + bui; xr = nxr; xi = nxi; }
;         asm volatile("s_waitcnt lgkmcnt(0)" ::: "memory");
;     }
;     f32x2_t e = {xr, xi};
;     *(f32x2_t*)(ws + WS_S5END + ((size_t)((b * 64 + grp) * 32 + ch) * 64 + lane) * 8) = e;
	v_add_f32_e32 v38, v38, v42
	v_add_f32_e32 v40, v40, v44
	v_pk_mul_f32 v[42:43], v[88:89], v[38:39] op_sel:[1,0] op_sel_hi:[0,0]
	v_pk_fma_f32 v[44:45], v[88:89], v[40:41], v[42:43] neg_lo:[0,0,1] neg_hi:[0,0,1]
	v_pk_fma_f32 v[42:43], v[88:89], v[40:41], v[42:43] op_sel_hi:[1,0,1]
	v_mfma_f32_16x16x32_bf16 v[6:9], v[26:29], v[34:37], 0
	v_mov_b32_e32 v45, v43
	v_mov_b32_e32 v38, v41
	ds_write2_b32 v69, v2, v3 offset0:16 offset1:33
	ds_write2_b32 v69, v4, v5 offset0:50 offset1:67
	ds_write2_b32 v67, v30, v31 offset0:32 offset1:49
	v_mfma_f32_16x16x32_bf16 v[2:5], v[22:25], v[34:37], 0
	v_add_f32_e64 v38, v38, v44
	v_add_f32_e64 v39, v39, v45
	ds_write2_b32 v67, v32, v33 offset0:66 offset1:83
	ds_write2_b32 v71, v6, v7 offset0:48 offset1:65
	ds_write2_b32 v71, v8, v9 offset0:82 offset1:99
	v_pk_mul_f32 v[40:41], v[88:89], v[38:39]
	v_pk_mul_f32 v[38:39], v[88:89], v[38:39] op_sel:[0,1] op_sel_hi:[1,0]
	v_mfma_f32_16x16x32_bf16 v[6:9], v[18:21], v[34:37], 0
	v_add_f32_e32 v38, v38, v39
	v_sub_f32_e32 v40, v40, v41
	s_waitcnt lgkmcnt(9)
	v_add_f32_e32 v38, v104, v38
	ds_write2_b32 v73, v2, v3 offset0:64 offset1:81
	ds_write2_b32 v73, v4, v5 offset0:98 offset1:115
	s_nop 1
	ds_write2_b32 v75, v6, v7 offset0:80 offset1:97
	v_mfma_f32_16x16x32_bf16 v[2:5], v[14:17], v[34:37], 0
	v_add_f32_e32 v40, v100, v40
	v_pk_mul_f32 v[38:39], v[88:89], v[38:39] op_sel:[1,0] op_sel_hi:[0,0]
	v_pk_fma_f32 v[42:43], v[88:89], v[40:41], v[38:39] neg_lo:[0,0,1] neg_hi:[0,0,1]
	v_pk_fma_f32 v[38:39], v[88:89], v[40:41], v[38:39] op_sel_hi:[1,0,1]
	v_mov_b32_e32 v104, v101
	v_mov_b32_e32 v43, v39
	ds_write2_b32 v75, v8, v9 offset0:114 offset1:131
	s_nop 0
	ds_write2_b32 v77, v2, v3 offset0:96 offset1:113
	ds_write2_b32 v77, v4, v5 offset0:130 offset1:147
	v_mfma_f32_16x16x32_bf16 v[2:5], v[10:13], v[34:37], 0
	v_add_f32_e64 v38, v104, v42
	v_add_f32_e64 v39, v105, v43
	s_nop 5
	ds_write2_b32 v98, v2, v3 offset0:112 offset1:129
	ds_write2_b32 v98, v4, v5 offset0:146 offset1:163
	v_pk_mul_f32 v[40:41], v[88:89], v[38:39]
	v_pk_mul_f32 v[38:39], v[88:89], v[38:39] op_sel:[0,1] op_sel_hi:[1,0]
	v_sub_f32_e32 v40, v40, v41
	v_add_f32_e32 v38, v38, v39
	s_waitcnt lgkmcnt(14)
	v_add_f32_e32 v38, v106, v38
	v_add_f32_e32 v40, v102, v40
	s_waitcnt lgkmcnt(0)
	v_pk_mul_f32 v[6:7], v[88:89], v[38:39] op_sel:[1,0] op_sel_hi:[0,0]
	ds_read2_b32 v[2:3], v61 offset1:1
	ds_read2_b32 v[4:5], v63 offset1:1
	v_pk_fma_f32 v[8:9], v[88:89], v[40:41], v[6:7] neg_lo:[0,0,1] neg_hi:[0,0,1]
	v_pk_fma_f32 v[6:7], v[88:89], v[40:41], v[6:7] op_sel_hi:[1,0,1]
	v_mov_b32_e32 v106, v103
	v_mov_b32_e32 v9, v7
	v_pk_add_f32 v[6:7], v[106:107], v[8:9]
	s_nop 0
	v_pk_mul_f32 v[8:9], v[88:89], v[6:7]
	v_pk_mul_f32 v[6:7], v[88:89], v[6:7] op_sel:[0,1] op_sel_hi:[1,0]
	v_sub_f32_e32 v14, v8, v9
	v_add_f32_e32 v18, v6, v7
	s_waitcnt lgkmcnt(0)
	v_add_f32_e32 v4, v18, v4
	v_add_f32_e32 v2, v14, v2
	v_pk_mul_f32 v[18:19], v[88:89], v[4:5] op_sel:[1,0] op_sel_hi:[0,0]
	v_pk_fma_f32 v[20:21], v[88:89], v[2:3], v[18:19] neg_lo:[0,0,1] neg_hi:[0,0,1]
	v_pk_fma_f32 v[18:19], v[88:89], v[2:3], v[18:19] op_sel_hi:[1,0,1]
	v_mov_b32_e32 v4, v3
	v_mov_b32_e32 v21, v19
	ds_read2_b32 v[8:9], v61 offset0:2 offset1:3
	ds_read2_b32 v[10:11], v61 offset0:4 offset1:5
	ds_read2_b32 v[12:13], v61 offset0:6 offset1:7
	ds_read2_b32 v[6:7], v79 offset1:1
	ds_read2_b32 v[14:15], v81 offset1:1
	ds_read2_b32 v[16:17], v83 offset1:1
	v_pk_add_f32 v[2:3], v[4:5], v[20:21]
	s_nop 0
	v_pk_mul_f32 v[4:5], v[88:89], v[2:3]
	v_pk_mul_f32 v[2:3], v[88:89], v[2:3] op_sel:[0,1] op_sel_hi:[1,0]
	v_sub_f32_e32 v4, v4, v5
	v_add_f32_e32 v2, v2, v3
	s_waitcnt lgkmcnt(2)
	v_add_f32_e32 v2, v6, v2
	v_add_f32_e32 v4, v8, v4
	v_pk_mul_f32 v[2:3], v[88:89], v[2:3] op_sel:[1,0] op_sel_hi:[0,0]
	v_pk_fma_f32 v[18:19], v[88:89], v[4:5], v[2:3] neg_lo:[0,0,1] neg_hi:[0,0,1]
	v_pk_fma_f32 v[2:3], v[88:89], v[4:5], v[2:3] op_sel_hi:[1,0,1]
	v_mov_b32_e32 v6, v9
	v_mov_b32_e32 v19, v3
	v_pk_add_f32 v[2:3], v[6:7], v[18:19]
	s_nop 0
	v_pk_mul_f32 v[4:5], v[88:89], v[2:3]
	v_pk_mul_f32 v[2:3], v[88:89], v[2:3] op_sel:[0,1] op_sel_hi:[1,0]
	v_sub_f32_e32 v4, v4, v5
	v_add_f32_e32 v2, v2, v3
	s_waitcnt lgkmcnt(1)
; DI void s5_pass1_item(const Params& P, int bitem, unsigned char* smem) {
;     ...
; #pragma unroll
;     for (int sub = 0; sub < 4; ++sub) {
;         s5_bu16(ubs[sub], af, buf, r, q);
;         asm volatile("s_waitcnt lgkmcnt(0)" ::: "memory");
; #pragma unroll
;         for (int tt = 0; tt < 16; ++tt) { const float bur = buf[lane * 17 + tt], bui = buf[(64 + lane) * 17 + tt];
;             const float nxr = ab[0] * xr - ab[1] * xi + bur, nxi = ab[0] * xi + ab[1] * xr + bui; xr = nxr; xi = nxi; }
;         asm volatile("s_waitcnt lgkmcnt(0)" ::: "memory");
;     }
;     f32x2_t e = {xr, xi};
;     *(f32x2_t*)(ws + WS_S5END + ((size_t)((b * 64 + grp) * 32 + ch) * 64 + lane) * 8) = e;
	v_add_f32_e32 v2, v14, v2
	v_add_f32_e32 v4, v10, v4
	v_pk_mul_f32 v[2:3], v[88:89], v[2:3] op_sel:[1,0] op_sel_hi:[0,0]
	v_pk_fma_f32 v[6:7], v[88:89], v[4:5], v[2:3] neg_lo:[0,0,1] neg_hi:[0,0,1]
	v_pk_fma_f32 v[2:3], v[88:89], v[4:5], v[2:3] op_sel_hi:[1,0,1]
	v_mov_b32_e32 v14, v11
	v_mov_b32_e32 v7, v3
	v_pk_add_f32 v[2:3], v[14:15], v[6:7]
	ds_read2_b32 v[6:7], v61 offset0:8 offset1:9
	ds_read2_b32 v[8:9], v85 offset1:1
	v_pk_mul_f32 v[4:5], v[88:89], v[2:3]
	v_pk_mul_f32 v[2:3], v[88:89], v[2:3] op_sel:[0,1] op_sel_hi:[1,0]
	v_sub_f32_e32 v4, v4, v5
	v_add_f32_e32 v2, v2, v3
	s_waitcnt lgkmcnt(2)
	v_add_f32_e32 v2, v16, v2
	v_add_f32_e32 v4, v12, v4
	v_pk_mul_f32 v[2:3], v[88:89], v[2:3] op_sel:[1,0] op_sel_hi:[0,0]
	v_pk_fma_f32 v[10:11], v[88:89], v[4:5], v[2:3] neg_lo:[0,0,1] neg_hi:[0,0,1]
	v_pk_fma_f32 v[2:3], v[88:89], v[4:5], v[2:3] op_sel_hi:[1,0,1]
	v_mov_b32_e32 v16, v13
	v_mov_b32_e32 v11, v3
	v_pk_add_f32 v[2:3], v[16:17], v[10:11]
	s_nop 0
	v_pk_mul_f32 v[4:5], v[88:89], v[2:3]
	v_pk_mul_f32 v[2:3], v[88:89], v[2:3] op_sel:[0,1] op_sel_hi:[1,0]
	v_sub_f32_e32 v14, v4, v5
	v_add_f32_e32 v18, v2, v3
	s_waitcnt lgkmcnt(0)
	v_add_f32_e32 v8, v8, v18
	v_add_f32_e32 v6, v6, v14
	v_pk_mul_f32 v[18:19], v[88:89], v[8:9] op_sel:[1,0] op_sel_hi:[0,0]
	v_pk_fma_f32 v[20:21], v[88:89], v[6:7], v[18:19] neg_lo:[0,0,1] neg_hi:[0,0,1]
	v_pk_fma_f32 v[18:19], v[88:89], v[6:7], v[18:19] op_sel_hi:[1,0,1]
	v_mov_b32_e32 v8, v7
	v_mov_b32_e32 v21, v19
	ds_read2_b32 v[4:5], v61 offset0:10 offset1:11
	ds_read2_b32 v[10:11], v61 offset0:12 offset1:13
	ds_read2_b32 v[12:13], v61 offset0:14 offset1:15
	ds_read2_b32 v[2:3], v87 offset1:1
	ds_read2_b32 v[14:15], v96 offset1:1
	ds_read2_b32 v[16:17], v97 offset1:1
	v_pk_add_f32 v[6:7], v[8:9], v[20:21]
	s_waitcnt lgkmcnt(0)
	s_nop 0
	v_pk_mul_f32 v[8:9], v[88:89], v[6:7]
	v_pk_mul_f32 v[6:7], v[88:89], v[6:7] op_sel:[0,1] op_sel_hi:[1,0]
	v_sub_f32_e32 v8, v8, v9
	v_add_f32_e32 v6, v6, v7
	s_waitcnt lgkmcnt(2)
	v_add_f32_e32 v2, v2, v6
	v_add_f32_e32 v4, v4, v8
	v_pk_mul_f32 v[6:7], v[88:89], v[2:3] op_sel_hi:[1,0]
	s_nop 0
	v_pk_fma_f32 v[8:9], v[88:89], v[4:5], v[6:7] op_sel:[1,0,0] op_sel_hi:[0,1,1]
	v_pk_fma_f32 v[6:7], v[88:89], v[4:5], v[6:7] op_sel:[1,0,0] op_sel_hi:[0,0,1] neg_lo:[0,0,1] neg_hi:[0,0,1]
	v_mov_b32_e32 v9, v7
	v_mov_b32_e32 v4, v3
	v_pk_add_f32 v[2:3], v[4:5], v[8:9]
	s_nop 0
	v_pk_mul_f32 v[4:5], v[88:89], v[2:3] op_sel:[0,1] op_sel_hi:[1,0]
	v_pk_mul_f32 v[2:3], v[88:89], v[2:3]
	v_sub_f32_e32 v4, v4, v5
	v_add_f32_e32 v2, v2, v3
	s_waitcnt lgkmcnt(1)
	v_add_f32_e32 v2, v14, v2
	v_add_f32_e32 v4, v10, v4
	v_pk_mul_f32 v[2:3], v[88:89], v[2:3] op_sel_hi:[1,0]
	v_mov_b32_e32 v10, v15
	v_pk_fma_f32 v[6:7], v[88:89], v[4:5], v[2:3] op_sel:[1,0,0] op_sel_hi:[0,1,1]
	v_pk_fma_f32 v[2:3], v[88:89], v[4:5], v[2:3] op_sel:[1,0,0] op_sel_hi:[0,0,1] neg_lo:[0,0,1] neg_hi:[0,0,1]
	v_mov_b32_e32 v7, v3
	v_pk_add_f32 v[2:3], v[10:11], v[6:7]
	s_nop 0
	v_pk_mul_f32 v[4:5], v[88:89], v[2:3] op_sel:[0,1] op_sel_hi:[1,0]
	v_pk_mul_f32 v[2:3], v[88:89], v[2:3]
	v_sub_f32_e32 v4, v4, v5
	v_add_f32_e32 v2, v2, v3
	s_waitcnt lgkmcnt(0)
	v_add_f32_e32 v2, v16, v2
	v_add_f32_e32 v4, v12, v4
	v_pk_mul_f32 v[2:3], v[88:89], v[2:3] op_sel:[1,0] op_sel_hi:[0,0]
	v_pk_fma_f32 v[6:7], v[88:89], v[4:5], v[2:3] neg_lo:[0,0,1] neg_hi:[0,0,1]
	v_pk_fma_f32 v[2:3], v[88:89], v[4:5], v[2:3] op_sel_hi:[1,0,1]
	v_or3_b32 v4, v46, v57, v55
	v_ashrrev_i32_e32 v5, 31, v4
	v_lshlrev_b64 v[4:5], 9, v[4:5]
	v_mov_b32_e32 v7, v3
	v_mov_b32_e32 v16, v13
	v_lshlrev_b32_e32 v46, 3, v59
	v_lshl_add_u64 v[4:5], s[8:9], 0, v[4:5]
	v_pk_add_f32 v[2:3], v[16:17], v[6:7]
	v_lshl_add_u64 v[4:5], v[4:5], 0, v[46:47]
	global_store_dwordx2 v[4:5], v[2:3], off
	s_barrier

; DI void s5_bu16(const bf16x8 ub, const bf16x8 (&af)[8], float* buf, int r, int q) {
; #pragma unroll
;     for (int pt = 0; pt < 8; ++pt) { f32x4 d = {0.f, 0.f, 0.f, 0.f}; d = __builtin_amdgcn_mfma_f32_16x16x32_bf16(af[pt], ub, d, 0, 0, 0);
; #pragma unroll
;         for (int j = 0; j < 4; ++j) buf[(16 * pt + 4 * q + j) * 17 + r] = d[j]; }
; }
; DI void s5_pass1_item(const Params& P, int bitem, unsigned char* smem) {
;     int tid_ = threadIdx.x; asm volatile("" : "+v"(tid_));
;     unsigned char* ws = P.ws; const int tid = tid_, wid = tid >> 6, lane = tid & 63, r = lane & 15, q = lane >> 4;
;     const int item = bitem * 8 + wid, ch = item & 31, grp = (item >> 5) & 63, b = item >> 11;
;     const bf16_t* proj = (const bf16_t*)(ws + WS_PROJ); const float* sm = (const float*)(ws + WS_SMALL);
;     float* buf = (float*)smem + wid * 2176;
;     const bf16_t* tb = (const bf16_t*)(sm + SM_BB);
;     bf16x8 af[8];
; #pragma unroll
;     for (int pt = 0; pt < 8; ++pt) af[pt] = *(const bf16x8*)(tb + (grp * 128 + 16 * pt + r) * 32 + 8 * q);
;     const f32x4 ab = *(const f32x4*)(sm + SM_AB + (grp * 64 + lane) * 4);
;     const bf16_t* ubase = proj + (size_t)(b * TT + ch * 64) * NPROJ + C_SSM + grp * 16;
;     float xr = 0.f, xi = 0.f;
;     bf16x8 ubs[4];
; #pragma unroll
;     for (int sub = 0; sub < 4; ++sub) ubs[sub] = *(const bf16x8*)(ubase + (size_t)(sub * 16 + r) * NPROJ + 8 * (q & 1));
; #pragma unroll
;     for (int sub = 0; sub < 4; ++sub) {
;         s5_bu16(ubs[sub], af, buf, r, q);
;         asm volatile("s_waitcnt lgkmcnt(0)" ::: "memory");
; #pragma unroll
;         for (int tt = 0; tt < 16; ++tt) { const float bur = buf[lane * 17 + tt], bui = buf[(64 + lane) * 17 + tt];
;             const float nxr = ab[0] * xr - ab[1] * xi + bur, nxi = ab[0] * xi + ab[1] * xr + bui; xr = nxr; xi = nxi; }
.Ls5p1_start:
	v_readlane_b32 s74, v245, 7
	v_readlane_b32 s75, v245, 8
	v_lshrrev_b32_e32 v1, 6, v206
	v_and_b32_e32 v2, 63, v206
	v_and_b32_e32 v3, 15, v206
	v_readfirstlane_b32 s23, v1
	v_bfe_u32 v4, v206, 4, 2
	s_sub_i32 s2, s71, 0xfe
	s_lshr_b32 s24, s2, 2
	s_and_b32 s25, s2, 3
	s_lshl_b32 s25, s25, 3
	s_add_i32 s25, s25, s23
	v_and_b32_e32 v5, 1, v4
	v_lshlrev_b32_e32 v5, 4, v5
	s_movk_i32 s3, 0x1e00
	v_mad_u32_u24 v83, v3, s3, v5
	v_lshlrev_b32_e32 v84, 3, v2
	s_lshl_b32 s4, s24, 13
	s_add_u32 s6, s74, 0x9f20400
	s_addc_u32 s7, s75, 0
	s_add_u32 s6, s6, s4
	s_addc_u32 s7, s7, 0
	s_add_u32 s8, s6, 0x1000
	s_addc_u32 s9, s7, 0
	v_lshlrev_b32_e32 v5, 6, v3
	v_lshl_add_u32 v5, v4, 4, v5
	global_load_dwordx4 v[8:11], v5, s[6:7] offset:0
	global_load_dwordx4 v[12:15], v5, s[6:7] offset:1024
	global_load_dwordx4 v[16:19], v5, s[6:7] offset:2048
	global_load_dwordx4 v[20:23], v5, s[6:7] offset:3072
	global_load_dwordx4 v[24:27], v5, s[8:9] offset:0
	global_load_dwordx4 v[28:31], v5, s[8:9] offset:1024
	global_load_dwordx4 v[32:35], v5, s[8:9] offset:2048
	global_load_dwordx4 v[36:39], v5, s[8:9] offset:3072
	s_lshl_b32 s4, s24, 10
	s_add_u32 s10, s74, 0x9f10400
	s_addc_u32 s11, s75, 0
	s_add_u32 s10, s10, s4
	s_addc_u32 s11, s11, 0
	v_lshlrev_b32_e32 v6, 4, v2
	global_load_dwordx4 v[72:75], v6, s[10:11]
	s_mul_i32 s4, s25, 0x78000
	s_lshl_b32 s5, s24, 5
	s_add_i32 s4, s4, s5
	s_add_i32 s4, s4, 0xf911430
	s_add_u32 s28, s74, s4
	s_addc_u32 s29, s75, 0
	s_lshl_b32 s4, s24, 5
	s_add_i32 s4, s4, s25
	s_lshl_b32 s4, s4, 9
	s_add_i32 s4, s4, 0xa110000
	s_add_u32 s30, s74, s4
	s_addc_u32 s31, s75, 0
	s_add_u32 s40, s28, 0x0
	s_addc_u32 s41, s29, 0
	s_add_u32 s42, s28, 0x1e000
	s_addc_u32 s43, s29, 0
	s_add_u32 s44, s28, 0x3c000
	s_addc_u32 s45, s29, 0
	s_add_u32 s46, s28, 0x5a000
	s_addc_u32 s47, s29, 0
	global_load_dwordx4 v[120:123], v83, s[40:41]
	global_load_dwordx4 v[124:127], v83, s[42:43]
	global_load_dwordx4 v[128:131], v83, s[44:45]
	global_load_dwordx4 v[132:135], v83, s[46:47]
	s_mov_b32 s26, 0
	s_waitcnt vmcnt(0)
.Ls5p1_round:
	s_waitcnt vmcnt(1)
	v_mov_b32_e32 v88, v120
	v_mov_b32_e32 v89, v121
	v_mov_b32_e32 v90, v122
	v_mov_b32_e32 v91, v123
	v_mov_b32_e32 v92, v124
	v_mov_b32_e32 v93, v125
	v_mov_b32_e32 v94, v126
	v_mov_b32_e32 v95, v127
	v_mov_b32_e32 v96, v128
	v_mov_b32_e32 v97, v129
	v_mov_b32_e32 v98, v130
	v_mov_b32_e32 v99, v131
	v_mov_b32_e32 v100, v132
	v_mov_b32_e32 v101, v133
	v_mov_b32_e32 v102, v134
	v_mov_b32_e32 v103, v135
	s_add_u32 s28, s28, 0xf00000
	s_addc_u32 s29, s29, 0
	s_add_u32 s40, s28, 0x0
	s_addc_u32 s41, s29, 0
	s_add_u32 s42, s28, 0x1e000
	s_addc_u32 s43, s29, 0
	s_add_u32 s44, s28, 0x3c000
	s_addc_u32 s45, s29, 0
	s_add_u32 s46, s28, 0x5a000
	s_addc_u32 s47, s29, 0
	global_load_dwordx4 v[120:123], v83, s[40:41]
	global_load_dwordx4 v[124:127], v83, s[42:43]
	global_load_dwordx4 v[128:131], v83, s[44:45]
	global_load_dwordx4 v[132:135], v83, s[46:47]
	v_mov_b32_e32 v192, 0
	v_mov_b32_e32 v193, 0
	v_mfma_f32_16x16x32_bf16 v[160:163], v[88:91], v[8:11], 0
	v_mfma_f32_16x16x32_bf16 v[164:167], v[88:91], v[12:15], 0
	v_mfma_f32_16x16x32_bf16 v[168:171], v[88:91], v[16:19], 0
	v_mfma_f32_16x16x32_bf16 v[172:175], v[88:91], v[20:23], 0
	v_mfma_f32_16x16x32_bf16 v[176:179], v[88:91], v[24:27], 0
	v_mfma_f32_16x16x32_bf16 v[180:183], v[88:91], v[28:31], 0
	v_mfma_f32_16x16x32_bf16 v[184:187], v[88:91], v[32:35], 0
	v_mfma_f32_16x16x32_bf16 v[188:191], v[88:91], v[36:39], 0
	s_nop 7
	v_permlane32_swap_b32_e32 v160, v168
	v_permlane32_swap_b32_e32 v161, v169
	v_permlane32_swap_b32_e32 v162, v170
	v_permlane32_swap_b32_e32 v163, v171
	v_permlane32_swap_b32_e32 v164, v172
	v_permlane32_swap_b32_e32 v165, v173
	v_permlane32_swap_b32_e32 v166, v174
	v_permlane32_swap_b32_e32 v167, v175
	v_permlane32_swap_b32_e32 v176, v184
	v_permlane32_swap_b32_e32 v177, v185
	v_permlane32_swap_b32_e32 v178, v186
	v_permlane32_swap_b32_e32 v179, v187
	v_permlane32_swap_b32_e32 v180, v188
	v_permlane32_swap_b32_e32 v181, v189
	v_permlane32_swap_b32_e32 v182, v190
	v_permlane32_swap_b32_e32 v183, v191
	v_permlane16_swap_b32_e32 v160, v164
	v_permlane16_swap_b32_e32 v161, v165
	v_permlane16_swap_b32_e32 v162, v166
	v_permlane16_swap_b32_e32 v163, v167
	v_permlane16_swap_b32_e32 v168, v172
	v_permlane16_swap_b32_e32 v169, v173
	v_permlane16_swap_b32_e32 v170, v174
	v_permlane16_swap_b32_e32 v171, v175
	v_permlane16_swap_b32_e32 v176, v180
	v_permlane16_swap_b32_e32 v177, v181
	v_permlane16_swap_b32_e32 v178, v182
	v_permlane16_swap_b32_e32 v179, v183
	v_permlane16_swap_b32_e32 v184, v188
	v_permlane16_swap_b32_e32 v185, v189
	v_permlane16_swap_b32_e32 v186, v190
	v_permlane16_swap_b32_e32 v187, v191
	v_mul_f32_e32 v194, v73, v193
	v_mul_f32_e32 v195, v73, v192
	v_fma_f32 v194, v72, v192, -v194
	v_fma_f32 v195, v72, v193, v195
	v_add_f32_e32 v192, v194, v160
	v_add_f32_e32 v193, v195, v176
	v_mul_f32_e32 v194, v73, v193
	v_mul_f32_e32 v195, v73, v192
	v_fma_f32 v194, v72, v192, -v194
	v_fma_f32 v195, v72, v193, v195
	v_add_f32_e32 v192, v194, v161
	v_add_f32_e32 v193, v195, v177
	v_mul_f32_e32 v194, v73, v193
	v_mul_f32_e32 v195, v73, v192
	v_fma_f32 v194, v72, v192, -v194
	v_fma_f32 v195, v72, v193, v195
	v_add_f32_e32 v192, v194, v162
	v_add_f32_e32 v193, v195, v178
	v_mul_f32_e32 v194, v73, v193
	v_mul_f32_e32 v195, v73, v192
	v_fma_f32 v194, v72, v192, -v194
	v_fma_f32 v195, v72, v193, v195
	v_add_f32_e32 v192, v194, v163
	v_add_f32_e32 v193, v195, v179
	v_mul_f32_e32 v194, v73, v193
	v_mul_f32_e32 v195, v73, v192
	v_fma_f32 v194, v72, v192, -v194
	v_fma_f32 v195, v72, v193, v195
	v_add_f32_e32 v192, v194, v164
; DI void s5_bu16(const bf16x8 ub, const bf16x8 (&af)[8], float* buf, int r, int q) {
; #pragma unroll
;     for (int pt = 0; pt < 8; ++pt) { f32x4 d = {0.f, 0.f, 0.f, 0.f}; d = __builtin_amdgcn_mfma_f32_16x16x32_bf16(af[pt], ub, d, 0, 0, 0);
; #pragma unroll
;         for (int j = 0; j < 4; ++j) buf[(16 * pt + 4 * q + j) * 17 + r] = d[j]; }
; }
; DI void s5_pass1_item(const Params& P, int bitem, unsigned char* smem) {
;     int tid_ = threadIdx.x; asm volatile("" : "+v"(tid_));
;     unsigned char* ws = P.ws; const int tid = tid_, wid = tid >> 6, lane = tid & 63, r = lane & 15, q = lane >> 4;
;     const int item = bitem * 8 + wid, ch = item & 31, grp = (item >> 5) & 63, b = item >> 11;
;     const bf16_t* proj = (const bf16_t*)(ws + WS_PROJ); const float* sm = (const float*)(ws + WS_SMALL);
;     float* buf = (float*)smem + wid * 2176;
;     const bf16_t* tb = (const bf16_t*)(sm + SM_BB);
;     bf16x8 af[8];
; #pragma unroll
;     for (int pt = 0; pt < 8; ++pt) af[pt] = *(const bf16x8*)(tb + (grp * 128 + 16 * pt + r) * 32 + 8 * q);
;     const f32x4 ab = *(const f32x4*)(sm + SM_AB + (grp * 64 + lane) * 4);
;     const bf16_t* ubase = proj + (size_t)(b * TT + ch * 64) * NPROJ + C_SSM + grp * 16;
;     float xr = 0.f, xi = 0.f;
;     bf16x8 ubs[4];
; #pragma unroll
;     for (int sub = 0; sub < 4; ++sub) ubs[sub] = *(const bf16x8*)(ubase + (size_t)(sub * 16 + r) * NPROJ + 8 * (q & 1));
; #pragma unroll
;     for (int sub = 0; sub < 4; ++sub) {
;         s5_bu16(ubs[sub], af, buf, r, q);
;         asm volatile("s_waitcnt lgkmcnt(0)" ::: "memory");
; #pragma unroll
;         for (int tt = 0; tt < 16; ++tt) { const float bur = buf[lane * 17 + tt], bui = buf[(64 + lane) * 17 + tt];
;             const float nxr = ab[0] * xr - ab[1] * xi + bur, nxi = ab[0] * xi + ab[1] * xr + bui; xr = nxr; xi = nxi; }
	v_add_f32_e32 v193, v195, v180
	v_mul_f32_e32 v194, v73, v193
	v_mul_f32_e32 v195, v73, v192
	v_fma_f32 v194, v72, v192, -v194
	v_fma_f32 v195, v72, v193, v195
	v_add_f32_e32 v192, v194, v165
	v_add_f32_e32 v193, v195, v181
	v_mul_f32_e32 v194, v73, v193
	v_mul_f32_e32 v195, v73, v192
	v_fma_f32 v194, v72, v192, -v194
	v_fma_f32 v195, v72, v193, v195
	v_add_f32_e32 v192, v194, v166
	v_add_f32_e32 v193, v195, v182
	v_mul_f32_e32 v194, v73, v193
	v_mul_f32_e32 v195, v73, v192
	v_fma_f32 v194, v72, v192, -v194
	v_fma_f32 v195, v72, v193, v195
	v_add_f32_e32 v192, v194, v167
	v_add_f32_e32 v193, v195, v183
	v_mul_f32_e32 v194, v73, v193
	v_mul_f32_e32 v195, v73, v192
	v_fma_f32 v194, v72, v192, -v194
	v_fma_f32 v195, v72, v193, v195
	v_add_f32_e32 v192, v194, v168
	v_add_f32_e32 v193, v195, v184
	v_mul_f32_e32 v194, v73, v193
	v_mul_f32_e32 v195, v73, v192
	v_fma_f32 v194, v72, v192, -v194
	v_fma_f32 v195, v72, v193, v195
	v_add_f32_e32 v192, v194, v169
	v_add_f32_e32 v193, v195, v185
	v_mul_f32_e32 v194, v73, v193
	v_mul_f32_e32 v195, v73, v192
	v_fma_f32 v194, v72, v192, -v194
	v_fma_f32 v195, v72, v193, v195
	v_add_f32_e32 v192, v194, v170
	v_add_f32_e32 v193, v195, v186
	v_mul_f32_e32 v194, v73, v193
	v_mul_f32_e32 v195, v73, v192
	v_fma_f32 v194, v72, v192, -v194
	v_fma_f32 v195, v72, v193, v195
	v_add_f32_e32 v192, v194, v171
	v_add_f32_e32 v193, v195, v187
	v_mul_f32_e32 v194, v73, v193
	v_mul_f32_e32 v195, v73, v192
	v_fma_f32 v194, v72, v192, -v194
	v_fma_f32 v195, v72, v193, v195
	v_add_f32_e32 v192, v194, v172
	v_add_f32_e32 v193, v195, v188
	v_mul_f32_e32 v194, v73, v193
	v_mul_f32_e32 v195, v73, v192
	v_fma_f32 v194, v72, v192, -v194
	v_fma_f32 v195, v72, v193, v195
	v_add_f32_e32 v192, v194, v173
	v_add_f32_e32 v193, v195, v189
	v_mul_f32_e32 v194, v73, v193
	v_mul_f32_e32 v195, v73, v192
	v_fma_f32 v194, v72, v192, -v194
	v_fma_f32 v195, v72, v193, v195
	v_add_f32_e32 v192, v194, v174
	v_add_f32_e32 v193, v195, v190
	v_mul_f32_e32 v194, v73, v193
	v_mul_f32_e32 v195, v73, v192
	v_fma_f32 v194, v72, v192, -v194
	v_fma_f32 v195, v72, v193, v195
	v_add_f32_e32 v192, v194, v175
	v_add_f32_e32 v193, v195, v191
	v_mfma_f32_16x16x32_bf16 v[160:163], v[92:95], v[8:11], 0
	v_mfma_f32_16x16x32_bf16 v[164:167], v[92:95], v[12:15], 0
	v_mfma_f32_16x16x32_bf16 v[168:171], v[92:95], v[16:19], 0
	v_mfma_f32_16x16x32_bf16 v[172:175], v[92:95], v[20:23], 0
	v_mfma_f32_16x16x32_bf16 v[176:179], v[92:95], v[24:27], 0
	v_mfma_f32_16x16x32_bf16 v[180:183], v[92:95], v[28:31], 0
	v_mfma_f32_16x16x32_bf16 v[184:187], v[92:95], v[32:35], 0
	v_mfma_f32_16x16x32_bf16 v[188:191], v[92:95], v[36:39], 0
	s_nop 7
	v_permlane32_swap_b32_e32 v160, v168
	v_permlane32_swap_b32_e32 v161, v169
	v_permlane32_swap_b32_e32 v162, v170
	v_permlane32_swap_b32_e32 v163, v171
	v_permlane32_swap_b32_e32 v164, v172
	v_permlane32_swap_b32_e32 v165, v173
	v_permlane32_swap_b32_e32 v166, v174
	v_permlane32_swap_b32_e32 v167, v175
	v_permlane32_swap_b32_e32 v176, v184
	v_permlane32_swap_b32_e32 v177, v185
	v_permlane32_swap_b32_e32 v178, v186
	v_permlane32_swap_b32_e32 v179, v187
	v_permlane32_swap_b32_e32 v180, v188
	v_permlane32_swap_b32_e32 v181, v189
	v_permlane32_swap_b32_e32 v182, v190
	v_permlane32_swap_b32_e32 v183, v191
	v_permlane16_swap_b32_e32 v160, v164
	v_permlane16_swap_b32_e32 v161, v165
	v_permlane16_swap_b32_e32 v162, v166
	v_permlane16_swap_b32_e32 v163, v167
	v_permlane16_swap_b32_e32 v168, v172
	v_permlane16_swap_b32_e32 v169, v173
	v_permlane16_swap_b32_e32 v170, v174
	v_permlane16_swap_b32_e32 v171, v175
	v_permlane16_swap_b32_e32 v176, v180
	v_permlane16_swap_b32_e32 v177, v181
	v_permlane16_swap_b32_e32 v178, v182
	v_permlane16_swap_b32_e32 v179, v183
	v_permlane16_swap_b32_e32 v184, v188
	v_permlane16_swap_b32_e32 v185, v189
	v_permlane16_swap_b32_e32 v186, v190
	v_permlane16_swap_b32_e32 v187, v191
	v_mul_f32_e32 v194, v73, v193
	v_mul_f32_e32 v195, v73, v192
	v_fma_f32 v194, v72, v192, -v194
	v_fma_f32 v195, v72, v193, v195
	v_add_f32_e32 v192, v194, v160
	v_add_f32_e32 v193, v195, v176
	v_mul_f32_e32 v194, v73, v193
	v_mul_f32_e32 v195, v73, v192
	v_fma_f32 v194, v72, v192, -v194
	v_fma_f32 v195, v72, v193, v195
	v_add_f32_e32 v192, v194, v161
	v_add_f32_e32 v193, v195, v177
	v_mul_f32_e32 v194, v73, v193
	v_mul_f32_e32 v195, v73, v192
	v_fma_f32 v194, v72, v192, -v194
	v_fma_f32 v195, v72, v193, v195
	v_add_f32_e32 v192, v194, v162
	v_add_f32_e32 v193, v195, v178
	v_mul_f32_e32 v194, v73, v193
	v_mul_f32_e32 v195, v73, v192
	v_fma_f32 v194, v72, v192, -v194
	v_fma_f32 v195, v72, v193, v195
	v_add_f32_e32 v192, v194, v163
	v_add_f32_e32 v193, v195, v179
	v_mul_f32_e32 v194, v73, v193
	v_mul_f32_e32 v195, v73, v192
	v_fma_f32 v194, v72, v192, -v194
	v_fma_f32 v195, v72, v193, v195
	v_add_f32_e32 v192, v194, v164
	v_add_f32_e32 v193, v195, v180
	v_mul_f32_e32 v194, v73, v193
	v_mul_f32_e32 v195, v73, v192
	v_fma_f32 v194, v72, v192, -v194
	v_fma_f32 v195, v72, v193, v195
	v_add_f32_e32 v192, v194, v165
	v_add_f32_e32 v193, v195, v181
	v_mul_f32_e32 v194, v73, v193
	v_mul_f32_e32 v195, v73, v192
	v_fma_f32 v194, v72, v192, -v194
	v_fma_f32 v195, v72, v193, v195
	v_add_f32_e32 v192, v194, v166
	v_add_f32_e32 v193, v195, v182
	v_mul_f32_e32 v194, v73, v193
	v_mul_f32_e32 v195, v73, v192
	v_fma_f32 v194, v72, v192, -v194
	v_fma_f32 v195, v72, v193, v195
	v_add_f32_e32 v192, v194, v167
	v_add_f32_e32 v193, v195, v183
	v_mul_f32_e32 v194, v73, v193
	v_mul_f32_e32 v195, v73, v192
	v_fma_f32 v194, v72, v192, -v194
	v_fma_f32 v195, v72, v193, v195
	v_add_f32_e32 v192, v194, v168
	v_add_f32_e32 v193, v195, v184
	v_mul_f32_e32 v194, v73, v193
; DI void s5_bu16(const bf16x8 ub, const bf16x8 (&af)[8], float* buf, int r, int q) {
; #pragma unroll
;     for (int pt = 0; pt < 8; ++pt) { f32x4 d = {0.f, 0.f, 0.f, 0.f}; d = __builtin_amdgcn_mfma_f32_16x16x32_bf16(af[pt], ub, d, 0, 0, 0);
; #pragma unroll
;         for (int j = 0; j < 4; ++j) buf[(16 * pt + 4 * q + j) * 17 + r] = d[j]; }
; }
; DI void s5_pass1_item(const Params& P, int bitem, unsigned char* smem) {
;     int tid_ = threadIdx.x; asm volatile("" : "+v"(tid_));
;     unsigned char* ws = P.ws; const int tid = tid_, wid = tid >> 6, lane = tid & 63, r = lane & 15, q = lane >> 4;
;     const int item = bitem * 8 + wid, ch = item & 31, grp = (item >> 5) & 63, b = item >> 11;
;     const bf16_t* proj = (const bf16_t*)(ws + WS_PROJ); const float* sm = (const float*)(ws + WS_SMALL);
;     float* buf = (float*)smem + wid * 2176;
;     const bf16_t* tb = (const bf16_t*)(sm + SM_BB);
;     bf16x8 af[8];
; #pragma unroll
;     for (int pt = 0; pt < 8; ++pt) af[pt] = *(const bf16x8*)(tb + (grp * 128 + 16 * pt + r) * 32 + 8 * q);
;     const f32x4 ab = *(const f32x4*)(sm + SM_AB + (grp * 64 + lane) * 4);
;     const bf16_t* ubase = proj + (size_t)(b * TT + ch * 64) * NPROJ + C_SSM + grp * 16;
;     float xr = 0.f, xi = 0.f;
;     bf16x8 ubs[4];
; #pragma unroll
;     for (int sub = 0; sub < 4; ++sub) ubs[sub] = *(const bf16x8*)(ubase + (size_t)(sub * 16 + r) * NPROJ + 8 * (q & 1));
; #pragma unroll
;     for (int sub = 0; sub < 4; ++sub) {
;         s5_bu16(ubs[sub], af, buf, r, q);
;         asm volatile("s_waitcnt lgkmcnt(0)" ::: "memory");
; #pragma unroll
;         for (int tt = 0; tt < 16; ++tt) { const float bur = buf[lane * 17 + tt], bui = buf[(64 + lane) * 17 + tt];
;             const float nxr = ab[0] * xr - ab[1] * xi + bur, nxi = ab[0] * xi + ab[1] * xr + bui; xr = nxr; xi = nxi; }
	v_mul_f32_e32 v195, v73, v192
	v_fma_f32 v194, v72, v192, -v194
	v_fma_f32 v195, v72, v193, v195
	v_add_f32_e32 v192, v194, v169
	v_add_f32_e32 v193, v195, v185
	v_mul_f32_e32 v194, v73, v193
	v_mul_f32_e32 v195, v73, v192
	v_fma_f32 v194, v72, v192, -v194
	v_fma_f32 v195, v72, v193, v195
	v_add_f32_e32 v192, v194, v170
	v_add_f32_e32 v193, v195, v186
	v_mul_f32_e32 v194, v73, v193
	v_mul_f32_e32 v195, v73, v192
	v_fma_f32 v194, v72, v192, -v194
	v_fma_f32 v195, v72, v193, v195
	v_add_f32_e32 v192, v194, v171
	v_add_f32_e32 v193, v195, v187
	v_mul_f32_e32 v194, v73, v193
	v_mul_f32_e32 v195, v73, v192
	v_fma_f32 v194, v72, v192, -v194
	v_fma_f32 v195, v72, v193, v195
	v_add_f32_e32 v192, v194, v172
	v_add_f32_e32 v193, v195, v188
	v_mul_f32_e32 v194, v73, v193
	v_mul_f32_e32 v195, v73, v192
	v_fma_f32 v194, v72, v192, -v194
	v_fma_f32 v195, v72, v193, v195
	v_add_f32_e32 v192, v194, v173
	v_add_f32_e32 v193, v195, v189
	v_mul_f32_e32 v194, v73, v193
	v_mul_f32_e32 v195, v73, v192
	v_fma_f32 v194, v72, v192, -v194
	v_fma_f32 v195, v72, v193, v195
	v_add_f32_e32 v192, v194, v174
	v_add_f32_e32 v193, v195, v190
	v_mul_f32_e32 v194, v73, v193
	v_mul_f32_e32 v195, v73, v192
	v_fma_f32 v194, v72, v192, -v194
	v_fma_f32 v195, v72, v193, v195
	v_add_f32_e32 v192, v194, v175
	v_add_f32_e32 v193, v195, v191
	v_mfma_f32_16x16x32_bf16 v[160:163], v[96:99], v[8:11], 0
	v_mfma_f32_16x16x32_bf16 v[164:167], v[96:99], v[12:15], 0
	v_mfma_f32_16x16x32_bf16 v[168:171], v[96:99], v[16:19], 0
	v_mfma_f32_16x16x32_bf16 v[172:175], v[96:99], v[20:23], 0
	v_mfma_f32_16x16x32_bf16 v[176:179], v[96:99], v[24:27], 0
	v_mfma_f32_16x16x32_bf16 v[180:183], v[96:99], v[28:31], 0
	v_mfma_f32_16x16x32_bf16 v[184:187], v[96:99], v[32:35], 0
	v_mfma_f32_16x16x32_bf16 v[188:191], v[96:99], v[36:39], 0
	s_nop 7
	v_permlane32_swap_b32_e32 v160, v168
	v_permlane32_swap_b32_e32 v161, v169
	v_permlane32_swap_b32_e32 v162, v170
	v_permlane32_swap_b32_e32 v163, v171
	v_permlane32_swap_b32_e32 v164, v172
	v_permlane32_swap_b32_e32 v165, v173
	v_permlane32_swap_b32_e32 v166, v174
	v_permlane32_swap_b32_e32 v167, v175
	v_permlane32_swap_b32_e32 v176, v184
	v_permlane32_swap_b32_e32 v177, v185
	v_permlane32_swap_b32_e32 v178, v186
	v_permlane32_swap_b32_e32 v179, v187
	v_permlane32_swap_b32_e32 v180, v188
	v_permlane32_swap_b32_e32 v181, v189
	v_permlane32_swap_b32_e32 v182, v190
	v_permlane32_swap_b32_e32 v183, v191
	v_permlane16_swap_b32_e32 v160, v164
	v_permlane16_swap_b32_e32 v161, v165
	v_permlane16_swap_b32_e32 v162, v166
	v_permlane16_swap_b32_e32 v163, v167
	v_permlane16_swap_b32_e32 v168, v172
	v_permlane16_swap_b32_e32 v169, v173
	v_permlane16_swap_b32_e32 v170, v174
	v_permlane16_swap_b32_e32 v171, v175
	v_permlane16_swap_b32_e32 v176, v180
	v_permlane16_swap_b32_e32 v177, v181
	v_permlane16_swap_b32_e32 v178, v182
	v_permlane16_swap_b32_e32 v179, v183
	v_permlane16_swap_b32_e32 v184, v188
	v_permlane16_swap_b32_e32 v185, v189
	v_permlane16_swap_b32_e32 v186, v190
	v_permlane16_swap_b32_e32 v187, v191
	v_mul_f32_e32 v194, v73, v193
	v_mul_f32_e32 v195, v73, v192
	v_fma_f32 v194, v72, v192, -v194
	v_fma_f32 v195, v72, v193, v195
	v_add_f32_e32 v192, v194, v160
	v_add_f32_e32 v193, v195, v176
	v_mul_f32_e32 v194, v73, v193
	v_mul_f32_e32 v195, v73, v192
	v_fma_f32 v194, v72, v192, -v194
	v_fma_f32 v195, v72, v193, v195
	v_add_f32_e32 v192, v194, v161
	v_add_f32_e32 v193, v195, v177
	v_mul_f32_e32 v194, v73, v193
	v_mul_f32_e32 v195, v73, v192
	v_fma_f32 v194, v72, v192, -v194
	v_fma_f32 v195, v72, v193, v195
	v_add_f32_e32 v192, v194, v162
	v_add_f32_e32 v193, v195, v178
	v_mul_f32_e32 v194, v73, v193
	v_mul_f32_e32 v195, v73, v192
	v_fma_f32 v194, v72, v192, -v194
	v_fma_f32 v195, v72, v193, v195
	v_add_f32_e32 v192, v194, v163
	v_add_f32_e32 v193, v195, v179
	v_mul_f32_e32 v194, v73, v193
	v_mul_f32_e32 v195, v73, v192
	v_fma_f32 v194, v72, v192, -v194
	v_fma_f32 v195, v72, v193, v195
	v_add_f32_e32 v192, v194, v164
	v_add_f32_e32 v193, v195, v180
	v_mul_f32_e32 v194, v73, v193
	v_mul_f32_e32 v195, v73, v192
	v_fma_f32 v194, v72, v192, -v194
	v_fma_f32 v195, v72, v193, v195
	v_add_f32_e32 v192, v194, v165
	v_add_f32_e32 v193, v195, v181
	v_mul_f32_e32 v194, v73, v193
	v_mul_f32_e32 v195, v73, v192
	v_fma_f32 v194, v72, v192, -v194
	v_fma_f32 v195, v72, v193, v195
	v_add_f32_e32 v192, v194, v166
	v_add_f32_e32 v193, v195, v182
	v_mul_f32_e32 v194, v73, v193
	v_mul_f32_e32 v195, v73, v192
	v_fma_f32 v194, v72, v192, -v194
	v_fma_f32 v195, v72, v193, v195
	v_add_f32_e32 v192, v194, v167
	v_add_f32_e32 v193, v195, v183
	v_mul_f32_e32 v194, v73, v193
	v_mul_f32_e32 v195, v73, v192
	v_fma_f32 v194, v72, v192, -v194
	v_fma_f32 v195, v72, v193, v195
	v_add_f32_e32 v192, v194, v168
	v_add_f32_e32 v193, v195, v184
	v_mul_f32_e32 v194, v73, v193
	v_mul_f32_e32 v195, v73, v192
	v_fma_f32 v194, v72, v192, -v194
	v_fma_f32 v195, v72, v193, v195
	v_add_f32_e32 v192, v194, v169
	v_add_f32_e32 v193, v195, v185
	v_mul_f32_e32 v194, v73, v193
	v_mul_f32_e32 v195, v73, v192
	v_fma_f32 v194, v72, v192, -v194
	v_fma_f32 v195, v72, v193, v195
	v_add_f32_e32 v192, v194, v170
	v_add_f32_e32 v193, v195, v186
	v_mul_f32_e32 v194, v73, v193
	v_mul_f32_e32 v195, v73, v192
	v_fma_f32 v194, v72, v192, -v194
	v_fma_f32 v195, v72, v193, v195
	v_add_f32_e32 v192, v194, v171
	v_add_f32_e32 v193, v195, v187
	v_mul_f32_e32 v194, v73, v193
	v_mul_f32_e32 v195, v73, v192
	v_fma_f32 v194, v72, v192, -v194
	v_fma_f32 v195, v72, v193, v195
	v_add_f32_e32 v192, v194, v172
	v_add_f32_e32 v193, v195, v188
	v_mul_f32_e32 v194, v73, v193
; DI void s5_pass1_item(const Params& P, int bitem, unsigned char* smem) {
;     ...
; #pragma unroll
;     for (int sub = 0; sub < 4; ++sub) {
;         s5_bu16(ubs[sub], af, buf, r, q);
;         asm volatile("s_waitcnt lgkmcnt(0)" ::: "memory");
; #pragma unroll
;         for (int tt = 0; tt < 16; ++tt) { const float bur = buf[lane * 17 + tt], bui = buf[(64 + lane) * 17 + tt];
;             const float nxr = ab[0] * xr - ab[1] * xi + bur, nxi = ab[0] * xi + ab[1] * xr + bui; xr = nxr; xi = nxi; }
;         asm volatile("s_waitcnt lgkmcnt(0)" ::: "memory");
;     }
;     f32x2_t e = {xr, xi};
;     *(f32x2_t*)(ws + WS_S5END + ((size_t)((b * 64 + grp) * 32 + ch) * 64 + lane) * 8) = e;
	v_mul_f32_e32 v195, v73, v192
	v_fma_f32 v194, v72, v192, -v194
	v_fma_f32 v195, v72, v193, v195
	v_add_f32_e32 v192, v194, v173
	v_add_f32_e32 v193, v195, v189
	v_mul_f32_e32 v194, v73, v193
	v_mul_f32_e32 v195, v73, v192
	v_fma_f32 v194, v72, v192, -v194
	v_fma_f32 v195, v72, v193, v195
	v_add_f32_e32 v192, v194, v174
	v_add_f32_e32 v193, v195, v190
	v_mul_f32_e32 v194, v73, v193
	v_mul_f32_e32 v195, v73, v192
	v_fma_f32 v194, v72, v192, -v194
	v_fma_f32 v195, v72, v193, v195
	v_add_f32_e32 v192, v194, v175
	v_add_f32_e32 v193, v195, v191
	v_mfma_f32_16x16x32_bf16 v[160:163], v[100:103], v[8:11], 0
	v_mfma_f32_16x16x32_bf16 v[164:167], v[100:103], v[12:15], 0
	v_mfma_f32_16x16x32_bf16 v[168:171], v[100:103], v[16:19], 0
	v_mfma_f32_16x16x32_bf16 v[172:175], v[100:103], v[20:23], 0
	v_mfma_f32_16x16x32_bf16 v[176:179], v[100:103], v[24:27], 0
	v_mfma_f32_16x16x32_bf16 v[180:183], v[100:103], v[28:31], 0
	v_mfma_f32_16x16x32_bf16 v[184:187], v[100:103], v[32:35], 0
	v_mfma_f32_16x16x32_bf16 v[188:191], v[100:103], v[36:39], 0
	s_nop 7
	v_permlane32_swap_b32_e32 v160, v168
	v_permlane32_swap_b32_e32 v161, v169
	v_permlane32_swap_b32_e32 v162, v170
	v_permlane32_swap_b32_e32 v163, v171
	v_permlane32_swap_b32_e32 v164, v172
	v_permlane32_swap_b32_e32 v165, v173
	v_permlane32_swap_b32_e32 v166, v174
	v_permlane32_swap_b32_e32 v167, v175
	v_permlane32_swap_b32_e32 v176, v184
	v_permlane32_swap_b32_e32 v177, v185
	v_permlane32_swap_b32_e32 v178, v186
	v_permlane32_swap_b32_e32 v179, v187
	v_permlane32_swap_b32_e32 v180, v188
	v_permlane32_swap_b32_e32 v181, v189
	v_permlane32_swap_b32_e32 v182, v190
	v_permlane32_swap_b32_e32 v183, v191
	v_permlane16_swap_b32_e32 v160, v164
	v_permlane16_swap_b32_e32 v161, v165
	v_permlane16_swap_b32_e32 v162, v166
	v_permlane16_swap_b32_e32 v163, v167
	v_permlane16_swap_b32_e32 v168, v172
	v_permlane16_swap_b32_e32 v169, v173
	v_permlane16_swap_b32_e32 v170, v174
	v_permlane16_swap_b32_e32 v171, v175
	v_permlane16_swap_b32_e32 v176, v180
	v_permlane16_swap_b32_e32 v177, v181
	v_permlane16_swap_b32_e32 v178, v182
	v_permlane16_swap_b32_e32 v179, v183
	v_permlane16_swap_b32_e32 v184, v188
	v_permlane16_swap_b32_e32 v185, v189
	v_permlane16_swap_b32_e32 v186, v190
	v_permlane16_swap_b32_e32 v187, v191
	v_mul_f32_e32 v194, v73, v193
	v_mul_f32_e32 v195, v73, v192
	v_fma_f32 v194, v72, v192, -v194
	v_fma_f32 v195, v72, v193, v195
	v_add_f32_e32 v192, v194, v160
	v_add_f32_e32 v193, v195, v176
	v_mul_f32_e32 v194, v73, v193
	v_mul_f32_e32 v195, v73, v192
	v_fma_f32 v194, v72, v192, -v194
	v_fma_f32 v195, v72, v193, v195
	v_add_f32_e32 v192, v194, v161
	v_add_f32_e32 v193, v195, v177
	v_mul_f32_e32 v194, v73, v193
	v_mul_f32_e32 v195, v73, v192
	v_fma_f32 v194, v72, v192, -v194
	v_fma_f32 v195, v72, v193, v195
	v_add_f32_e32 v192, v194, v162
	v_add_f32_e32 v193, v195, v178
	v_mul_f32_e32 v194, v73, v193
	v_mul_f32_e32 v195, v73, v192
	v_fma_f32 v194, v72, v192, -v194
	v_fma_f32 v195, v72, v193, v195
	v_add_f32_e32 v192, v194, v163
	v_add_f32_e32 v193, v195, v179
	v_mul_f32_e32 v194, v73, v193
	v_mul_f32_e32 v195, v73, v192
	v_fma_f32 v194, v72, v192, -v194
	v_fma_f32 v195, v72, v193, v195
	v_add_f32_e32 v192, v194, v164
	v_add_f32_e32 v193, v195, v180
	v_mul_f32_e32 v194, v73, v193
	v_mul_f32_e32 v195, v73, v192
	v_fma_f32 v194, v72, v192, -v194
	v_fma_f32 v195, v72, v193, v195
	v_add_f32_e32 v192, v194, v165
	v_add_f32_e32 v193, v195, v181
	v_mul_f32_e32 v194, v73, v193
	v_mul_f32_e32 v195, v73, v192
	v_fma_f32 v194, v72, v192, -v194
	v_fma_f32 v195, v72, v193, v195
	v_add_f32_e32 v192, v194, v166
	v_add_f32_e32 v193, v195, v182
	v_mul_f32_e32 v194, v73, v193
	v_mul_f32_e32 v195, v73, v192
	v_fma_f32 v194, v72, v192, -v194
	v_fma_f32 v195, v72, v193, v195
	v_add_f32_e32 v192, v194, v167
	v_add_f32_e32 v193, v195, v183
	v_mul_f32_e32 v194, v73, v193
	v_mul_f32_e32 v195, v73, v192
	v_fma_f32 v194, v72, v192, -v194
	v_fma_f32 v195, v72, v193, v195
	v_add_f32_e32 v192, v194, v168
	v_add_f32_e32 v193, v195, v184
	v_mul_f32_e32 v194, v73, v193
	v_mul_f32_e32 v195, v73, v192
	v_fma_f32 v194, v72, v192, -v194
	v_fma_f32 v195, v72, v193, v195
	v_add_f32_e32 v192, v194, v169
	v_add_f32_e32 v193, v195, v185
	v_mul_f32_e32 v194, v73, v193
	v_mul_f32_e32 v195, v73, v192
	v_fma_f32 v194, v72, v192, -v194
	v_fma_f32 v195, v72, v193, v195
	v_add_f32_e32 v192, v194, v170
	v_add_f32_e32 v193, v195, v186
	v_mul_f32_e32 v194, v73, v193
	v_mul_f32_e32 v195, v73, v192
	v_fma_f32 v194, v72, v192, -v194
	v_fma_f32 v195, v72, v193, v195
	v_add_f32_e32 v192, v194, v171
	v_add_f32_e32 v193, v195, v187
	v_mul_f32_e32 v194, v73, v193
	v_mul_f32_e32 v195, v73, v192
	v_fma_f32 v194, v72, v192, -v194
	v_fma_f32 v195, v72, v193, v195
	v_add_f32_e32 v192, v194, v172
	v_add_f32_e32 v193, v195, v188
	v_mul_f32_e32 v194, v73, v193
	v_mul_f32_e32 v195, v73, v192
	v_fma_f32 v194, v72, v192, -v194
	v_fma_f32 v195, v72, v193, v195
	v_add_f32_e32 v192, v194, v173
	v_add_f32_e32 v193, v195, v189
	v_mul_f32_e32 v194, v73, v193
	v_mul_f32_e32 v195, v73, v192
	v_fma_f32 v194, v72, v192, -v194
	v_fma_f32 v195, v72, v193, v195
	v_add_f32_e32 v192, v194, v174
	v_add_f32_e32 v193, v195, v190
	v_mul_f32_e32 v194, v73, v193
	v_mul_f32_e32 v195, v73, v192
	v_fma_f32 v194, v72, v192, -v194
	v_fma_f32 v195, v72, v193, v195
	v_add_f32_e32 v192, v194, v175
	v_add_f32_e32 v193, v195, v191
	global_store_dwordx2 v84, v[192:193], s[30:31]
	s_add_u32 s30, s30, 0x100000
	s_addc_u32 s31, s31, 0
	s_add_i32 s26, s26, 1
	s_cmp_lt_u32 s26, 8
	s_cbranch_scc1 .Ls5p1_round
	s_waitcnt vmcnt(0)
	s_branch .LBB0_654

; DI void s5_pass3_item(const Params& P, int bitem, unsigned char* smem) {
;     int tid_ = threadIdx.x; asm volatile("" : "+v"(tid_));
;     unsigned char* ws = P.ws; const int tid = tid_, wid = tid >> 6, lane = tid & 63, r = lane & 15, q = lane >> 4;
;     const int item = bitem * 8 + wid, ch = item & 31, grp = (item >> 5) & 63, b = item >> 11;
;     const bf16_t* proj = (const bf16_t*)(ws + WS_PROJ); const float* sm = (const float*)(ws + WS_SMALL);
;     float* xs = (float*)smem + wid * 2176;
;     bf16_t* HG = (bf16_t*)(ws + WS_HG);
;     const bf16_t* tb = (const bf16_t*)(sm + SM_BB);
;     bf16x8 af[8];
; #pragma unroll
;     for (int pt = 0; pt < 8; ++pt) af[pt] = *(const bf16x8*)(tb + (grp * 128 + 16 * pt + r) * 32 + 8 * q);
;     const f32x4 ab = *(const f32x4*)(sm + SM_AB + (grp * 64 + lane) * 4);
;     float cB[32];
;     { const float* cre = P.in[21] + (size_t)(grp * 16 + r) * 64; const float* cim = P.in[22] + (size_t)(grp * 16 + r) * 64;
; #pragma unroll
;       for (int i = 0; i < 32; ++i) { const int k = 4 * i + q; cB[i] = (i < 16) ? cre[k] : -cim[k - 64]; } }
;     const float dsk = P.in[23][grp * 16 + r];
;     const bf16_t* ubase = proj + (size_t)(b * TT + ch * 64) * NPROJ + C_SSM + grp * 16;
;     bf16x8 ubs[4]; unsigned short uvs[4][4];
; #pragma unroll
;     for (int sub = 0; sub < 4; ++sub) { ubs[sub] = *(const bf16x8*)(ubase + (size_t)(sub * 16 + r) * NPROJ + 8 * (q & 1));
; #pragma unroll
;         for (int j = 0; j < 4; ++j) uvs[sub][j] = ubase[(size_t)(sub * 16 + 4 * q + j) * NPROJ + r]; }
;     float xr = 0.f, xi = 0.f;
;     {
;       const f32x2_t* e = (const f32x2_t*)(ws + WS_S5END) + (size_t)((b * 64 + grp) * 32) * 64 + lane;
;       f32x2_t ev[31];
; #pragma unroll
;       for (int j = 0; j < 31; ++j) ev[j] = e[(j < ch ? j : 0) * 64];
; #pragma unroll
;       for (int j = 0; j < 31; ++j) { const float ex = j < ch ? ev[j][0] : 0.f, ey = j < ch ? ev[j][1] : 0.f;
;           const float ncr = ab[2] * xr - ab[3] * xi + ex, nci = ab[2] * xi + ab[3] * xr + ey; xr = j < ch ? ncr : xr; xi = j < ch ? nci : xi; } }
.Ls5n_start:
	v_lshrrev_b32_e32 v1, 6, v206
	v_and_b32_e32 v2, 63, v206
	v_readfirstlane_b32 s16, v1
	v_and_b32_e32 v3, 15, v206
	v_bfe_u32 v4, v206, 4, 2
	s_lshr_b32 s17, s88, 2
	s_and_b32 s18, s88, 3
	s_lshl_b32 s18, s18, 3
	s_add_i32 s18, s18, s16
	v_mov_b32_e32 v205, 0
	s_mul_i32 s0, s16, 0x2200
	s_mov_b32 m0, s0
	v_mul_u32_u24_e32 v5, 0x210, v3
	v_lshl_add_u32 v5, v4, 4, v5
	v_add_u32_e32 v77, s0, v5
	v_lshlrev_b32_e32 v5, 2, v1
	v_add_u32_e32 v78, 0x19000, v5
	v_and_b32_e32 v5, 7, v2
	v_lshlrev_b32_e32 v5, 2, v5
	v_add_u32_e32 v79, 0x19000, v5
	v_lshlrev_b32_e32 v5, 3, v206
	v_add_u32_e32 v81, 0x11000, v5
	v_add_u32_e32 v199, 0x1000, v5
	v_add_u32_e32 v204, 0x3000, v5
	v_lshlrev_b32_e32 v5, 3, v2
	v_add_u32_e32 v82, 0x11000, v5
	v_and_b32_e32 v5, 1, v4
	v_lshlrev_b32_e32 v5, 4, v5
	s_movk_i32 s1, 0x1e00
	v_mad_u32_u24 v83, v3, s1, v5
	v_lshlrev_b32_e32 v5, 2, v4
	v_lshlrev_b32_e32 v6, 1, v3
	v_mad_u32_u24 v84, v5, s1, v6
	v_add_u32_e32 v85, 0x1e00, v84
	v_add_u32_e32 v86, 0x3c00, v84
	v_add_u32_e32 v87, 0x5a00, v84
	v_lshlrev_b32_e32 v7, 13, v4
	v_add_u32_e32 v7, v7, v6
	v_add_u32_e32 v198, 0x1000, v7
	s_lshl_b32 s2, s17, 13
	s_add_u32 s0, s74, 0x9f20400
	s_addc_u32 s1, s75, 0
	s_add_u32 s0, s0, s2
	s_addc_u32 s1, s1, 0
	s_add_u32 s2, s0, 0x1000
	s_addc_u32 s3, s1, 0
	v_lshlrev_b32_e32 v5, 6, v3
	v_lshl_add_u32 v5, v4, 4, v5
	global_load_dwordx4 v[8:11], v5, s[0:1] offset:0
	global_load_dwordx4 v[12:15], v5, s[0:1] offset:1024
	global_load_dwordx4 v[16:19], v5, s[0:1] offset:2048
	global_load_dwordx4 v[20:23], v5, s[0:1] offset:3072
	global_load_dwordx4 v[24:27], v5, s[2:3] offset:0
	global_load_dwordx4 v[28:31], v5, s[2:3] offset:1024
	global_load_dwordx4 v[32:35], v5, s[2:3] offset:2048
	global_load_dwordx4 v[36:39], v5, s[2:3] offset:3072
	s_lshl_b32 s6, s17, 10
	s_add_u32 s4, s74, 0x9f10400
	s_addc_u32 s5, s75, 0
	s_add_u32 s4, s4, s6
	s_addc_u32 s5, s5, 0
	v_lshlrev_b32_e32 v6, 4, v2
	global_load_dwordx4 v[72:75], v6, s[4:5]
	s_lshl_b32 s6, s17, 12
	s_add_u32 s8, s62, s6
	s_addc_u32 s9, s63, 0
	s_add_u32 s10, s64, s6
	s_addc_u32 s11, s65, 0
	v_lshlrev_b32_e32 v7, 8, v3
	v_lshl_add_u32 v7, v4, 4, v7
	global_load_dword v40, v7, s[8:9] offset:0
	global_load_dword v41, v7, s[8:9] offset:4
	global_load_dword v42, v7, s[8:9] offset:8
	global_load_dword v43, v7, s[8:9] offset:12
	global_load_dword v44, v7, s[8:9] offset:64
	global_load_dword v45, v7, s[8:9] offset:68
	global_load_dword v46, v7, s[8:9] offset:72
	global_load_dword v47, v7, s[8:9] offset:76
	global_load_dword v48, v7, s[8:9] offset:128
	global_load_dword v49, v7, s[8:9] offset:132
	global_load_dword v50, v7, s[8:9] offset:136
	global_load_dword v51, v7, s[8:9] offset:140
	global_load_dword v52, v7, s[8:9] offset:192
	global_load_dword v53, v7, s[8:9] offset:196
	global_load_dword v54, v7, s[8:9] offset:200
	global_load_dword v55, v7, s[8:9] offset:204
	global_load_dword v56, v7, s[10:11] offset:0
	global_load_dword v57, v7, s[10:11] offset:4
	global_load_dword v58, v7, s[10:11] offset:8
	global_load_dword v59, v7, s[10:11] offset:12
	global_load_dword v60, v7, s[10:11] offset:64
	global_load_dword v61, v7, s[10:11] offset:68
	global_load_dword v62, v7, s[10:11] offset:72
	global_load_dword v63, v7, s[10:11] offset:76
	global_load_dword v64, v7, s[10:11] offset:128
	global_load_dword v65, v7, s[10:11] offset:132
	global_load_dword v66, v7, s[10:11] offset:136
	global_load_dword v67, v7, s[10:11] offset:140
	global_load_dword v68, v7, s[10:11] offset:192
	global_load_dword v69, v7, s[10:11] offset:196
	global_load_dword v70, v7, s[10:11] offset:200
	global_load_dword v71, v7, s[10:11] offset:204
	s_lshl_b32 s6, s17, 6
	s_add_u32 s12, s66, s6
	s_addc_u32 s13, s67, 0
	v_lshlrev_b32_e32 v6, 2, v3
	global_load_dword v76, v6, s[12:13]
	s_mul_i32 s0, s18, 0x78000
	s_lshl_b32 s1, s17, 5
	s_add_i32 s0, s0, s1
	s_add_i32 s0, s0, 0xf911430
	s_add_u32 s22, s74, s0
	s_addc_u32 s23, s75, 0
	s_lshl_b32 s0, s17, 14
	s_add_i32 s0, s0, 0xa110000
	s_add_u32 s24, s74, s0
	s_addc_u32 s25, s75, 0
	s_lshl_b32 s0, s18, 17
	s_lshl_b32 s1, s17, 5
	s_add_i32 s0, s0, s1
	s_add_i32 s0, s0, 0xb910000
	s_add_u32 s26, s74, s0
	s_addc_u32 s27, s75, 0
	s_add_u32 s40, s22, 0x0
	s_addc_u32 s41, s23, 0
	s_add_u32 s42, s22, 0x1e000
	s_addc_u32 s43, s23, 0
	s_add_u32 s44, s22, 0x3c000
	s_addc_u32 s45, s23, 0
	s_add_u32 s46, s22, 0x5a000
	s_addc_u32 s47, s23, 0
	global_load_dwordx4 v[120:123], v83, s[40:41]
	global_load_dwordx4 v[124:127], v83, s[42:43]
	global_load_dwordx4 v[128:131], v83, s[44:45]
	global_load_dwordx4 v[132:135], v83, s[46:47]
	global_load_ushort v136, v84, s[40:41]
	global_load_ushort v137, v85, s[40:41]
	global_load_ushort v138, v86, s[40:41]
	global_load_ushort v139, v87, s[40:41]
	global_load_ushort v140, v84, s[42:43]
	global_load_ushort v141, v85, s[42:43]
	global_load_ushort v142, v86, s[42:43]
	global_load_ushort v143, v87, s[42:43]
	global_load_ushort v144, v84, s[44:45]
	global_load_ushort v145, v85, s[44:45]
	global_load_ushort v146, v86, s[44:45]
	global_load_ushort v147, v87, s[44:45]
	global_load_ushort v148, v84, s[46:47]
	global_load_ushort v149, v85, s[46:47]
	global_load_ushort v150, v86, s[46:47]
	global_load_ushort v151, v87, s[46:47]
	global_load_dwordx2 v[152:153], v199, s[24:25] offset:-4096
	global_load_dwordx2 v[154:155], v199, s[24:25]
	global_load_dwordx2 v[156:157], v204, s[24:25] offset:-4096
	global_load_dwordx2 v[158:159], v204, s[24:25]
	s_mov_b32 s19, 0
	s_mov_b32 s20, 0
	s_waitcnt vmcnt(0)
	v_xor_b32_e32 v56, 0x80000000, v56
	v_xor_b32_e32 v57, 0x80000000, v57
	v_xor_b32_e32 v58, 0x80000000, v58
	v_xor_b32_e32 v59, 0x80000000, v59
	v_xor_b32_e32 v60, 0x80000000, v60
	v_xor_b32_e32 v61, 0x80000000, v61
	v_xor_b32_e32 v62, 0x80000000, v62
	v_xor_b32_e32 v63, 0x80000000, v63
	v_xor_b32_e32 v64, 0x80000000, v64
	v_xor_b32_e32 v65, 0x80000000, v65
	v_xor_b32_e32 v66, 0x80000000, v66
	v_xor_b32_e32 v67, 0x80000000, v67
	v_xor_b32_e32 v68, 0x80000000, v68
	v_xor_b32_e32 v69, 0x80000000, v69
	v_xor_b32_e32 v70, 0x80000000, v70
	v_xor_b32_e32 v71, 0x80000000, v71
	ds_write_b64 v81, v[152:153] offset:0
	ds_write_b64 v81, v[154:155] offset:4096
	ds_write_b64 v81, v[156:157] offset:8192
	ds_write_b64 v81, v[158:159] offset:12288
	v_mov_b32_e32 v1, 1
	s_waitcnt lgkmcnt(0)
	ds_write_b32 v78, v1
	s_waitcnt lgkmcnt(0)
	s_barrier
	s_lshr_b32 s0, s16, 2
	s_lshl_b32 s0, s0, 2
	s_and_b32 s1, s16, 3
	s_add_i32 s0, s0, s1
	s_cmp_eq_u32 s0, 0
	s_cbranch_scc1 .Ls5n_nostag
; DI float bf2f(unsigned x) { return __uint_as_float(x << 16); }
; DI void s5_pass3_item(const Params& P, int bitem, unsigned char* smem) {
;     ...
;     {
;       const f32x2_t* e = (const f32x2_t*)(ws + WS_S5END) + (size_t)((b * 64 + grp) * 32) * 64 + lane;
;       f32x2_t ev[31];
; #pragma unroll
;       for (int j = 0; j < 31; ++j) ev[j] = e[(j < ch ? j : 0) * 64];
; #pragma unroll
;       for (int j = 0; j < 31; ++j) { const float ex = j < ch ? ev[j][0] : 0.f, ey = j < ch ? ev[j][1] : 0.f;
;           const float ncr = ab[2] * xr - ab[3] * xi + ex, nci = ab[2] * xi + ab[3] * xr + ey; xr = j < ch ? ncr : xr; xi = j < ch ? nci : xi; } }
; #pragma unroll
;     for (int sub = 0; sub < 4; ++sub) {
;         s5_bu16(ubs[sub], af, xs, r, q);
;         float uv[4];
; #pragma unroll
;         for (int j = 0; j < 4; ++j) uv[j] = bf2f(uvs[sub][j]);
;         asm volatile("s_waitcnt lgkmcnt(0)" ::: "memory");
; #pragma unroll
;         for (int tt = 0; tt < 16; ++tt) { const float bur = xs[lane * 17 + tt], bui = xs[(64 + lane) * 17 + tt];
;             const float nxr = ab[0] * xr - ab[1] * xi + bur, nxi = ab[0] * xi + ab[1] * xr + bui; xr = nxr; xi = nxi;
;             xs[lane * 17 + tt] = xr; xs[(64 + lane) * 17 + tt] = xi; }
.Ls5n_stagloop:
	s_sleep 40
	s_sub_u32 s0, s0, 1
	s_cmp_lg_u32 s0, 0
	s_cbranch_scc1 .Ls5n_stagloop
.Ls5n_nostag:
.Ls5n_round:
	s_waitcnt vmcnt(16)
	v_mov_b32_e32 v88, v120
	v_mov_b32_e32 v89, v121
	v_mov_b32_e32 v90, v122
	v_mov_b32_e32 v91, v123
	v_mov_b32_e32 v92, v124
	v_mov_b32_e32 v93, v125
	v_mov_b32_e32 v94, v126
	v_mov_b32_e32 v95, v127
	v_mov_b32_e32 v96, v128
	v_mov_b32_e32 v97, v129
	v_mov_b32_e32 v98, v130
	v_mov_b32_e32 v99, v131
	v_mov_b32_e32 v100, v132
	v_mov_b32_e32 v101, v133
	v_mov_b32_e32 v102, v134
	v_mov_b32_e32 v103, v135
	v_lshlrev_b32_e32 v104, 16, v136
	v_lshlrev_b32_e32 v105, 16, v137
	v_lshlrev_b32_e32 v106, 16, v138
	v_lshlrev_b32_e32 v107, 16, v139
	v_lshlrev_b32_e32 v108, 16, v140
	v_lshlrev_b32_e32 v109, 16, v141
	v_lshlrev_b32_e32 v110, 16, v142
	v_lshlrev_b32_e32 v111, 16, v143
	v_lshlrev_b32_e32 v112, 16, v144
	v_lshlrev_b32_e32 v113, 16, v145
	v_lshlrev_b32_e32 v114, 16, v146
	v_lshlrev_b32_e32 v115, 16, v147
	v_lshlrev_b32_e32 v116, 16, v148
	v_lshlrev_b32_e32 v117, 16, v149
	v_lshlrev_b32_e32 v118, 16, v150
	v_lshlrev_b32_e32 v119, 16, v151
	v_mov_b32_e32 v2, s19
.Ls5n_spin:
	ds_read_b32 v1, v79
	s_waitcnt lgkmcnt(0)
	v_cmp_le_u32_e32 vcc, v1, v2
	s_cbranch_vccz .Ls5n_spun
	s_sleep 1
	s_branch .Ls5n_spin

; DI float bf2f(unsigned x) { return __uint_as_float(x << 16); }
; DI void s5_pass3_item(const Params& P, int bitem, unsigned char* smem) {
;     ...
;     for (int sub = 0; sub < 4; ++sub) {
;         s5_bu16(ubs[sub], af, xs, r, q);
;         float uv[4];
; #pragma unroll
;         for (int j = 0; j < 4; ++j) uv[j] = bf2f(uvs[sub][j]);
;         asm volatile("s_waitcnt lgkmcnt(0)" ::: "memory");
; #pragma unroll
;         for (int tt = 0; tt < 16; ++tt) { const float bur = xs[lane * 17 + tt], bui = xs[(64 + lane) * 17 + tt];
;             const float nxr = ab[0] * xr - ab[1] * xi + bur, nxi = ab[0] * xi + ab[1] * xr + bui; xr = nxr; xi = nxi;
;             xs[lane * 17 + tt] = xr; xs[(64 + lane) * 17 + tt] = xi; }
;         asm volatile("s_waitcnt lgkmcnt(0)" ::: "memory");
;         f32x4 ya[4];
; #pragma unroll
;         for (int j = 0; j < 4; ++j) ya[j] = (f32x4){0.f, 0.f, 0.f, 0.f};
; #pragma unroll
;         for (int i = 0; i < 32; ++i) { const float a = xs[(4 * i + q) * 17 + r]; ya[i & 3] = __builtin_amdgcn_mfma_f32_16x16x4f32(a, cB[i], ya[i & 3], 0, 0, 0); }
.Ls5n_cdone:
	s_waitcnt lgkmcnt(0)
	s_mov_b64 s[28:29], s[26:27]
	v_mfma_f32_16x16x32_bf16 v[160:163], v[88:91], v[8:11], 0
	v_mfma_f32_16x16x32_bf16 v[164:167], v[88:91], v[12:15], 0
	v_mfma_f32_16x16x32_bf16 v[168:171], v[88:91], v[16:19], 0
	v_mfma_f32_16x16x32_bf16 v[172:175], v[88:91], v[20:23], 0
	v_mfma_f32_16x16x32_bf16 v[176:179], v[88:91], v[24:27], 0
	v_mfma_f32_16x16x32_bf16 v[180:183], v[88:91], v[28:31], 0
	v_mfma_f32_16x16x32_bf16 v[184:187], v[88:91], v[32:35], 0
	v_mfma_f32_16x16x32_bf16 v[188:191], v[88:91], v[36:39], 0
	s_nop 7
	v_permlane32_swap_b32_e32 v160, v168
	v_permlane32_swap_b32_e32 v161, v169
	v_permlane32_swap_b32_e32 v162, v170
	v_permlane32_swap_b32_e32 v163, v171
	v_permlane32_swap_b32_e32 v164, v172
	v_permlane32_swap_b32_e32 v165, v173
	v_permlane32_swap_b32_e32 v166, v174
	v_permlane32_swap_b32_e32 v167, v175
	v_permlane32_swap_b32_e32 v176, v184
	v_permlane32_swap_b32_e32 v177, v185
	v_permlane32_swap_b32_e32 v178, v186
	v_permlane32_swap_b32_e32 v179, v187
	v_permlane32_swap_b32_e32 v180, v188
	v_permlane32_swap_b32_e32 v181, v189
	v_permlane32_swap_b32_e32 v182, v190
	v_permlane32_swap_b32_e32 v183, v191
	v_permlane16_swap_b32_e32 v160, v164
	v_permlane16_swap_b32_e32 v161, v165
	v_permlane16_swap_b32_e32 v162, v166
	v_permlane16_swap_b32_e32 v163, v167
	v_permlane16_swap_b32_e32 v168, v172
	v_permlane16_swap_b32_e32 v169, v173
	v_permlane16_swap_b32_e32 v170, v174
	v_permlane16_swap_b32_e32 v171, v175
	v_permlane16_swap_b32_e32 v176, v180
	v_permlane16_swap_b32_e32 v177, v181
	v_permlane16_swap_b32_e32 v178, v182
	v_permlane16_swap_b32_e32 v179, v183
	v_permlane16_swap_b32_e32 v184, v188
	v_permlane16_swap_b32_e32 v185, v189
	v_permlane16_swap_b32_e32 v186, v190
	v_permlane16_swap_b32_e32 v187, v191
	v_mul_f32_e32 v194, v73, v193
	v_mul_f32_e32 v195, v73, v192
	v_fma_f32 v194, v72, v192, -v194
	v_fma_f32 v195, v72, v193, v195
	v_add_f32_e32 v160, v194, v160
	v_add_f32_e32 v176, v195, v176
	ds_write_addtid_b32 v160 offset:0
	ds_write_addtid_b32 v176 offset:256
	v_mul_f32_e32 v194, v73, v176
	v_mul_f32_e32 v195, v73, v160
	v_fma_f32 v194, v72, v160, -v194
	v_fma_f32 v195, v72, v176, v195
	v_add_f32_e32 v161, v194, v161
	v_add_f32_e32 v177, v195, v177
	ds_write_addtid_b32 v161 offset:528
	ds_write_addtid_b32 v177 offset:784
	v_mul_f32_e32 v194, v73, v177
	v_mul_f32_e32 v195, v73, v161
	v_fma_f32 v194, v72, v161, -v194
	v_fma_f32 v195, v72, v177, v195
	v_add_f32_e32 v162, v194, v162
	v_add_f32_e32 v178, v195, v178
	ds_write_addtid_b32 v162 offset:1056
	ds_write_addtid_b32 v178 offset:1312
	v_mul_f32_e32 v194, v73, v178
	v_mul_f32_e32 v195, v73, v162
	v_fma_f32 v194, v72, v162, -v194
	v_fma_f32 v195, v72, v178, v195
	v_add_f32_e32 v163, v194, v163
	v_add_f32_e32 v179, v195, v179
	ds_write_addtid_b32 v163 offset:1584
	ds_write_addtid_b32 v179 offset:1840
	v_mul_f32_e32 v194, v73, v179
	v_mul_f32_e32 v195, v73, v163
	v_fma_f32 v194, v72, v163, -v194
	v_fma_f32 v195, v72, v179, v195
	v_add_f32_e32 v164, v194, v164
	v_add_f32_e32 v180, v195, v180
	ds_write_addtid_b32 v164 offset:2112
	ds_write_addtid_b32 v180 offset:2368
	v_mul_f32_e32 v194, v73, v180
	v_mul_f32_e32 v195, v73, v164
	v_fma_f32 v194, v72, v164, -v194
	v_fma_f32 v195, v72, v180, v195
	v_add_f32_e32 v165, v194, v165
	v_add_f32_e32 v181, v195, v181
	ds_write_addtid_b32 v165 offset:2640
	ds_write_addtid_b32 v181 offset:2896
	v_mul_f32_e32 v194, v73, v181
	v_mul_f32_e32 v195, v73, v165
	v_fma_f32 v194, v72, v165, -v194
	v_fma_f32 v195, v72, v181, v195
	v_add_f32_e32 v166, v194, v166
	v_add_f32_e32 v182, v195, v182
	ds_write_addtid_b32 v166 offset:3168
	ds_write_addtid_b32 v182 offset:3424
	v_mul_f32_e32 v194, v73, v182
	v_mul_f32_e32 v195, v73, v166
	v_fma_f32 v194, v72, v166, -v194
	v_fma_f32 v195, v72, v182, v195
	v_add_f32_e32 v167, v194, v167
	v_add_f32_e32 v183, v195, v183
	ds_write_addtid_b32 v167 offset:3696
	ds_write_addtid_b32 v183 offset:3952
	v_mul_f32_e32 v194, v73, v183
	v_mul_f32_e32 v195, v73, v167
	v_fma_f32 v194, v72, v167, -v194
	v_fma_f32 v195, v72, v183, v195
	v_add_f32_e32 v168, v194, v168
	v_add_f32_e32 v184, v195, v184
	ds_write_addtid_b32 v168 offset:4224
	ds_write_addtid_b32 v184 offset:4480
	v_mul_f32_e32 v194, v73, v184
	v_mul_f32_e32 v195, v73, v168
	v_fma_f32 v194, v72, v168, -v194
	v_fma_f32 v195, v72, v184, v195
	v_add_f32_e32 v169, v194, v169
	v_add_f32_e32 v185, v195, v185
	ds_write_addtid_b32 v169 offset:4752
	ds_write_addtid_b32 v185 offset:5008
	v_mul_f32_e32 v194, v73, v185
	v_mul_f32_e32 v195, v73, v169
	v_fma_f32 v194, v72, v169, -v194
	v_fma_f32 v195, v72, v185, v195
	v_add_f32_e32 v170, v194, v170
	v_add_f32_e32 v186, v195, v186
	ds_write_addtid_b32 v170 offset:5280
	ds_write_addtid_b32 v186 offset:5536
	v_mul_f32_e32 v194, v73, v186
	v_mul_f32_e32 v195, v73, v170
	v_fma_f32 v194, v72, v170, -v194
	v_fma_f32 v195, v72, v186, v195
	v_add_f32_e32 v171, v194, v171
	v_add_f32_e32 v187, v195, v187
	ds_write_addtid_b32 v171 offset:5808
	ds_write_addtid_b32 v187 offset:6064
	v_mul_f32_e32 v194, v73, v187
	v_mul_f32_e32 v195, v73, v171
	v_fma_f32 v194, v72, v171, -v194
	v_fma_f32 v195, v72, v187, v195
	v_add_f32_e32 v172, v194, v172
	v_add_f32_e32 v188, v195, v188
	ds_write_addtid_b32 v172 offset:6336
	ds_write_addtid_b32 v188 offset:6592
	v_mul_f32_e32 v194, v73, v188
	v_mul_f32_e32 v195, v73, v172
	v_fma_f32 v194, v72, v172, -v194
	v_fma_f32 v195, v72, v188, v195
	v_add_f32_e32 v173, v194, v173
	v_add_f32_e32 v189, v195, v189
	ds_write_addtid_b32 v173 offset:6864
	ds_write_addtid_b32 v189 offset:7120
	v_mul_f32_e32 v194, v73, v189
	v_mul_f32_e32 v195, v73, v173
	v_fma_f32 v194, v72, v173, -v194
	v_fma_f32 v195, v72, v189, v195
	v_add_f32_e32 v174, v194, v174
	v_add_f32_e32 v190, v195, v190
	ds_write_addtid_b32 v174 offset:7392
	ds_write_addtid_b32 v190 offset:7648
	v_mul_f32_e32 v194, v73, v190
	v_mul_f32_e32 v195, v73, v174
	v_fma_f32 v194, v72, v174, -v194
	v_fma_f32 v195, v72, v190, v195
	v_add_f32_e32 v175, v194, v175
	v_add_f32_e32 v191, v195, v191
	ds_write_addtid_b32 v175 offset:7920
	ds_write_addtid_b32 v191 offset:8176
	v_mov_b32_e32 v192, v175
	v_mov_b32_e32 v193, v191
	ds_read_b128 v[208:211], v77 offset:0
	ds_read_b128 v[212:215], v77 offset:64
	ds_read_b128 v[216:219], v77 offset:128
	ds_read_b128 v[220:223], v77 offset:192
	ds_read_b128 v[224:227], v77 offset:256
	ds_read_b128 v[228:231], v77 offset:320
	ds_read_b128 v[232:235], v77 offset:384
	ds_read_b128 v[236:239], v77 offset:448
	s_waitcnt lgkmcnt(7)
; DI unsigned pk2(float a, float b) { f32x2_t v = {a, b}; return __builtin_bit_cast(unsigned, __builtin_convertvector(v, bf16x2_t)); }
; DI float bf2f(unsigned x) { return __uint_as_float(x << 16); }
; DI float gelu_tanh(float v) { const float z = 0.7978845608028654f * (v + 0.044715f * v * v * v); const float th = 1.0f - 2.0f * __builtin_amdgcn_rcpf(__builtin_amdgcn_exp2f(2.8853900817779268f * z) + 1.0f); return 0.5f * v * (1.0f + th); }
; DI void s5_pass3_item(const Params& P, int bitem, unsigned char* smem) {
;     ...
;     for (int sub = 0; sub < 4; ++sub) {
;         s5_bu16(ubs[sub], af, xs, r, q);
;         float uv[4];
; #pragma unroll
;         for (int j = 0; j < 4; ++j) uv[j] = bf2f(uvs[sub][j]);
;         asm volatile("s_waitcnt lgkmcnt(0)" ::: "memory");
; #pragma unroll
;         for (int tt = 0; tt < 16; ++tt) { const float bur = xs[lane * 17 + tt], bui = xs[(64 + lane) * 17 + tt];
;             const float nxr = ab[0] * xr - ab[1] * xi + bur, nxi = ab[0] * xi + ab[1] * xr + bui; xr = nxr; xi = nxi;
;             xs[lane * 17 + tt] = xr; xs[(64 + lane) * 17 + tt] = xi; }
;         asm volatile("s_waitcnt lgkmcnt(0)" ::: "memory");
;         f32x4 ya[4];
; #pragma unroll
;         for (int j = 0; j < 4; ++j) ya[j] = (f32x4){0.f, 0.f, 0.f, 0.f};
; #pragma unroll
;         for (int i = 0; i < 32; ++i) { const float a = xs[(4 * i + q) * 17 + r]; ya[i & 3] = __builtin_amdgcn_mfma_f32_16x16x4f32(a, cB[i], ya[i & 3], 0, 0, 0); }
;         const f32x4 y = (ya[0] + ya[1]) + (ya[2] + ya[3]);
; #pragma unroll
;         for (int j = 0; j < 4; ++j) { const int tl = sub * 16 + 4 * q + j; const float v = y[j] + dsk * uv[j];
;             HG[(size_t)(b * TT + ch * 64 + tl) * 1024 + grp * 16 + r] = (bf16_t)(pk2(gelu_tanh(v), 0.f) & 0xffffu); }
	v_mfma_f32_16x16x4_f32 v[200:203], v208, v40, 0
	s_waitcnt lgkmcnt(7)
	v_mfma_f32_16x16x4_f32 v[240:243], v209, v41, 0
	s_waitcnt lgkmcnt(7)
	v_mfma_f32_16x16x4_f32 v[200:203], v210, v42, v[200:203]
	s_waitcnt lgkmcnt(7)
	v_mfma_f32_16x16x4_f32 v[240:243], v211, v43, v[240:243]
	s_waitcnt lgkmcnt(6)
	v_mfma_f32_16x16x4_f32 v[200:203], v212, v44, v[200:203]
	s_waitcnt lgkmcnt(6)
	v_mfma_f32_16x16x4_f32 v[240:243], v213, v45, v[240:243]
	s_waitcnt lgkmcnt(6)
	v_mfma_f32_16x16x4_f32 v[200:203], v214, v46, v[200:203]
	s_waitcnt lgkmcnt(6)
	v_mfma_f32_16x16x4_f32 v[240:243], v215, v47, v[240:243]
	s_waitcnt lgkmcnt(5)
	v_mfma_f32_16x16x4_f32 v[200:203], v216, v48, v[200:203]
	s_waitcnt lgkmcnt(5)
	v_mfma_f32_16x16x4_f32 v[240:243], v217, v49, v[240:243]
	s_waitcnt lgkmcnt(5)
	v_mfma_f32_16x16x4_f32 v[200:203], v218, v50, v[200:203]
	s_waitcnt lgkmcnt(5)
	v_mfma_f32_16x16x4_f32 v[240:243], v219, v51, v[240:243]
	s_waitcnt lgkmcnt(4)
	v_mfma_f32_16x16x4_f32 v[200:203], v220, v52, v[200:203]
	s_waitcnt lgkmcnt(4)
	v_mfma_f32_16x16x4_f32 v[240:243], v221, v53, v[240:243]
	s_waitcnt lgkmcnt(4)
	v_mfma_f32_16x16x4_f32 v[200:203], v222, v54, v[200:203]
	s_waitcnt lgkmcnt(4)
	v_mfma_f32_16x16x4_f32 v[240:243], v223, v55, v[240:243]
	s_waitcnt lgkmcnt(3)
	v_mfma_f32_16x16x4_f32 v[200:203], v224, v56, v[200:203]
	s_waitcnt lgkmcnt(3)
	v_mfma_f32_16x16x4_f32 v[240:243], v225, v57, v[240:243]
	s_waitcnt lgkmcnt(3)
	v_mfma_f32_16x16x4_f32 v[200:203], v226, v58, v[200:203]
	s_waitcnt lgkmcnt(3)
	v_mfma_f32_16x16x4_f32 v[240:243], v227, v59, v[240:243]
	s_waitcnt lgkmcnt(2)
	v_mfma_f32_16x16x4_f32 v[200:203], v228, v60, v[200:203]
	s_waitcnt lgkmcnt(2)
	v_mfma_f32_16x16x4_f32 v[240:243], v229, v61, v[240:243]
	s_waitcnt lgkmcnt(2)
	v_mfma_f32_16x16x4_f32 v[200:203], v230, v62, v[200:203]
	s_waitcnt lgkmcnt(2)
	v_mfma_f32_16x16x4_f32 v[240:243], v231, v63, v[240:243]
	s_waitcnt lgkmcnt(1)
	v_mfma_f32_16x16x4_f32 v[200:203], v232, v64, v[200:203]
	s_waitcnt lgkmcnt(1)
	v_mfma_f32_16x16x4_f32 v[240:243], v233, v65, v[240:243]
	s_waitcnt lgkmcnt(1)
	v_mfma_f32_16x16x4_f32 v[200:203], v234, v66, v[200:203]
	s_waitcnt lgkmcnt(1)
	v_mfma_f32_16x16x4_f32 v[240:243], v235, v67, v[240:243]
	s_waitcnt lgkmcnt(0)
	v_mfma_f32_16x16x4_f32 v[200:203], v236, v68, v[200:203]
	s_waitcnt lgkmcnt(0)
	v_mfma_f32_16x16x4_f32 v[240:243], v237, v69, v[240:243]
	s_waitcnt lgkmcnt(0)
	v_mfma_f32_16x16x4_f32 v[200:203], v238, v70, v[200:203]
	s_waitcnt lgkmcnt(0)
	v_mfma_f32_16x16x4_f32 v[240:243], v239, v71, v[240:243]
	s_nop 9
	v_add_f32_e32 v1, v200, v240
	v_add_f32_e32 v2, v201, v241
	v_add_f32_e32 v3, v202, v242
	v_add_f32_e32 v4, v203, v243
	v_fmac_f32_e32 v1, v76, v104
	v_fmac_f32_e32 v2, v76, v105
	v_fmac_f32_e32 v3, v76, v106
	v_fmac_f32_e32 v4, v76, v107
	v_mul_f32_e32 v5, 0x3d372713, v1
	v_mul_f32_e32 v6, 0x3d372713, v2
	v_mul_f32_e32 v7, 0x3d372713, v3
	v_mul_f32_e32 v246, 0x3d372713, v4
	v_mul_f32_e32 v5, v1, v5
	v_mul_f32_e32 v6, v2, v6
	v_mul_f32_e32 v7, v3, v7
	v_mul_f32_e32 v246, v4, v246
	v_mul_f32_e32 v194, 0.5, v1
	v_mul_f32_e32 v195, 0.5, v2
	v_mul_f32_e32 v196, 0.5, v3
	v_mul_f32_e32 v197, 0.5, v4
	v_fma_f32 v1, v1, v5, v1
	v_fma_f32 v2, v2, v6, v2
	v_fma_f32 v3, v3, v7, v3
	v_fma_f32 v4, v4, v246, v4
	v_mul_f32_e32 v1, 0x3f4c422a, v1
	v_mul_f32_e32 v2, 0x3f4c422a, v2
	v_mul_f32_e32 v3, 0x3f4c422a, v3
	v_mul_f32_e32 v4, 0x3f4c422a, v4
	v_mul_f32_e32 v1, 0x4038aa3b, v1
	v_mul_f32_e32 v2, 0x4038aa3b, v2
	v_mul_f32_e32 v3, 0x4038aa3b, v3
	v_mul_f32_e32 v4, 0x4038aa3b, v4
	v_exp_f32_e32 v1, v1
	v_exp_f32_e32 v2, v2
	v_exp_f32_e32 v3, v3
	v_exp_f32_e32 v4, v4
	v_add_f32_e32 v1, 1.0, v1
	v_add_f32_e32 v2, 1.0, v2
	v_add_f32_e32 v3, 1.0, v3
	v_add_f32_e32 v4, 1.0, v4
	v_rcp_f32_e32 v1, v1
	v_rcp_f32_e32 v2, v2
	v_rcp_f32_e32 v3, v3
	v_rcp_f32_e32 v4, v4
	v_fma_f32 v1, v1, -2.0, 1.0
	v_fma_f32 v2, v2, -2.0, 1.0
	v_fma_f32 v3, v3, -2.0, 1.0
	v_fma_f32 v4, v4, -2.0, 1.0
	v_add_f32_e32 v1, 1.0, v1
	v_add_f32_e32 v2, 1.0, v2
	v_add_f32_e32 v3, 1.0, v3
	v_add_f32_e32 v4, 1.0, v4
	v_mul_f32_e32 v1, v194, v1
	v_mul_f32_e32 v2, v195, v2
	v_mul_f32_e32 v3, v196, v3
	v_mul_f32_e32 v4, v197, v4
	v_cvt_pk_bf16_f32 v1, v1, v1
	v_cvt_pk_bf16_f32 v2, v2, v2
	v_cvt_pk_bf16_f32 v3, v3, v3
	v_cvt_pk_bf16_f32 v4, v4, v4
	global_store_short v198, v1, s[28:29] offset:-4096
	global_store_short v198, v2, s[28:29] offset:-2048
	global_store_short v198, v3, s[28:29] offset:0
	global_store_short v198, v4, s[28:29] offset:2048
	s_add_u32 s28, s28, 0x8000
	s_addc_u32 s29, s29, 0
	v_mfma_f32_16x16x32_bf16 v[160:163], v[92:95], v[8:11], 0
	v_mfma_f32_16x16x32_bf16 v[164:167], v[92:95], v[12:15], 0
	v_mfma_f32_16x16x32_bf16 v[168:171], v[92:95], v[16:19], 0
	v_mfma_f32_16x16x32_bf16 v[172:175], v[92:95], v[20:23], 0
	v_mfma_f32_16x16x32_bf16 v[176:179], v[92:95], v[24:27], 0
	v_mfma_f32_16x16x32_bf16 v[180:183], v[92:95], v[28:31], 0
	v_mfma_f32_16x16x32_bf16 v[184:187], v[92:95], v[32:35], 0
	v_mfma_f32_16x16x32_bf16 v[188:191], v[92:95], v[36:39], 0
	s_nop 7
	v_permlane32_swap_b32_e32 v160, v168
	v_permlane32_swap_b32_e32 v161, v169
	v_permlane32_swap_b32_e32 v162, v170
	v_permlane32_swap_b32_e32 v163, v171
	v_permlane32_swap_b32_e32 v164, v172
	v_permlane32_swap_b32_e32 v165, v173
	v_permlane32_swap_b32_e32 v166, v174
	v_permlane32_swap_b32_e32 v167, v175
	v_permlane32_swap_b32_e32 v176, v184
	v_permlane32_swap_b32_e32 v177, v185
	v_permlane32_swap_b32_e32 v178, v186
	v_permlane32_swap_b32_e32 v179, v187
	v_permlane32_swap_b32_e32 v180, v188
	v_permlane32_swap_b32_e32 v181, v189
	v_permlane32_swap_b32_e32 v182, v190
	v_permlane32_swap_b32_e32 v183, v191
	v_permlane16_swap_b32_e32 v160, v164
; DI float bf2f(unsigned x) { return __uint_as_float(x << 16); }
; DI void s5_pass3_item(const Params& P, int bitem, unsigned char* smem) {
;     ...
;     for (int sub = 0; sub < 4; ++sub) {
;         s5_bu16(ubs[sub], af, xs, r, q);
;         float uv[4];
; #pragma unroll
;         for (int j = 0; j < 4; ++j) uv[j] = bf2f(uvs[sub][j]);
;         asm volatile("s_waitcnt lgkmcnt(0)" ::: "memory");
; #pragma unroll
;         for (int tt = 0; tt < 16; ++tt) { const float bur = xs[lane * 17 + tt], bui = xs[(64 + lane) * 17 + tt];
;             const float nxr = ab[0] * xr - ab[1] * xi + bur, nxi = ab[0] * xi + ab[1] * xr + bui; xr = nxr; xi = nxi;
;             xs[lane * 17 + tt] = xr; xs[(64 + lane) * 17 + tt] = xi; }
;         asm volatile("s_waitcnt lgkmcnt(0)" ::: "memory");
;         f32x4 ya[4];
; #pragma unroll
;         for (int j = 0; j < 4; ++j) ya[j] = (f32x4){0.f, 0.f, 0.f, 0.f};
; #pragma unroll
;         for (int i = 0; i < 32; ++i) { const float a = xs[(4 * i + q) * 17 + r]; ya[i & 3] = __builtin_amdgcn_mfma_f32_16x16x4f32(a, cB[i], ya[i & 3], 0, 0, 0); }
	v_permlane16_swap_b32_e32 v161, v165
	v_permlane16_swap_b32_e32 v162, v166
	v_permlane16_swap_b32_e32 v163, v167
	v_permlane16_swap_b32_e32 v168, v172
	v_permlane16_swap_b32_e32 v169, v173
	v_permlane16_swap_b32_e32 v170, v174
	v_permlane16_swap_b32_e32 v171, v175
	v_permlane16_swap_b32_e32 v176, v180
	v_permlane16_swap_b32_e32 v177, v181
	v_permlane16_swap_b32_e32 v178, v182
	v_permlane16_swap_b32_e32 v179, v183
	v_permlane16_swap_b32_e32 v184, v188
	v_permlane16_swap_b32_e32 v185, v189
	v_permlane16_swap_b32_e32 v186, v190
	v_permlane16_swap_b32_e32 v187, v191
	v_mul_f32_e32 v194, v73, v193
	v_mul_f32_e32 v195, v73, v192
	v_fma_f32 v194, v72, v192, -v194
	v_fma_f32 v195, v72, v193, v195
	v_add_f32_e32 v160, v194, v160
	v_add_f32_e32 v176, v195, v176
	ds_write_addtid_b32 v160 offset:0
	ds_write_addtid_b32 v176 offset:256
	v_mul_f32_e32 v194, v73, v176
	v_mul_f32_e32 v195, v73, v160
	v_fma_f32 v194, v72, v160, -v194
	v_fma_f32 v195, v72, v176, v195
	v_add_f32_e32 v161, v194, v161
	v_add_f32_e32 v177, v195, v177
	ds_write_addtid_b32 v161 offset:528
	ds_write_addtid_b32 v177 offset:784
	v_mul_f32_e32 v194, v73, v177
	v_mul_f32_e32 v195, v73, v161
	v_fma_f32 v194, v72, v161, -v194
	v_fma_f32 v195, v72, v177, v195
	v_add_f32_e32 v162, v194, v162
	v_add_f32_e32 v178, v195, v178
	ds_write_addtid_b32 v162 offset:1056
	ds_write_addtid_b32 v178 offset:1312
	v_mul_f32_e32 v194, v73, v178
	v_mul_f32_e32 v195, v73, v162
	v_fma_f32 v194, v72, v162, -v194
	v_fma_f32 v195, v72, v178, v195
	v_add_f32_e32 v163, v194, v163
	v_add_f32_e32 v179, v195, v179
	ds_write_addtid_b32 v163 offset:1584
	ds_write_addtid_b32 v179 offset:1840
	v_mul_f32_e32 v194, v73, v179
	v_mul_f32_e32 v195, v73, v163
	v_fma_f32 v194, v72, v163, -v194
	v_fma_f32 v195, v72, v179, v195
	v_add_f32_e32 v164, v194, v164
	v_add_f32_e32 v180, v195, v180
	ds_write_addtid_b32 v164 offset:2112
	ds_write_addtid_b32 v180 offset:2368
	v_mul_f32_e32 v194, v73, v180
	v_mul_f32_e32 v195, v73, v164
	v_fma_f32 v194, v72, v164, -v194
	v_fma_f32 v195, v72, v180, v195
	v_add_f32_e32 v165, v194, v165
	v_add_f32_e32 v181, v195, v181
	ds_write_addtid_b32 v165 offset:2640
	ds_write_addtid_b32 v181 offset:2896
	v_mul_f32_e32 v194, v73, v181
	v_mul_f32_e32 v195, v73, v165
	v_fma_f32 v194, v72, v165, -v194
	v_fma_f32 v195, v72, v181, v195
	v_add_f32_e32 v166, v194, v166
	v_add_f32_e32 v182, v195, v182
	ds_write_addtid_b32 v166 offset:3168
	ds_write_addtid_b32 v182 offset:3424
	v_mul_f32_e32 v194, v73, v182
	v_mul_f32_e32 v195, v73, v166
	v_fma_f32 v194, v72, v166, -v194
	v_fma_f32 v195, v72, v182, v195
	v_add_f32_e32 v167, v194, v167
	v_add_f32_e32 v183, v195, v183
	ds_write_addtid_b32 v167 offset:3696
	ds_write_addtid_b32 v183 offset:3952
	v_mul_f32_e32 v194, v73, v183
	v_mul_f32_e32 v195, v73, v167
	v_fma_f32 v194, v72, v167, -v194
	v_fma_f32 v195, v72, v183, v195
	v_add_f32_e32 v168, v194, v168
	v_add_f32_e32 v184, v195, v184
	ds_write_addtid_b32 v168 offset:4224
	ds_write_addtid_b32 v184 offset:4480
	v_mul_f32_e32 v194, v73, v184
	v_mul_f32_e32 v195, v73, v168
	v_fma_f32 v194, v72, v168, -v194
	v_fma_f32 v195, v72, v184, v195
	v_add_f32_e32 v169, v194, v169
	v_add_f32_e32 v185, v195, v185
	ds_write_addtid_b32 v169 offset:4752
	ds_write_addtid_b32 v185 offset:5008
	v_mul_f32_e32 v194, v73, v185
	v_mul_f32_e32 v195, v73, v169
	v_fma_f32 v194, v72, v169, -v194
	v_fma_f32 v195, v72, v185, v195
	v_add_f32_e32 v170, v194, v170
	v_add_f32_e32 v186, v195, v186
	ds_write_addtid_b32 v170 offset:5280
	ds_write_addtid_b32 v186 offset:5536
	v_mul_f32_e32 v194, v73, v186
	v_mul_f32_e32 v195, v73, v170
	v_fma_f32 v194, v72, v170, -v194
	v_fma_f32 v195, v72, v186, v195
	v_add_f32_e32 v171, v194, v171
	v_add_f32_e32 v187, v195, v187
	ds_write_addtid_b32 v171 offset:5808
	ds_write_addtid_b32 v187 offset:6064
	v_mul_f32_e32 v194, v73, v187
	v_mul_f32_e32 v195, v73, v171
	v_fma_f32 v194, v72, v171, -v194
	v_fma_f32 v195, v72, v187, v195
	v_add_f32_e32 v172, v194, v172
	v_add_f32_e32 v188, v195, v188
	ds_write_addtid_b32 v172 offset:6336
	ds_write_addtid_b32 v188 offset:6592
	v_mul_f32_e32 v194, v73, v188
	v_mul_f32_e32 v195, v73, v172
	v_fma_f32 v194, v72, v172, -v194
	v_fma_f32 v195, v72, v188, v195
	v_add_f32_e32 v173, v194, v173
	v_add_f32_e32 v189, v195, v189
	ds_write_addtid_b32 v173 offset:6864
	ds_write_addtid_b32 v189 offset:7120
	v_mul_f32_e32 v194, v73, v189
	v_mul_f32_e32 v195, v73, v173
	v_fma_f32 v194, v72, v173, -v194
	v_fma_f32 v195, v72, v189, v195
	v_add_f32_e32 v174, v194, v174
	v_add_f32_e32 v190, v195, v190
	ds_write_addtid_b32 v174 offset:7392
	ds_write_addtid_b32 v190 offset:7648
	v_mul_f32_e32 v194, v73, v190
	v_mul_f32_e32 v195, v73, v174
	v_fma_f32 v194, v72, v174, -v194
	v_fma_f32 v195, v72, v190, v195
	v_add_f32_e32 v175, v194, v175
	v_add_f32_e32 v191, v195, v191
	ds_write_addtid_b32 v175 offset:7920
	ds_write_addtid_b32 v191 offset:8176
	v_mov_b32_e32 v192, v175
	v_mov_b32_e32 v193, v191
	ds_read_b128 v[208:211], v77 offset:0
	ds_read_b128 v[212:215], v77 offset:64
	ds_read_b128 v[216:219], v77 offset:128
	ds_read_b128 v[220:223], v77 offset:192
	ds_read_b128 v[224:227], v77 offset:256
	ds_read_b128 v[228:231], v77 offset:320
	ds_read_b128 v[232:235], v77 offset:384
	ds_read_b128 v[236:239], v77 offset:448
	s_waitcnt lgkmcnt(7)
	v_mfma_f32_16x16x4_f32 v[200:203], v208, v40, 0
	s_waitcnt lgkmcnt(7)
	v_mfma_f32_16x16x4_f32 v[240:243], v209, v41, 0
	s_waitcnt lgkmcnt(7)
	v_mfma_f32_16x16x4_f32 v[200:203], v210, v42, v[200:203]
	s_waitcnt lgkmcnt(7)
	v_mfma_f32_16x16x4_f32 v[240:243], v211, v43, v[240:243]
	s_waitcnt lgkmcnt(6)
	v_mfma_f32_16x16x4_f32 v[200:203], v212, v44, v[200:203]
	s_waitcnt lgkmcnt(6)
; DI unsigned pk2(float a, float b) { f32x2_t v = {a, b}; return __builtin_bit_cast(unsigned, __builtin_convertvector(v, bf16x2_t)); }
; DI float gelu_tanh(float v) { const float z = 0.7978845608028654f * (v + 0.044715f * v * v * v); const float th = 1.0f - 2.0f * __builtin_amdgcn_rcpf(__builtin_amdgcn_exp2f(2.8853900817779268f * z) + 1.0f); return 0.5f * v * (1.0f + th); }
; DI void s5_pass3_item(const Params& P, int bitem, unsigned char* smem) {
;     ...
;     {
;       const f32x2_t* e = (const f32x2_t*)(ws + WS_S5END) + (size_t)((b * 64 + grp) * 32) * 64 + lane;
;       f32x2_t ev[31];
; #pragma unroll
;       for (int j = 0; j < 31; ++j) ev[j] = e[(j < ch ? j : 0) * 64];
; #pragma unroll
;       for (int j = 0; j < 31; ++j) { const float ex = j < ch ? ev[j][0] : 0.f, ey = j < ch ? ev[j][1] : 0.f;
;           const float ncr = ab[2] * xr - ab[3] * xi + ex, nci = ab[2] * xi + ab[3] * xr + ey; xr = j < ch ? ncr : xr; xi = j < ch ? nci : xi; } }
;     ...
;         f32x4 ya[4];
; #pragma unroll
;         for (int j = 0; j < 4; ++j) ya[j] = (f32x4){0.f, 0.f, 0.f, 0.f};
; #pragma unroll
;         for (int i = 0; i < 32; ++i) { const float a = xs[(4 * i + q) * 17 + r]; ya[i & 3] = __builtin_amdgcn_mfma_f32_16x16x4f32(a, cB[i], ya[i & 3], 0, 0, 0); }
;         const f32x4 y = (ya[0] + ya[1]) + (ya[2] + ya[3]);
; #pragma unroll
;         for (int j = 0; j < 4; ++j) { const int tl = sub * 16 + 4 * q + j; const float v = y[j] + dsk * uv[j];
;             HG[(size_t)(b * TT + ch * 64 + tl) * 1024 + grp * 16 + r] = (bf16_t)(pk2(gelu_tanh(v), 0.f) & 0xffffu); }
;         asm volatile("s_waitcnt lgkmcnt(0)" ::: "memory");
	v_mfma_f32_16x16x4_f32 v[240:243], v213, v45, v[240:243]
	s_waitcnt lgkmcnt(6)
	v_mfma_f32_16x16x4_f32 v[200:203], v214, v46, v[200:203]
	s_waitcnt lgkmcnt(6)
	v_mfma_f32_16x16x4_f32 v[240:243], v215, v47, v[240:243]
	s_waitcnt lgkmcnt(5)
	v_mfma_f32_16x16x4_f32 v[200:203], v216, v48, v[200:203]
	s_waitcnt lgkmcnt(5)
	v_mfma_f32_16x16x4_f32 v[240:243], v217, v49, v[240:243]
	s_waitcnt lgkmcnt(5)
	v_mfma_f32_16x16x4_f32 v[200:203], v218, v50, v[200:203]
	s_waitcnt lgkmcnt(5)
	v_mfma_f32_16x16x4_f32 v[240:243], v219, v51, v[240:243]
	s_waitcnt lgkmcnt(4)
	v_mfma_f32_16x16x4_f32 v[200:203], v220, v52, v[200:203]
	s_waitcnt lgkmcnt(4)
	v_mfma_f32_16x16x4_f32 v[240:243], v221, v53, v[240:243]
	s_waitcnt lgkmcnt(4)
	v_mfma_f32_16x16x4_f32 v[200:203], v222, v54, v[200:203]
	s_waitcnt lgkmcnt(4)
	v_mfma_f32_16x16x4_f32 v[240:243], v223, v55, v[240:243]
	s_waitcnt lgkmcnt(3)
	v_mfma_f32_16x16x4_f32 v[200:203], v224, v56, v[200:203]
	s_waitcnt lgkmcnt(3)
	v_mfma_f32_16x16x4_f32 v[240:243], v225, v57, v[240:243]
	s_waitcnt lgkmcnt(3)
	v_mfma_f32_16x16x4_f32 v[200:203], v226, v58, v[200:203]
	s_waitcnt lgkmcnt(3)
	v_mfma_f32_16x16x4_f32 v[240:243], v227, v59, v[240:243]
	s_waitcnt lgkmcnt(2)
	v_mfma_f32_16x16x4_f32 v[200:203], v228, v60, v[200:203]
	s_waitcnt lgkmcnt(2)
	v_mfma_f32_16x16x4_f32 v[240:243], v229, v61, v[240:243]
	s_waitcnt lgkmcnt(2)
	v_mfma_f32_16x16x4_f32 v[200:203], v230, v62, v[200:203]
	s_waitcnt lgkmcnt(2)
	v_mfma_f32_16x16x4_f32 v[240:243], v231, v63, v[240:243]
	s_waitcnt lgkmcnt(1)
	v_mfma_f32_16x16x4_f32 v[200:203], v232, v64, v[200:203]
	s_waitcnt lgkmcnt(1)
	v_mfma_f32_16x16x4_f32 v[240:243], v233, v65, v[240:243]
	s_waitcnt lgkmcnt(1)
	v_mfma_f32_16x16x4_f32 v[200:203], v234, v66, v[200:203]
	s_waitcnt lgkmcnt(1)
	v_mfma_f32_16x16x4_f32 v[240:243], v235, v67, v[240:243]
	s_waitcnt lgkmcnt(0)
	v_mfma_f32_16x16x4_f32 v[200:203], v236, v68, v[200:203]
	s_waitcnt lgkmcnt(0)
	v_mfma_f32_16x16x4_f32 v[240:243], v237, v69, v[240:243]
	s_waitcnt lgkmcnt(0)
	v_mfma_f32_16x16x4_f32 v[200:203], v238, v70, v[200:203]
	s_waitcnt lgkmcnt(0)
	v_mfma_f32_16x16x4_f32 v[240:243], v239, v71, v[240:243]
	s_nop 9
	v_add_f32_e32 v1, v200, v240
	v_add_f32_e32 v2, v201, v241
	v_add_f32_e32 v3, v202, v242
	v_add_f32_e32 v4, v203, v243
	v_fmac_f32_e32 v1, v76, v108
	v_fmac_f32_e32 v2, v76, v109
	v_fmac_f32_e32 v3, v76, v110
	v_fmac_f32_e32 v4, v76, v111
	v_mul_f32_e32 v5, 0x3d372713, v1
	v_mul_f32_e32 v6, 0x3d372713, v2
	v_mul_f32_e32 v7, 0x3d372713, v3
	v_mul_f32_e32 v246, 0x3d372713, v4
	v_mul_f32_e32 v5, v1, v5
	v_mul_f32_e32 v6, v2, v6
	v_mul_f32_e32 v7, v3, v7
	v_mul_f32_e32 v246, v4, v246
	v_mul_f32_e32 v194, 0.5, v1
	v_mul_f32_e32 v195, 0.5, v2
	v_mul_f32_e32 v196, 0.5, v3
	v_mul_f32_e32 v197, 0.5, v4
	v_fma_f32 v1, v1, v5, v1
	v_fma_f32 v2, v2, v6, v2
	v_fma_f32 v3, v3, v7, v3
	v_fma_f32 v4, v4, v246, v4
	v_mul_f32_e32 v1, 0x3f4c422a, v1
	v_mul_f32_e32 v2, 0x3f4c422a, v2
	v_mul_f32_e32 v3, 0x3f4c422a, v3
	v_mul_f32_e32 v4, 0x3f4c422a, v4
	v_mul_f32_e32 v1, 0x4038aa3b, v1
	v_mul_f32_e32 v2, 0x4038aa3b, v2
	v_mul_f32_e32 v3, 0x4038aa3b, v3
	v_mul_f32_e32 v4, 0x4038aa3b, v4
	v_exp_f32_e32 v1, v1
	v_exp_f32_e32 v2, v2
	v_exp_f32_e32 v3, v3
	v_exp_f32_e32 v4, v4
	v_add_f32_e32 v1, 1.0, v1
	v_add_f32_e32 v2, 1.0, v2
	v_add_f32_e32 v3, 1.0, v3
	v_add_f32_e32 v4, 1.0, v4
	v_rcp_f32_e32 v1, v1
	v_rcp_f32_e32 v2, v2
	v_rcp_f32_e32 v3, v3
	v_rcp_f32_e32 v4, v4
	v_fma_f32 v1, v1, -2.0, 1.0
	v_fma_f32 v2, v2, -2.0, 1.0
	v_fma_f32 v3, v3, -2.0, 1.0
	v_fma_f32 v4, v4, -2.0, 1.0
	v_add_f32_e32 v1, 1.0, v1
	v_add_f32_e32 v2, 1.0, v2
	v_add_f32_e32 v3, 1.0, v3
	v_add_f32_e32 v4, 1.0, v4
	v_mul_f32_e32 v1, v194, v1
	v_mul_f32_e32 v2, v195, v2
	v_mul_f32_e32 v3, v196, v3
	v_mul_f32_e32 v4, v197, v4
	v_cvt_pk_bf16_f32 v1, v1, v1
	v_cvt_pk_bf16_f32 v2, v2, v2
	v_cvt_pk_bf16_f32 v3, v3, v3
	v_cvt_pk_bf16_f32 v4, v4, v4
	global_store_short v198, v1, s[28:29] offset:-4096
	global_store_short v198, v2, s[28:29] offset:-2048
	global_store_short v198, v3, s[28:29] offset:0
	global_store_short v198, v4, s[28:29] offset:2048
	s_add_u32 s28, s28, 0x8000
	s_addc_u32 s29, s29, 0
	s_cmp_eq_u32 s19, 7
	s_cbranch_scc1 .Ls5n_nostage
	s_waitcnt vmcnt(8)
	s_xor_b32 s0, s20, 0x4000
	v_add_u32_e32 v1, s0, v81
	ds_write_b64 v1, v[152:153] offset:0
	ds_write_b64 v1, v[154:155] offset:4096
	ds_write_b64 v1, v[156:157] offset:8192
	ds_write_b64 v1, v[158:159] offset:12288
	s_add_i32 s0, s19, 2
	v_mov_b32_e32 v2, s0
	s_waitcnt lgkmcnt(0)
	ds_write_b32 v78, v2
; DI float bf2f(unsigned x) { return __uint_as_float(x << 16); }
; DI void s5_bu16(const bf16x8 ub, const bf16x8 (&af)[8], float* buf, int r, int q) {
; #pragma unroll
;     for (int pt = 0; pt < 8; ++pt) { f32x4 d = {0.f, 0.f, 0.f, 0.f}; d = __builtin_amdgcn_mfma_f32_16x16x32_bf16(af[pt], ub, d, 0, 0, 0);
; #pragma unroll
;         for (int j = 0; j < 4; ++j) buf[(16 * pt + 4 * q + j) * 17 + r] = d[j]; }
; }
; DI void s5_pass3_item(const Params& P, int bitem, unsigned char* smem) {
;     ...
;     for (int sub = 0; sub < 4; ++sub) {
;         s5_bu16(ubs[sub], af, xs, r, q);
;         float uv[4];
; #pragma unroll
;         for (int j = 0; j < 4; ++j) uv[j] = bf2f(uvs[sub][j]);
;         asm volatile("s_waitcnt lgkmcnt(0)" ::: "memory");
; #pragma unroll
;         for (int tt = 0; tt < 16; ++tt) { const float bur = xs[lane * 17 + tt], bui = xs[(64 + lane) * 17 + tt];
;             const float nxr = ab[0] * xr - ab[1] * xi + bur, nxi = ab[0] * xi + ab[1] * xr + bui; xr = nxr; xi = nxi;
;             xs[lane * 17 + tt] = xr; xs[(64 + lane) * 17 + tt] = xi; }
.Ls5n_nostage:
	v_mfma_f32_16x16x32_bf16 v[160:163], v[96:99], v[8:11], 0
	v_mfma_f32_16x16x32_bf16 v[164:167], v[96:99], v[12:15], 0
	v_mfma_f32_16x16x32_bf16 v[168:171], v[96:99], v[16:19], 0
	v_mfma_f32_16x16x32_bf16 v[172:175], v[96:99], v[20:23], 0
	v_mfma_f32_16x16x32_bf16 v[176:179], v[96:99], v[24:27], 0
	v_mfma_f32_16x16x32_bf16 v[180:183], v[96:99], v[28:31], 0
	v_mfma_f32_16x16x32_bf16 v[184:187], v[96:99], v[32:35], 0
	v_mfma_f32_16x16x32_bf16 v[188:191], v[96:99], v[36:39], 0
	s_nop 7
	v_permlane32_swap_b32_e32 v160, v168
	v_permlane32_swap_b32_e32 v161, v169
	v_permlane32_swap_b32_e32 v162, v170
	v_permlane32_swap_b32_e32 v163, v171
	v_permlane32_swap_b32_e32 v164, v172
	v_permlane32_swap_b32_e32 v165, v173
	v_permlane32_swap_b32_e32 v166, v174
	v_permlane32_swap_b32_e32 v167, v175
	v_permlane32_swap_b32_e32 v176, v184
	v_permlane32_swap_b32_e32 v177, v185
	v_permlane32_swap_b32_e32 v178, v186
	v_permlane32_swap_b32_e32 v179, v187
	v_permlane32_swap_b32_e32 v180, v188
	v_permlane32_swap_b32_e32 v181, v189
	v_permlane32_swap_b32_e32 v182, v190
	v_permlane32_swap_b32_e32 v183, v191
	v_permlane16_swap_b32_e32 v160, v164
	v_permlane16_swap_b32_e32 v161, v165
	v_permlane16_swap_b32_e32 v162, v166
	v_permlane16_swap_b32_e32 v163, v167
	v_permlane16_swap_b32_e32 v168, v172
	v_permlane16_swap_b32_e32 v169, v173
	v_permlane16_swap_b32_e32 v170, v174
	v_permlane16_swap_b32_e32 v171, v175
	v_permlane16_swap_b32_e32 v176, v180
	v_permlane16_swap_b32_e32 v177, v181
	v_permlane16_swap_b32_e32 v178, v182
	v_permlane16_swap_b32_e32 v179, v183
	v_permlane16_swap_b32_e32 v184, v188
	v_permlane16_swap_b32_e32 v185, v189
	v_permlane16_swap_b32_e32 v186, v190
	v_permlane16_swap_b32_e32 v187, v191
	v_mul_f32_e32 v194, v73, v193
	v_mul_f32_e32 v195, v73, v192
	v_fma_f32 v194, v72, v192, -v194
	v_fma_f32 v195, v72, v193, v195
	v_add_f32_e32 v160, v194, v160
	v_add_f32_e32 v176, v195, v176
	ds_write_addtid_b32 v160 offset:0
	ds_write_addtid_b32 v176 offset:256
	v_mul_f32_e32 v194, v73, v176
	v_mul_f32_e32 v195, v73, v160
	v_fma_f32 v194, v72, v160, -v194
	v_fma_f32 v195, v72, v176, v195
	v_add_f32_e32 v161, v194, v161
	v_add_f32_e32 v177, v195, v177
	ds_write_addtid_b32 v161 offset:528
	ds_write_addtid_b32 v177 offset:784
	v_mul_f32_e32 v194, v73, v177
	v_mul_f32_e32 v195, v73, v161
	v_fma_f32 v194, v72, v161, -v194
	v_fma_f32 v195, v72, v177, v195
	v_add_f32_e32 v162, v194, v162
	v_add_f32_e32 v178, v195, v178
	ds_write_addtid_b32 v162 offset:1056
	ds_write_addtid_b32 v178 offset:1312
	v_mul_f32_e32 v194, v73, v178
	v_mul_f32_e32 v195, v73, v162
	v_fma_f32 v194, v72, v162, -v194
	v_fma_f32 v195, v72, v178, v195
	v_add_f32_e32 v163, v194, v163
	v_add_f32_e32 v179, v195, v179
	ds_write_addtid_b32 v163 offset:1584
	ds_write_addtid_b32 v179 offset:1840
	v_mul_f32_e32 v194, v73, v179
	v_mul_f32_e32 v195, v73, v163
	v_fma_f32 v194, v72, v163, -v194
	v_fma_f32 v195, v72, v179, v195
	v_add_f32_e32 v164, v194, v164
	v_add_f32_e32 v180, v195, v180
	ds_write_addtid_b32 v164 offset:2112
	ds_write_addtid_b32 v180 offset:2368
	v_mul_f32_e32 v194, v73, v180
	v_mul_f32_e32 v195, v73, v164
	v_fma_f32 v194, v72, v164, -v194
	v_fma_f32 v195, v72, v180, v195
	v_add_f32_e32 v165, v194, v165
	v_add_f32_e32 v181, v195, v181
	ds_write_addtid_b32 v165 offset:2640
	ds_write_addtid_b32 v181 offset:2896
	v_mul_f32_e32 v194, v73, v181
	v_mul_f32_e32 v195, v73, v165
	v_fma_f32 v194, v72, v165, -v194
	v_fma_f32 v195, v72, v181, v195
	v_add_f32_e32 v166, v194, v166
	v_add_f32_e32 v182, v195, v182
	ds_write_addtid_b32 v166 offset:3168
	ds_write_addtid_b32 v182 offset:3424
	v_mul_f32_e32 v194, v73, v182
	v_mul_f32_e32 v195, v73, v166
	v_fma_f32 v194, v72, v166, -v194
	v_fma_f32 v195, v72, v182, v195
	v_add_f32_e32 v167, v194, v167
	v_add_f32_e32 v183, v195, v183
	ds_write_addtid_b32 v167 offset:3696
	ds_write_addtid_b32 v183 offset:3952
	v_mul_f32_e32 v194, v73, v183
	v_mul_f32_e32 v195, v73, v167
	v_fma_f32 v194, v72, v167, -v194
	v_fma_f32 v195, v72, v183, v195
	v_add_f32_e32 v168, v194, v168
	v_add_f32_e32 v184, v195, v184
	ds_write_addtid_b32 v168 offset:4224
	ds_write_addtid_b32 v184 offset:4480
	v_mul_f32_e32 v194, v73, v184
	v_mul_f32_e32 v195, v73, v168
	v_fma_f32 v194, v72, v168, -v194
	v_fma_f32 v195, v72, v184, v195
	v_add_f32_e32 v169, v194, v169
	v_add_f32_e32 v185, v195, v185
	ds_write_addtid_b32 v169 offset:4752
	ds_write_addtid_b32 v185 offset:5008
	v_mul_f32_e32 v194, v73, v185
	v_mul_f32_e32 v195, v73, v169
	v_fma_f32 v194, v72, v169, -v194
	v_fma_f32 v195, v72, v185, v195
	v_add_f32_e32 v170, v194, v170
	v_add_f32_e32 v186, v195, v186
	ds_write_addtid_b32 v170 offset:5280
	ds_write_addtid_b32 v186 offset:5536
	v_mul_f32_e32 v194, v73, v186
	v_mul_f32_e32 v195, v73, v170
	v_fma_f32 v194, v72, v170, -v194
	v_fma_f32 v195, v72, v186, v195
	v_add_f32_e32 v171, v194, v171
	v_add_f32_e32 v187, v195, v187
	ds_write_addtid_b32 v171 offset:5808
	ds_write_addtid_b32 v187 offset:6064
	v_mul_f32_e32 v194, v73, v187
	v_mul_f32_e32 v195, v73, v171
	v_fma_f32 v194, v72, v171, -v194
	v_fma_f32 v195, v72, v187, v195
	v_add_f32_e32 v172, v194, v172
	v_add_f32_e32 v188, v195, v188
	ds_write_addtid_b32 v172 offset:6336
	ds_write_addtid_b32 v188 offset:6592
	v_mul_f32_e32 v194, v73, v188
	v_mul_f32_e32 v195, v73, v172
	v_fma_f32 v194, v72, v172, -v194
	v_fma_f32 v195, v72, v188, v195
	v_add_f32_e32 v173, v194, v173
	v_add_f32_e32 v189, v195, v189
	ds_write_addtid_b32 v173 offset:6864
	ds_write_addtid_b32 v189 offset:7120
	v_mul_f32_e32 v194, v73, v189
	v_mul_f32_e32 v195, v73, v173
	v_fma_f32 v194, v72, v173, -v194
	v_fma_f32 v195, v72, v189, v195
	v_add_f32_e32 v174, v194, v174
	v_add_f32_e32 v190, v195, v190
	ds_write_addtid_b32 v174 offset:7392
	ds_write_addtid_b32 v190 offset:7648
	v_mul_f32_e32 v194, v73, v190
	v_mul_f32_e32 v195, v73, v174
	v_fma_f32 v194, v72, v174, -v194
	v_fma_f32 v195, v72, v190, v195
	v_add_f32_e32 v175, v194, v175
	v_add_f32_e32 v191, v195, v191
	ds_write_addtid_b32 v175 offset:7920
	ds_write_addtid_b32 v191 offset:8176
	v_mov_b32_e32 v192, v175
	v_mov_b32_e32 v193, v191
	ds_read_b128 v[208:211], v77 offset:0
	ds_read_b128 v[212:215], v77 offset:64
	ds_read_b128 v[216:219], v77 offset:128
	ds_read_b128 v[220:223], v77 offset:192
	ds_read_b128 v[224:227], v77 offset:256
	ds_read_b128 v[228:231], v77 offset:320
	ds_read_b128 v[232:235], v77 offset:384
	ds_read_b128 v[236:239], v77 offset:448
	s_waitcnt lgkmcnt(7)
; DI unsigned pk2(float a, float b) { f32x2_t v = {a, b}; return __builtin_bit_cast(unsigned, __builtin_convertvector(v, bf16x2_t)); }
; DI float bf2f(unsigned x) { return __uint_as_float(x << 16); }
; DI float gelu_tanh(float v) { const float z = 0.7978845608028654f * (v + 0.044715f * v * v * v); const float th = 1.0f - 2.0f * __builtin_amdgcn_rcpf(__builtin_amdgcn_exp2f(2.8853900817779268f * z) + 1.0f); return 0.5f * v * (1.0f + th); }
; DI void s5_pass3_item(const Params& P, int bitem, unsigned char* smem) {
;     ...
;     for (int sub = 0; sub < 4; ++sub) {
;         s5_bu16(ubs[sub], af, xs, r, q);
;         float uv[4];
; #pragma unroll
;         for (int j = 0; j < 4; ++j) uv[j] = bf2f(uvs[sub][j]);
;         asm volatile("s_waitcnt lgkmcnt(0)" ::: "memory");
; #pragma unroll
;         for (int tt = 0; tt < 16; ++tt) { const float bur = xs[lane * 17 + tt], bui = xs[(64 + lane) * 17 + tt];
;             const float nxr = ab[0] * xr - ab[1] * xi + bur, nxi = ab[0] * xi + ab[1] * xr + bui; xr = nxr; xi = nxi;
;             xs[lane * 17 + tt] = xr; xs[(64 + lane) * 17 + tt] = xi; }
;         asm volatile("s_waitcnt lgkmcnt(0)" ::: "memory");
;         f32x4 ya[4];
; #pragma unroll
;         for (int j = 0; j < 4; ++j) ya[j] = (f32x4){0.f, 0.f, 0.f, 0.f};
; #pragma unroll
;         for (int i = 0; i < 32; ++i) { const float a = xs[(4 * i + q) * 17 + r]; ya[i & 3] = __builtin_amdgcn_mfma_f32_16x16x4f32(a, cB[i], ya[i & 3], 0, 0, 0); }
;         const f32x4 y = (ya[0] + ya[1]) + (ya[2] + ya[3]);
; #pragma unroll
;         for (int j = 0; j < 4; ++j) { const int tl = sub * 16 + 4 * q + j; const float v = y[j] + dsk * uv[j];
;             HG[(size_t)(b * TT + ch * 64 + tl) * 1024 + grp * 16 + r] = (bf16_t)(pk2(gelu_tanh(v), 0.f) & 0xffffu); }
	v_mfma_f32_16x16x4_f32 v[200:203], v208, v40, 0
	s_waitcnt lgkmcnt(7)
	v_mfma_f32_16x16x4_f32 v[240:243], v209, v41, 0
	s_waitcnt lgkmcnt(7)
	v_mfma_f32_16x16x4_f32 v[200:203], v210, v42, v[200:203]
	s_waitcnt lgkmcnt(7)
	v_mfma_f32_16x16x4_f32 v[240:243], v211, v43, v[240:243]
	s_waitcnt lgkmcnt(6)
	v_mfma_f32_16x16x4_f32 v[200:203], v212, v44, v[200:203]
	s_waitcnt lgkmcnt(6)
	v_mfma_f32_16x16x4_f32 v[240:243], v213, v45, v[240:243]
	s_waitcnt lgkmcnt(6)
	v_mfma_f32_16x16x4_f32 v[200:203], v214, v46, v[200:203]
	s_waitcnt lgkmcnt(6)
	v_mfma_f32_16x16x4_f32 v[240:243], v215, v47, v[240:243]
	s_waitcnt lgkmcnt(5)
	v_mfma_f32_16x16x4_f32 v[200:203], v216, v48, v[200:203]
	s_waitcnt lgkmcnt(5)
	v_mfma_f32_16x16x4_f32 v[240:243], v217, v49, v[240:243]
	s_waitcnt lgkmcnt(5)
	v_mfma_f32_16x16x4_f32 v[200:203], v218, v50, v[200:203]
	s_waitcnt lgkmcnt(5)
	v_mfma_f32_16x16x4_f32 v[240:243], v219, v51, v[240:243]
	s_waitcnt lgkmcnt(4)
	v_mfma_f32_16x16x4_f32 v[200:203], v220, v52, v[200:203]
	s_waitcnt lgkmcnt(4)
	v_mfma_f32_16x16x4_f32 v[240:243], v221, v53, v[240:243]
	s_waitcnt lgkmcnt(4)
	v_mfma_f32_16x16x4_f32 v[200:203], v222, v54, v[200:203]
	s_waitcnt lgkmcnt(4)
	v_mfma_f32_16x16x4_f32 v[240:243], v223, v55, v[240:243]
	s_waitcnt lgkmcnt(3)
	v_mfma_f32_16x16x4_f32 v[200:203], v224, v56, v[200:203]
	s_waitcnt lgkmcnt(3)
	v_mfma_f32_16x16x4_f32 v[240:243], v225, v57, v[240:243]
	s_waitcnt lgkmcnt(3)
	v_mfma_f32_16x16x4_f32 v[200:203], v226, v58, v[200:203]
	s_waitcnt lgkmcnt(3)
	v_mfma_f32_16x16x4_f32 v[240:243], v227, v59, v[240:243]
	s_waitcnt lgkmcnt(2)
	v_mfma_f32_16x16x4_f32 v[200:203], v228, v60, v[200:203]
	s_waitcnt lgkmcnt(2)
	v_mfma_f32_16x16x4_f32 v[240:243], v229, v61, v[240:243]
	s_waitcnt lgkmcnt(2)
	v_mfma_f32_16x16x4_f32 v[200:203], v230, v62, v[200:203]
	s_waitcnt lgkmcnt(2)
	v_mfma_f32_16x16x4_f32 v[240:243], v231, v63, v[240:243]
	s_waitcnt lgkmcnt(1)
	v_mfma_f32_16x16x4_f32 v[200:203], v232, v64, v[200:203]
	s_waitcnt lgkmcnt(1)
	v_mfma_f32_16x16x4_f32 v[240:243], v233, v65, v[240:243]
	s_waitcnt lgkmcnt(1)
	v_mfma_f32_16x16x4_f32 v[200:203], v234, v66, v[200:203]
	s_waitcnt lgkmcnt(1)
	v_mfma_f32_16x16x4_f32 v[240:243], v235, v67, v[240:243]
	s_waitcnt lgkmcnt(0)
	v_mfma_f32_16x16x4_f32 v[200:203], v236, v68, v[200:203]
	s_waitcnt lgkmcnt(0)
	v_mfma_f32_16x16x4_f32 v[240:243], v237, v69, v[240:243]
	s_waitcnt lgkmcnt(0)
	v_mfma_f32_16x16x4_f32 v[200:203], v238, v70, v[200:203]
	s_waitcnt lgkmcnt(0)
	v_mfma_f32_16x16x4_f32 v[240:243], v239, v71, v[240:243]
	s_nop 9
	v_add_f32_e32 v1, v200, v240
	v_add_f32_e32 v2, v201, v241
	v_add_f32_e32 v3, v202, v242
	v_add_f32_e32 v4, v203, v243
	v_fmac_f32_e32 v1, v76, v112
	v_fmac_f32_e32 v2, v76, v113
	v_fmac_f32_e32 v3, v76, v114
	v_fmac_f32_e32 v4, v76, v115
	v_mul_f32_e32 v5, 0x3d372713, v1
	v_mul_f32_e32 v6, 0x3d372713, v2
	v_mul_f32_e32 v7, 0x3d372713, v3
	v_mul_f32_e32 v246, 0x3d372713, v4
	v_mul_f32_e32 v5, v1, v5
	v_mul_f32_e32 v6, v2, v6
	v_mul_f32_e32 v7, v3, v7
	v_mul_f32_e32 v246, v4, v246
	v_mul_f32_e32 v194, 0.5, v1
	v_mul_f32_e32 v195, 0.5, v2
	v_mul_f32_e32 v196, 0.5, v3
	v_mul_f32_e32 v197, 0.5, v4
	v_fma_f32 v1, v1, v5, v1
	v_fma_f32 v2, v2, v6, v2
	v_fma_f32 v3, v3, v7, v3
	v_fma_f32 v4, v4, v246, v4
	v_mul_f32_e32 v1, 0x3f4c422a, v1
	v_mul_f32_e32 v2, 0x3f4c422a, v2
	v_mul_f32_e32 v3, 0x3f4c422a, v3
	v_mul_f32_e32 v4, 0x3f4c422a, v4
	v_mul_f32_e32 v1, 0x4038aa3b, v1
	v_mul_f32_e32 v2, 0x4038aa3b, v2
	v_mul_f32_e32 v3, 0x4038aa3b, v3
	v_mul_f32_e32 v4, 0x4038aa3b, v4
	v_exp_f32_e32 v1, v1
	v_exp_f32_e32 v2, v2
	v_exp_f32_e32 v3, v3
	v_exp_f32_e32 v4, v4
	v_add_f32_e32 v1, 1.0, v1
	v_add_f32_e32 v2, 1.0, v2
	v_add_f32_e32 v3, 1.0, v3
	v_add_f32_e32 v4, 1.0, v4
	v_rcp_f32_e32 v1, v1
	v_rcp_f32_e32 v2, v2
	v_rcp_f32_e32 v3, v3
	v_rcp_f32_e32 v4, v4
	v_fma_f32 v1, v1, -2.0, 1.0
	v_fma_f32 v2, v2, -2.0, 1.0
	v_fma_f32 v3, v3, -2.0, 1.0
	v_fma_f32 v4, v4, -2.0, 1.0
	v_add_f32_e32 v1, 1.0, v1
	v_add_f32_e32 v2, 1.0, v2
	v_add_f32_e32 v3, 1.0, v3
	v_add_f32_e32 v4, 1.0, v4
	v_mul_f32_e32 v1, v194, v1
	v_mul_f32_e32 v2, v195, v2
	v_mul_f32_e32 v3, v196, v3
	v_mul_f32_e32 v4, v197, v4
	v_cvt_pk_bf16_f32 v1, v1, v1
	v_cvt_pk_bf16_f32 v2, v2, v2
	v_cvt_pk_bf16_f32 v3, v3, v3
	v_cvt_pk_bf16_f32 v4, v4, v4
	global_store_short v198, v1, s[28:29] offset:-4096
	global_store_short v198, v2, s[28:29] offset:-2048
	global_store_short v198, v3, s[28:29] offset:0
	global_store_short v198, v4, s[28:29] offset:2048
	s_add_u32 s28, s28, 0x8000
	s_addc_u32 s29, s29, 0
	v_mfma_f32_16x16x32_bf16 v[160:163], v[100:103], v[8:11], 0
	v_mfma_f32_16x16x32_bf16 v[164:167], v[100:103], v[12:15], 0
	v_mfma_f32_16x16x32_bf16 v[168:171], v[100:103], v[16:19], 0
	v_mfma_f32_16x16x32_bf16 v[172:175], v[100:103], v[20:23], 0
	v_mfma_f32_16x16x32_bf16 v[176:179], v[100:103], v[24:27], 0
	v_mfma_f32_16x16x32_bf16 v[180:183], v[100:103], v[28:31], 0
	v_mfma_f32_16x16x32_bf16 v[184:187], v[100:103], v[32:35], 0
	v_mfma_f32_16x16x32_bf16 v[188:191], v[100:103], v[36:39], 0
	s_nop 7
	v_permlane32_swap_b32_e32 v160, v168
	v_permlane32_swap_b32_e32 v161, v169
	v_permlane32_swap_b32_e32 v162, v170
	v_permlane32_swap_b32_e32 v163, v171
	v_permlane32_swap_b32_e32 v164, v172
	v_permlane32_swap_b32_e32 v165, v173
	v_permlane32_swap_b32_e32 v166, v174
	v_permlane32_swap_b32_e32 v167, v175
	v_permlane32_swap_b32_e32 v176, v184
	v_permlane32_swap_b32_e32 v177, v185
	v_permlane32_swap_b32_e32 v178, v186
	v_permlane32_swap_b32_e32 v179, v187
	v_permlane32_swap_b32_e32 v180, v188
	v_permlane32_swap_b32_e32 v181, v189
	v_permlane32_swap_b32_e32 v182, v190
	v_permlane32_swap_b32_e32 v183, v191
	v_permlane16_swap_b32_e32 v160, v164
; DI float bf2f(unsigned x) { return __uint_as_float(x << 16); }
; DI void s5_pass3_item(const Params& P, int bitem, unsigned char* smem) {
;     ...
;     for (int sub = 0; sub < 4; ++sub) {
;         s5_bu16(ubs[sub], af, xs, r, q);
;         float uv[4];
; #pragma unroll
;         for (int j = 0; j < 4; ++j) uv[j] = bf2f(uvs[sub][j]);
;         asm volatile("s_waitcnt lgkmcnt(0)" ::: "memory");
; #pragma unroll
;         for (int tt = 0; tt < 16; ++tt) { const float bur = xs[lane * 17 + tt], bui = xs[(64 + lane) * 17 + tt];
;             const float nxr = ab[0] * xr - ab[1] * xi + bur, nxi = ab[0] * xi + ab[1] * xr + bui; xr = nxr; xi = nxi;
;             xs[lane * 17 + tt] = xr; xs[(64 + lane) * 17 + tt] = xi; }
	v_permlane16_swap_b32_e32 v161, v165
	v_permlane16_swap_b32_e32 v162, v166
	v_permlane16_swap_b32_e32 v163, v167
	v_permlane16_swap_b32_e32 v168, v172
	v_permlane16_swap_b32_e32 v169, v173
	v_permlane16_swap_b32_e32 v170, v174
	v_permlane16_swap_b32_e32 v171, v175
	v_permlane16_swap_b32_e32 v176, v180
	v_permlane16_swap_b32_e32 v177, v181
	v_permlane16_swap_b32_e32 v178, v182
	v_permlane16_swap_b32_e32 v179, v183
	v_permlane16_swap_b32_e32 v184, v188
	v_permlane16_swap_b32_e32 v185, v189
	v_permlane16_swap_b32_e32 v186, v190
	v_permlane16_swap_b32_e32 v187, v191
	v_mul_f32_e32 v194, v73, v193
	v_mul_f32_e32 v195, v73, v192
	v_fma_f32 v194, v72, v192, -v194
	v_fma_f32 v195, v72, v193, v195
	v_add_f32_e32 v160, v194, v160
	v_add_f32_e32 v176, v195, v176
	ds_write_addtid_b32 v160 offset:0
	ds_write_addtid_b32 v176 offset:256
	v_mul_f32_e32 v194, v73, v176
	v_mul_f32_e32 v195, v73, v160
	v_fma_f32 v194, v72, v160, -v194
	v_fma_f32 v195, v72, v176, v195
	v_add_f32_e32 v161, v194, v161
	v_add_f32_e32 v177, v195, v177
	ds_write_addtid_b32 v161 offset:528
	ds_write_addtid_b32 v177 offset:784
	v_mul_f32_e32 v194, v73, v177
	v_mul_f32_e32 v195, v73, v161
	v_fma_f32 v194, v72, v161, -v194
	v_fma_f32 v195, v72, v177, v195
	v_add_f32_e32 v162, v194, v162
	v_add_f32_e32 v178, v195, v178
	ds_write_addtid_b32 v162 offset:1056
	ds_write_addtid_b32 v178 offset:1312
	v_mul_f32_e32 v194, v73, v178
	v_mul_f32_e32 v195, v73, v162
	v_fma_f32 v194, v72, v162, -v194
	v_fma_f32 v195, v72, v178, v195
	v_add_f32_e32 v163, v194, v163
	v_add_f32_e32 v179, v195, v179
	ds_write_addtid_b32 v163 offset:1584
	ds_write_addtid_b32 v179 offset:1840
	v_mul_f32_e32 v194, v73, v179
	v_mul_f32_e32 v195, v73, v163
	v_fma_f32 v194, v72, v163, -v194
	v_fma_f32 v195, v72, v179, v195
	v_add_f32_e32 v164, v194, v164
	v_add_f32_e32 v180, v195, v180
	ds_write_addtid_b32 v164 offset:2112
	ds_write_addtid_b32 v180 offset:2368
	v_mul_f32_e32 v194, v73, v180
	v_mul_f32_e32 v195, v73, v164
	v_fma_f32 v194, v72, v164, -v194
	v_fma_f32 v195, v72, v180, v195
	v_add_f32_e32 v165, v194, v165
	v_add_f32_e32 v181, v195, v181
	ds_write_addtid_b32 v165 offset:2640
	ds_write_addtid_b32 v181 offset:2896
	v_mul_f32_e32 v194, v73, v181
	v_mul_f32_e32 v195, v73, v165
	v_fma_f32 v194, v72, v165, -v194
	v_fma_f32 v195, v72, v181, v195
	v_add_f32_e32 v166, v194, v166
	v_add_f32_e32 v182, v195, v182
	ds_write_addtid_b32 v166 offset:3168
	ds_write_addtid_b32 v182 offset:3424
	v_mul_f32_e32 v194, v73, v182
	v_mul_f32_e32 v195, v73, v166
	v_fma_f32 v194, v72, v166, -v194
	v_fma_f32 v195, v72, v182, v195
	v_add_f32_e32 v167, v194, v167
	v_add_f32_e32 v183, v195, v183
	ds_write_addtid_b32 v167 offset:3696
	ds_write_addtid_b32 v183 offset:3952
	v_mul_f32_e32 v194, v73, v183
	v_mul_f32_e32 v195, v73, v167
	v_fma_f32 v194, v72, v167, -v194
	v_fma_f32 v195, v72, v183, v195
	v_add_f32_e32 v168, v194, v168
	v_add_f32_e32 v184, v195, v184
	ds_write_addtid_b32 v168 offset:4224
	ds_write_addtid_b32 v184 offset:4480
	v_mul_f32_e32 v194, v73, v184
	v_mul_f32_e32 v195, v73, v168
	v_fma_f32 v194, v72, v168, -v194
	v_fma_f32 v195, v72, v184, v195
	v_add_f32_e32 v169, v194, v169
	v_add_f32_e32 v185, v195, v185
	ds_write_addtid_b32 v169 offset:4752
	ds_write_addtid_b32 v185 offset:5008
	v_mul_f32_e32 v194, v73, v185
	v_mul_f32_e32 v195, v73, v169
	v_fma_f32 v194, v72, v169, -v194
	v_fma_f32 v195, v72, v185, v195
	v_add_f32_e32 v170, v194, v170
	v_add_f32_e32 v186, v195, v186
	ds_write_addtid_b32 v170 offset:5280
	ds_write_addtid_b32 v186 offset:5536
	v_mul_f32_e32 v194, v73, v186
	v_mul_f32_e32 v195, v73, v170
	v_fma_f32 v194, v72, v170, -v194
	v_fma_f32 v195, v72, v186, v195
	v_add_f32_e32 v171, v194, v171
	v_add_f32_e32 v187, v195, v187
	ds_write_addtid_b32 v171 offset:5808
	ds_write_addtid_b32 v187 offset:6064
	v_mul_f32_e32 v194, v73, v187
	v_mul_f32_e32 v195, v73, v171
	v_fma_f32 v194, v72, v171, -v194
	v_fma_f32 v195, v72, v187, v195
	v_add_f32_e32 v172, v194, v172
	v_add_f32_e32 v188, v195, v188
	ds_write_addtid_b32 v172 offset:6336
	ds_write_addtid_b32 v188 offset:6592
	v_mul_f32_e32 v194, v73, v188
	v_mul_f32_e32 v195, v73, v172
	v_fma_f32 v194, v72, v172, -v194
	v_fma_f32 v195, v72, v188, v195
	v_add_f32_e32 v173, v194, v173
	v_add_f32_e32 v189, v195, v189
	ds_write_addtid_b32 v173 offset:6864
	ds_write_addtid_b32 v189 offset:7120
	v_mul_f32_e32 v194, v73, v189
	v_mul_f32_e32 v195, v73, v173
	v_fma_f32 v194, v72, v173, -v194
	v_fma_f32 v195, v72, v189, v195
	v_add_f32_e32 v174, v194, v174
	v_add_f32_e32 v190, v195, v190
	ds_write_addtid_b32 v174 offset:7392
	ds_write_addtid_b32 v190 offset:7648
	v_mul_f32_e32 v194, v73, v190
	v_mul_f32_e32 v195, v73, v174
	v_fma_f32 v194, v72, v174, -v194
	v_fma_f32 v195, v72, v190, v195
	v_add_f32_e32 v175, v194, v175
	v_add_f32_e32 v191, v195, v191
	ds_write_addtid_b32 v175 offset:7920
	ds_write_addtid_b32 v191 offset:8176
	v_mov_b32_e32 v192, v175
	v_mov_b32_e32 v193, v191
	ds_read_b128 v[208:211], v77 offset:0
	ds_read_b128 v[212:215], v77 offset:64
	ds_read_b128 v[216:219], v77 offset:128
	ds_read_b128 v[220:223], v77 offset:192
	ds_read_b128 v[224:227], v77 offset:256
	ds_read_b128 v[228:231], v77 offset:320
	ds_read_b128 v[232:235], v77 offset:384
	ds_read_b128 v[236:239], v77 offset:448
	s_waitcnt lgkmcnt(7)
; DI unsigned pk2(float a, float b) { f32x2_t v = {a, b}; return __builtin_bit_cast(unsigned, __builtin_convertvector(v, bf16x2_t)); }
; DI float gelu_tanh(float v) { const float z = 0.7978845608028654f * (v + 0.044715f * v * v * v); const float th = 1.0f - 2.0f * __builtin_amdgcn_rcpf(__builtin_amdgcn_exp2f(2.8853900817779268f * z) + 1.0f); return 0.5f * v * (1.0f + th); }
; DI void s5_pass3_item(const Params& P, int bitem, unsigned char* smem) {
;     ...
;         f32x4 ya[4];
; #pragma unroll
;         for (int j = 0; j < 4; ++j) ya[j] = (f32x4){0.f, 0.f, 0.f, 0.f};
; #pragma unroll
;         for (int i = 0; i < 32; ++i) { const float a = xs[(4 * i + q) * 17 + r]; ya[i & 3] = __builtin_amdgcn_mfma_f32_16x16x4f32(a, cB[i], ya[i & 3], 0, 0, 0); }
;         const f32x4 y = (ya[0] + ya[1]) + (ya[2] + ya[3]);
; #pragma unroll
;         for (int j = 0; j < 4; ++j) { const int tl = sub * 16 + 4 * q + j; const float v = y[j] + dsk * uv[j];
;             HG[(size_t)(b * TT + ch * 64 + tl) * 1024 + grp * 16 + r] = (bf16_t)(pk2(gelu_tanh(v), 0.f) & 0xffffu); }
;         asm volatile("s_waitcnt lgkmcnt(0)" ::: "memory");
;     }
	v_mfma_f32_16x16x4_f32 v[200:203], v208, v40, 0
	s_waitcnt lgkmcnt(7)
	v_mfma_f32_16x16x4_f32 v[240:243], v209, v41, 0
	s_waitcnt lgkmcnt(7)
	v_mfma_f32_16x16x4_f32 v[200:203], v210, v42, v[200:203]
	s_waitcnt lgkmcnt(7)
	v_mfma_f32_16x16x4_f32 v[240:243], v211, v43, v[240:243]
	s_waitcnt lgkmcnt(6)
	v_mfma_f32_16x16x4_f32 v[200:203], v212, v44, v[200:203]
	s_waitcnt lgkmcnt(6)
	v_mfma_f32_16x16x4_f32 v[240:243], v213, v45, v[240:243]
	s_waitcnt lgkmcnt(6)
	v_mfma_f32_16x16x4_f32 v[200:203], v214, v46, v[200:203]
	s_waitcnt lgkmcnt(6)
	v_mfma_f32_16x16x4_f32 v[240:243], v215, v47, v[240:243]
	s_waitcnt lgkmcnt(5)
	v_mfma_f32_16x16x4_f32 v[200:203], v216, v48, v[200:203]
	s_waitcnt lgkmcnt(5)
	v_mfma_f32_16x16x4_f32 v[240:243], v217, v49, v[240:243]
	s_waitcnt lgkmcnt(5)
	v_mfma_f32_16x16x4_f32 v[200:203], v218, v50, v[200:203]
	s_waitcnt lgkmcnt(5)
	v_mfma_f32_16x16x4_f32 v[240:243], v219, v51, v[240:243]
	s_waitcnt lgkmcnt(4)
	v_mfma_f32_16x16x4_f32 v[200:203], v220, v52, v[200:203]
	s_waitcnt lgkmcnt(4)
	v_mfma_f32_16x16x4_f32 v[240:243], v221, v53, v[240:243]
	s_waitcnt lgkmcnt(4)
	v_mfma_f32_16x16x4_f32 v[200:203], v222, v54, v[200:203]
	s_waitcnt lgkmcnt(4)
	v_mfma_f32_16x16x4_f32 v[240:243], v223, v55, v[240:243]
	s_waitcnt lgkmcnt(3)
	v_mfma_f32_16x16x4_f32 v[200:203], v224, v56, v[200:203]
	s_waitcnt lgkmcnt(3)
	v_mfma_f32_16x16x4_f32 v[240:243], v225, v57, v[240:243]
	s_waitcnt lgkmcnt(3)
	v_mfma_f32_16x16x4_f32 v[200:203], v226, v58, v[200:203]
	s_waitcnt lgkmcnt(3)
	v_mfma_f32_16x16x4_f32 v[240:243], v227, v59, v[240:243]
	s_waitcnt lgkmcnt(2)
	v_mfma_f32_16x16x4_f32 v[200:203], v228, v60, v[200:203]
	s_waitcnt lgkmcnt(2)
	v_mfma_f32_16x16x4_f32 v[240:243], v229, v61, v[240:243]
	s_waitcnt lgkmcnt(2)
	v_mfma_f32_16x16x4_f32 v[200:203], v230, v62, v[200:203]
	s_waitcnt lgkmcnt(2)
	v_mfma_f32_16x16x4_f32 v[240:243], v231, v63, v[240:243]
	s_waitcnt lgkmcnt(1)
	v_mfma_f32_16x16x4_f32 v[200:203], v232, v64, v[200:203]
	s_waitcnt lgkmcnt(1)
	v_mfma_f32_16x16x4_f32 v[240:243], v233, v65, v[240:243]
	s_waitcnt lgkmcnt(1)
	v_mfma_f32_16x16x4_f32 v[200:203], v234, v66, v[200:203]
	s_waitcnt lgkmcnt(1)
	v_mfma_f32_16x16x4_f32 v[240:243], v235, v67, v[240:243]
	s_waitcnt lgkmcnt(0)
	v_mfma_f32_16x16x4_f32 v[200:203], v236, v68, v[200:203]
	s_waitcnt lgkmcnt(0)
	v_mfma_f32_16x16x4_f32 v[240:243], v237, v69, v[240:243]
	s_waitcnt lgkmcnt(0)
	v_mfma_f32_16x16x4_f32 v[200:203], v238, v70, v[200:203]
	s_waitcnt lgkmcnt(0)
	v_mfma_f32_16x16x4_f32 v[240:243], v239, v71, v[240:243]
	s_nop 9
	v_add_f32_e32 v1, v200, v240
	v_add_f32_e32 v2, v201, v241
	v_add_f32_e32 v3, v202, v242
	v_add_f32_e32 v4, v203, v243
	v_fmac_f32_e32 v1, v76, v116
	v_fmac_f32_e32 v2, v76, v117
	v_fmac_f32_e32 v3, v76, v118
	v_fmac_f32_e32 v4, v76, v119
	v_mul_f32_e32 v5, 0x3d372713, v1
	v_mul_f32_e32 v6, 0x3d372713, v2
	v_mul_f32_e32 v7, 0x3d372713, v3
	v_mul_f32_e32 v246, 0x3d372713, v4
	v_mul_f32_e32 v5, v1, v5
	v_mul_f32_e32 v6, v2, v6
	v_mul_f32_e32 v7, v3, v7
	v_mul_f32_e32 v246, v4, v246
	v_mul_f32_e32 v194, 0.5, v1
	v_mul_f32_e32 v195, 0.5, v2
	v_mul_f32_e32 v196, 0.5, v3
	v_mul_f32_e32 v197, 0.5, v4
	v_fma_f32 v1, v1, v5, v1
	v_fma_f32 v2, v2, v6, v2
	v_fma_f32 v3, v3, v7, v3
	v_fma_f32 v4, v4, v246, v4
	v_mul_f32_e32 v1, 0x3f4c422a, v1
	v_mul_f32_e32 v2, 0x3f4c422a, v2
	v_mul_f32_e32 v3, 0x3f4c422a, v3
	v_mul_f32_e32 v4, 0x3f4c422a, v4
	v_mul_f32_e32 v1, 0x4038aa3b, v1
	v_mul_f32_e32 v2, 0x4038aa3b, v2
	v_mul_f32_e32 v3, 0x4038aa3b, v3
	v_mul_f32_e32 v4, 0x4038aa3b, v4
	v_exp_f32_e32 v1, v1
	v_exp_f32_e32 v2, v2
	v_exp_f32_e32 v3, v3
	v_exp_f32_e32 v4, v4
	v_add_f32_e32 v1, 1.0, v1
	v_add_f32_e32 v2, 1.0, v2
	v_add_f32_e32 v3, 1.0, v3
	v_add_f32_e32 v4, 1.0, v4
	v_rcp_f32_e32 v1, v1
	v_rcp_f32_e32 v2, v2
	v_rcp_f32_e32 v3, v3
	v_rcp_f32_e32 v4, v4
	v_fma_f32 v1, v1, -2.0, 1.0
	v_fma_f32 v2, v2, -2.0, 1.0
	v_fma_f32 v3, v3, -2.0, 1.0
	v_fma_f32 v4, v4, -2.0, 1.0
	v_add_f32_e32 v1, 1.0, v1
	v_add_f32_e32 v2, 1.0, v2
	v_add_f32_e32 v3, 1.0, v3
	v_add_f32_e32 v4, 1.0, v4
	v_mul_f32_e32 v1, v194, v1
	v_mul_f32_e32 v2, v195, v2
	v_mul_f32_e32 v3, v196, v3
	v_mul_f32_e32 v4, v197, v4
	v_cvt_pk_bf16_f32 v1, v1, v1
	v_cvt_pk_bf16_f32 v2, v2, v2
	v_cvt_pk_bf16_f32 v3, v3, v3
	v_cvt_pk_bf16_f32 v4, v4, v4
	global_store_short v198, v1, s[28:29] offset:-4096
	global_store_short v198, v2, s[28:29] offset:-2048
	global_store_short v198, v3, s[28:29] offset:0
	global_store_short v198, v4, s[28:29] offset:2048
	s_add_u32 s26, s26, 0x400000
	s_addc_u32 s27, s27, 0
	s_xor_b32 s20, s20, 0x4000
	s_add_i32 s19, s19, 1
	s_cmp_lt_u32 s19, 8
	s_cbranch_scc1 .Ls5n_round
	s_waitcnt vmcnt(0) lgkmcnt(0)
	s_barrier
	s_branch .LBB0_727
